# GEMM K-loops: DMA source addresses via 9 instead of 20 64-bit VALU adds per iteration (constants folded into the instruction offset, M0 lowered to match); M0-write->DMA wait states padded
# speedup vs baseline: 1.0224x; 1.0073x over previous
.LBB0_34:
	ds_read_b128 v[164:167], v151
	ds_read_b128 v[168:171], v151 offset:1024
	ds_read_b128 v[172:175], v151 offset:2048
	ds_read_b128 v[176:179], v151 offset:3072
	v_add_u32_e32 v162, 0xc000, v147
	v_lshl_add_u64 v[204:205], v[138:139], 0, s[12:13]
	v_lshl_add_u64 v[228:229], v[204:205], 0, s[60:61]
	s_add_i32 m0, s1, 0xc000
	v_add_u32_e32 v163, 0xe000, v147
	ds_read_b128 v[180:183], v0
	ds_read_b128 v[184:187], v0 offset:1024
	ds_read_b128 v[188:191], v0 offset:2048
	ds_read_b128 v[192:195], v0 offset:3072
	ds_read_b128 v[196:199], v0 offset:4096
	ds_read_b128 v[200:203], v0 offset:5120
	ds_read_b128 v[222:225], v0 offset:6144
	ds_read_b128 v[232:235], v0 offset:7168
	global_load_lds_dwordx4 v[228:229], off
	v_lshl_add_u64 v[210:211], v[140:141], 0, s[12:13]
	v_lshl_add_u64 v[152:153], v[210:211], 0, s[60:61]
	s_add_i32 m0, s1, 0xe000
	s_nop 0
	global_load_lds_dwordx4 v[152:153], off
	s_waitcnt lgkmcnt(8)
	s_barrier
	s_waitcnt lgkmcnt(0)
	s_setprio 1
	s_waitcnt lgkmcnt(0)
	v_mfma_f32_16x16x32_bf16 v[126:129], v[164:167], v[180:183], v[126:129]
	v_mfma_f32_16x16x32_bf16 v[122:125], v[172:175], v[180:183], v[122:125]
	v_mfma_f32_16x16x32_bf16 v[118:121], v[164:167], v[188:191], v[118:121]
	v_mfma_f32_16x16x32_bf16 v[114:117], v[172:175], v[188:191], v[114:117]
	v_mfma_f32_16x16x32_bf16 v[110:113], v[164:167], v[196:199], v[110:113]
	v_mfma_f32_16x16x32_bf16 v[106:109], v[172:175], v[196:199], v[106:109]
	v_mfma_f32_16x16x32_bf16 v[102:105], v[164:167], v[222:225], v[102:105]
	v_mfma_f32_16x16x32_bf16 v[98:101], v[172:175], v[222:225], v[98:101]
	v_mfma_f32_16x16x32_bf16 v[126:129], v[168:171], v[184:187], v[126:129]
	v_mfma_f32_16x16x32_bf16 v[122:125], v[176:179], v[184:187], v[122:125]
	v_mfma_f32_16x16x32_bf16 v[118:121], v[168:171], v[192:195], v[118:121]
	v_mfma_f32_16x16x32_bf16 v[114:117], v[176:179], v[192:195], v[114:117]
	v_mfma_f32_16x16x32_bf16 v[110:113], v[168:171], v[200:203], v[110:113]
	v_mfma_f32_16x16x32_bf16 v[106:109], v[176:179], v[200:203], v[106:109]
	v_mfma_f32_16x16x32_bf16 v[102:105], v[168:171], v[232:235], v[102:105]
	v_mfma_f32_16x16x32_bf16 v[98:101], v[176:179], v[232:235], v[98:101]
	s_setprio 0
	s_barrier
	v_lshl_add_u64 v[216:217], v[134:135], 0, s[12:13]
	s_add_i32 m0, s1, 0xff00
	ds_read_b128 v[236:239], v151 offset:16384
	ds_read_b128 v[240:243], v151 offset:17408
	ds_read_b128 v[244:247], v151 offset:18432
	ds_read_b128 v[248:251], v151 offset:19456
	global_load_lds_dwordx4 v[216:217], off offset:256
	v_lshl_add_u64 v[218:219], v[136:137], 0, s[12:13]
	s_add_i32 m0, s1, 0x11f00
	s_nop 0
	global_load_lds_dwordx4 v[218:219], off offset:256
	s_barrier
	s_waitcnt lgkmcnt(0)
	s_setprio 1
	s_waitcnt lgkmcnt(0)
	v_mfma_f32_16x16x32_bf16 v[94:97], v[236:239], v[180:183], v[94:97]
	v_mfma_f32_16x16x32_bf16 v[90:93], v[244:247], v[180:183], v[90:93]
	v_mfma_f32_16x16x32_bf16 v[86:89], v[236:239], v[188:191], v[86:89]
	v_mfma_f32_16x16x32_bf16 v[70:73], v[244:247], v[188:191], v[70:73]
	v_mfma_f32_16x16x32_bf16 v[62:65], v[236:239], v[196:199], v[62:65]
	v_mfma_f32_16x16x32_bf16 v[58:61], v[244:247], v[196:199], v[58:61]
	v_mfma_f32_16x16x32_bf16 v[54:57], v[236:239], v[222:225], v[54:57]
	v_mfma_f32_16x16x32_bf16 v[50:53], v[244:247], v[222:225], v[50:53]
	v_mfma_f32_16x16x32_bf16 v[94:97], v[240:243], v[184:187], v[94:97]
	v_mfma_f32_16x16x32_bf16 v[90:93], v[248:251], v[184:187], v[90:93]
	v_mfma_f32_16x16x32_bf16 v[86:89], v[240:243], v[192:195], v[86:89]
	v_mfma_f32_16x16x32_bf16 v[70:73], v[248:251], v[192:195], v[70:73]
	v_mfma_f32_16x16x32_bf16 v[62:65], v[240:243], v[200:203], v[62:65]
	v_mfma_f32_16x16x32_bf16 v[58:61], v[248:251], v[200:203], v[58:61]
	v_mfma_f32_16x16x32_bf16 v[54:57], v[240:243], v[232:235], v[54:57]
	v_mfma_f32_16x16x32_bf16 v[50:53], v[248:251], v[232:235], v[50:53]
	s_setprio 0
	v_lshl_add_u64 v[158:159], v[204:205], 0, s[74:75]
	s_mov_b32 m0, s1
	s_barrier
	ds_read_b128 v[180:183], v0 offset:16384
	ds_read_b128 v[184:187], v0 offset:17408
	ds_read_b128 v[188:191], v0 offset:18432
	ds_read_b128 v[192:195], v0 offset:19456
	ds_read_b128 v[196:199], v0 offset:20480
	ds_read_b128 v[200:203], v0 offset:21504
	ds_read_b128 v[222:225], v0 offset:22528
	ds_read_b128 v[232:235], v0 offset:23552
	global_load_lds_dwordx4 v[158:159], off
	s_add_i32 m0, s1, 0x1f00
	s_nop 0
	global_load_lds_dwordx4 v[210:211], off offset:256
	s_barrier
	s_waitcnt lgkmcnt(0)
	s_setprio 1
	s_waitcnt lgkmcnt(0)
	v_mfma_f32_16x16x32_bf16 v[46:49], v[164:167], v[180:183], v[46:49]
	v_mfma_f32_16x16x32_bf16 v[42:45], v[172:175], v[180:183], v[42:45]
	v_mfma_f32_16x16x32_bf16 v[38:41], v[164:167], v[188:191], v[38:41]
	v_mfma_f32_16x16x32_bf16 v[34:37], v[172:175], v[188:191], v[34:37]
	v_mfma_f32_16x16x32_bf16 v[30:33], v[164:167], v[196:199], v[30:33]
	v_mfma_f32_16x16x32_bf16 v[26:29], v[172:175], v[196:199], v[26:29]
	v_mfma_f32_16x16x32_bf16 v[22:25], v[164:167], v[222:225], v[22:25]
	v_mfma_f32_16x16x32_bf16 v[18:21], v[172:175], v[222:225], v[18:21]
	v_mfma_f32_16x16x32_bf16 v[46:49], v[168:171], v[184:187], v[46:49]
	v_mfma_f32_16x16x32_bf16 v[42:45], v[176:179], v[184:187], v[42:45]
	v_mfma_f32_16x16x32_bf16 v[38:41], v[168:171], v[192:195], v[38:41]
	v_mfma_f32_16x16x32_bf16 v[34:37], v[176:179], v[192:195], v[34:37]
	v_mfma_f32_16x16x32_bf16 v[30:33], v[168:171], v[200:203], v[30:33]
	v_mfma_f32_16x16x32_bf16 v[26:29], v[176:179], v[200:203], v[26:29]
	v_mfma_f32_16x16x32_bf16 v[22:25], v[168:171], v[232:235], v[22:25]
	v_mfma_f32_16x16x32_bf16 v[18:21], v[176:179], v[232:235], v[18:21]
	s_setprio 0
	s_barrier
	v_lshl_add_u64 v[154:155], v[216:217], 0, s[18:19]
	s_add_i32 m0, s1, 0x14000
	s_nop 0
	global_load_lds_dwordx4 v[154:155], off
	v_lshl_add_u64 v[156:157], v[218:219], 0, s[18:19]
	s_add_i32 m0, s1, 0x16000
	s_nop 0
	global_load_lds_dwordx4 v[156:157], off
	s_waitcnt vmcnt(6)
	s_barrier
	s_setprio 1
	v_mfma_f32_16x16x32_bf16 v[14:17], v[236:239], v[180:183], v[14:17]
	v_mfma_f32_16x16x32_bf16 v[10:13], v[244:247], v[180:183], v[10:13]
	v_mfma_f32_16x16x32_bf16 v[6:9], v[236:239], v[188:191], v[6:9]
	v_mfma_f32_16x16x32_bf16 v[2:5], v[244:247], v[188:191], v[2:5]
	v_mfma_f32_16x16x32_bf16 v[66:69], v[236:239], v[196:199], v[66:69]
	v_mfma_f32_16x16x32_bf16 v[74:77], v[244:247], v[196:199], v[74:77]
	v_mfma_f32_16x16x32_bf16 v[78:81], v[236:239], v[222:225], v[78:81]
	v_mfma_f32_16x16x32_bf16 v[82:85], v[244:247], v[222:225], v[82:85]
	v_mfma_f32_16x16x32_bf16 v[14:17], v[240:243], v[184:187], v[14:17]
	v_mfma_f32_16x16x32_bf16 v[10:13], v[248:251], v[184:187], v[10:13]
	v_mfma_f32_16x16x32_bf16 v[6:9], v[240:243], v[192:195], v[6:9]
	v_mfma_f32_16x16x32_bf16 v[2:5], v[248:251], v[192:195], v[2:5]
	v_mfma_f32_16x16x32_bf16 v[66:69], v[240:243], v[200:203], v[66:69]
	v_mfma_f32_16x16x32_bf16 v[74:77], v[248:251], v[200:203], v[74:77]
	v_mfma_f32_16x16x32_bf16 v[78:81], v[240:243], v[232:235], v[78:81]
	v_mfma_f32_16x16x32_bf16 v[82:85], v[248:251], v[232:235], v[82:85]
	s_setprio 0
	s_barrier
	ds_read_b128 v[164:167], v151 offset:32768
	ds_read_b128 v[168:171], v151 offset:33792
	ds_read_b128 v[172:175], v151 offset:34816
	ds_read_b128 v[176:179], v151 offset:35840
	s_add_i32 m0, s1, 0x3f80
	ds_read_b128 v[180:183], v0 offset:32768
	ds_read_b128 v[184:187], v0 offset:33792
	ds_read_b128 v[188:191], v0 offset:34816
	ds_read_b128 v[192:195], v0 offset:35840
	ds_read_b128 v[196:199], v0 offset:36864
	ds_read_b128 v[200:203], v0 offset:37888
	ds_read_b128 v[222:225], v0 offset:38912
	ds_read_b128 v[232:235], v0 offset:39936
	global_load_lds_dwordx4 v[228:229], off offset:128
	s_add_i32 m0, s1, 0x5f80
	s_nop 0
	global_load_lds_dwordx4 v[152:153], off offset:128
	s_waitcnt lgkmcnt(8)
	s_barrier
	s_waitcnt lgkmcnt(0)
	s_setprio 1
	s_waitcnt lgkmcnt(0)
	v_mfma_f32_16x16x32_bf16 v[126:129], v[164:167], v[180:183], v[126:129]
	v_mfma_f32_16x16x32_bf16 v[122:125], v[172:175], v[180:183], v[122:125]
	v_mfma_f32_16x16x32_bf16 v[118:121], v[164:167], v[188:191], v[118:121]
	v_mfma_f32_16x16x32_bf16 v[114:117], v[172:175], v[188:191], v[114:117]
	v_mfma_f32_16x16x32_bf16 v[110:113], v[164:167], v[196:199], v[110:113]
	v_mfma_f32_16x16x32_bf16 v[106:109], v[172:175], v[196:199], v[106:109]
	v_mfma_f32_16x16x32_bf16 v[102:105], v[164:167], v[222:225], v[102:105]
	v_mfma_f32_16x16x32_bf16 v[98:101], v[172:175], v[222:225], v[98:101]
	v_mfma_f32_16x16x32_bf16 v[126:129], v[168:171], v[184:187], v[126:129]
	v_mfma_f32_16x16x32_bf16 v[122:125], v[176:179], v[184:187], v[122:125]
	v_mfma_f32_16x16x32_bf16 v[118:121], v[168:171], v[192:195], v[118:121]
	v_mfma_f32_16x16x32_bf16 v[114:117], v[176:179], v[192:195], v[114:117]
	v_mfma_f32_16x16x32_bf16 v[110:113], v[168:171], v[200:203], v[110:113]
	v_mfma_f32_16x16x32_bf16 v[106:109], v[176:179], v[200:203], v[106:109]
	v_mfma_f32_16x16x32_bf16 v[102:105], v[168:171], v[232:235], v[102:105]
	v_mfma_f32_16x16x32_bf16 v[98:101], v[176:179], v[232:235], v[98:101]
	s_setprio 0
	s_barrier
	s_add_i32 m0, s1, 0x17e80
	ds_read_b128 v[236:239], v151 offset:49152
	ds_read_b128 v[240:243], v151 offset:50176
	ds_read_b128 v[244:247], v151 offset:51200
	ds_read_b128 v[248:251], v151 offset:52224
	global_load_lds_dwordx4 v[216:217], off offset:384
	s_add_i32 m0, s1, 0x19e80
	s_nop 0
	global_load_lds_dwordx4 v[218:219], off offset:384
	s_barrier
	s_waitcnt lgkmcnt(0)
	s_setprio 1
	s_waitcnt lgkmcnt(0)
	v_mfma_f32_16x16x32_bf16 v[94:97], v[236:239], v[180:183], v[94:97]
	v_mfma_f32_16x16x32_bf16 v[90:93], v[244:247], v[180:183], v[90:93]
	v_mfma_f32_16x16x32_bf16 v[86:89], v[236:239], v[188:191], v[86:89]
	v_mfma_f32_16x16x32_bf16 v[70:73], v[244:247], v[188:191], v[70:73]
	v_mfma_f32_16x16x32_bf16 v[62:65], v[236:239], v[196:199], v[62:65]
	v_mfma_f32_16x16x32_bf16 v[58:61], v[244:247], v[196:199], v[58:61]
	v_mfma_f32_16x16x32_bf16 v[54:57], v[236:239], v[222:225], v[54:57]
	v_mfma_f32_16x16x32_bf16 v[50:53], v[244:247], v[222:225], v[50:53]
	v_mfma_f32_16x16x32_bf16 v[94:97], v[240:243], v[184:187], v[94:97]
	v_mfma_f32_16x16x32_bf16 v[90:93], v[248:251], v[184:187], v[90:93]
	v_mfma_f32_16x16x32_bf16 v[86:89], v[240:243], v[192:195], v[86:89]
	v_mfma_f32_16x16x32_bf16 v[70:73], v[248:251], v[192:195], v[70:73]
	v_mfma_f32_16x16x32_bf16 v[62:65], v[240:243], v[200:203], v[62:65]
	v_mfma_f32_16x16x32_bf16 v[58:61], v[248:251], v[200:203], v[58:61]
	v_mfma_f32_16x16x32_bf16 v[54:57], v[240:243], v[232:235], v[54:57]
	v_mfma_f32_16x16x32_bf16 v[50:53], v[248:251], v[232:235], v[50:53]
	s_setprio 0
	s_add_i32 m0, s1, 0x7e80
	s_barrier
	ds_read_b128 v[180:183], v0 offset:49152
	ds_read_b128 v[184:187], v0 offset:50176
	ds_read_b128 v[188:191], v0 offset:51200
	ds_read_b128 v[192:195], v0 offset:52224
	ds_read_b128 v[196:199], v0 offset:53248
	ds_read_b128 v[200:203], v0 offset:54272
	ds_read_b128 v[222:225], v0 offset:55296
	ds_read_b128 v[232:235], v0 offset:56320
	global_load_lds_dwordx4 v[204:205], off offset:384
	s_add_i32 m0, s1, 0x9e80
	s_nop 0
	global_load_lds_dwordx4 v[210:211], off offset:384
	s_barrier
	s_waitcnt lgkmcnt(0)
	s_setprio 1
	s_waitcnt lgkmcnt(0)
	v_mfma_f32_16x16x32_bf16 v[46:49], v[164:167], v[180:183], v[46:49]
	v_mfma_f32_16x16x32_bf16 v[42:45], v[172:175], v[180:183], v[42:45]
	v_mfma_f32_16x16x32_bf16 v[38:41], v[164:167], v[188:191], v[38:41]
	v_mfma_f32_16x16x32_bf16 v[34:37], v[172:175], v[188:191], v[34:37]
	v_mfma_f32_16x16x32_bf16 v[30:33], v[164:167], v[196:199], v[30:33]
	v_mfma_f32_16x16x32_bf16 v[26:29], v[172:175], v[196:199], v[26:29]
	v_mfma_f32_16x16x32_bf16 v[22:25], v[164:167], v[222:225], v[22:25]
	v_mfma_f32_16x16x32_bf16 v[18:21], v[172:175], v[222:225], v[18:21]
	v_mfma_f32_16x16x32_bf16 v[46:49], v[168:171], v[184:187], v[46:49]
	v_mfma_f32_16x16x32_bf16 v[42:45], v[176:179], v[184:187], v[42:45]
	v_mfma_f32_16x16x32_bf16 v[38:41], v[168:171], v[192:195], v[38:41]
	v_mfma_f32_16x16x32_bf16 v[34:37], v[176:179], v[192:195], v[34:37]
	v_mfma_f32_16x16x32_bf16 v[30:33], v[168:171], v[200:203], v[30:33]
	v_mfma_f32_16x16x32_bf16 v[26:29], v[176:179], v[200:203], v[26:29]
	v_mfma_f32_16x16x32_bf16 v[22:25], v[168:171], v[232:235], v[22:25]
	v_mfma_f32_16x16x32_bf16 v[18:21], v[176:179], v[232:235], v[18:21]
	s_setprio 0
	s_barrier
	s_add_i32 m0, s1, 0x1bf80
	s_nop 0
	global_load_lds_dwordx4 v[154:155], off offset:128
	s_add_i32 m0, s1, 0x1df80
	s_nop 0
	global_load_lds_dwordx4 v[156:157], off offset:128
	s_waitcnt vmcnt(6)
	s_barrier
	s_setprio 1
	v_mfma_f32_16x16x32_bf16 v[14:17], v[236:239], v[180:183], v[14:17]
	v_mfma_f32_16x16x32_bf16 v[10:13], v[244:247], v[180:183], v[10:13]
	v_mfma_f32_16x16x32_bf16 v[6:9], v[236:239], v[188:191], v[6:9]
	v_mfma_f32_16x16x32_bf16 v[2:5], v[244:247], v[188:191], v[2:5]
	v_mfma_f32_16x16x32_bf16 v[66:69], v[236:239], v[196:199], v[66:69]
	v_mfma_f32_16x16x32_bf16 v[74:77], v[244:247], v[196:199], v[74:77]
	v_mfma_f32_16x16x32_bf16 v[78:81], v[236:239], v[222:225], v[78:81]
	v_mfma_f32_16x16x32_bf16 v[82:85], v[244:247], v[222:225], v[82:85]
	v_mfma_f32_16x16x32_bf16 v[14:17], v[240:243], v[184:187], v[14:17]
	v_mfma_f32_16x16x32_bf16 v[10:13], v[248:251], v[184:187], v[10:13]
	v_mfma_f32_16x16x32_bf16 v[6:9], v[240:243], v[192:195], v[6:9]
	v_mfma_f32_16x16x32_bf16 v[2:5], v[248:251], v[192:195], v[2:5]
	v_mfma_f32_16x16x32_bf16 v[66:69], v[240:243], v[200:203], v[66:69]
	v_mfma_f32_16x16x32_bf16 v[74:77], v[248:251], v[200:203], v[74:77]
	v_mfma_f32_16x16x32_bf16 v[78:81], v[240:243], v[232:235], v[78:81]
	v_mfma_f32_16x16x32_bf16 v[82:85], v[248:251], v[232:235], v[82:85]
	s_setprio 0
	s_add_i32 s0, s0, 2
	s_add_u32 s12, s12, 0x100
	s_addc_u32 s13, s13, 0
	s_cmp_lt_u32 s0, 28
	s_barrier
	s_cbranch_scc1 .LBB0_34
	s_add_i32 s1, s1, 0x1e000
	s_mov_b64 s[12:13], 0xf80
	v_readfirstlane_b32 s0, v162
	v_lshl_add_u64 v[132:133], v[132:133], 0, s[12:13]
	s_mov_b32 m0, s0
	v_readfirstlane_b32 s0, v163
	ds_read_b128 v[134:137], v151
	ds_read_b128 v[138:141], v151 offset:1024
	ds_read_b128 v[152:155], v151 offset:2048
	ds_read_b128 v[156:159], v151 offset:3072
	ds_read_b128 v[164:167], v0
	ds_read_b128 v[168:171], v0 offset:1024
	ds_read_b128 v[172:175], v0 offset:2048
	ds_read_b128 v[176:179], v0 offset:3072
	ds_read_b128 v[180:183], v0 offset:4096
	ds_read_b128 v[184:187], v0 offset:5120
	ds_read_b128 v[188:191], v0 offset:6144
	ds_read_b128 v[192:195], v0 offset:7168
	global_load_lds_dwordx4 v[132:133], off
	v_lshl_add_u64 v[130:131], v[130:131], 0, s[12:13]
	s_mov_b32 m0, s0
	s_nop 0
	global_load_lds_dwordx4 v[130:131], off
	s_barrier
	s_waitcnt lgkmcnt(0)
	s_setprio 1
	s_waitcnt lgkmcnt(0)
	v_mfma_f32_16x16x32_bf16 v[122:125], v[152:155], v[164:167], v[122:125]
	v_mfma_f32_16x16x32_bf16 v[118:121], v[134:137], v[172:175], v[118:121]
	v_mfma_f32_16x16x32_bf16 v[114:117], v[152:155], v[172:175], v[114:117]
	v_mfma_f32_16x16x32_bf16 v[102:105], v[134:137], v[188:191], v[102:105]
	v_mfma_f32_16x16x32_bf16 v[98:101], v[152:155], v[188:191], v[98:101]
	v_mfma_f32_16x16x32_bf16 v[126:129], v[134:137], v[164:167], v[126:129]
	v_mfma_f32_16x16x32_bf16 v[122:125], v[156:159], v[168:171], v[122:125]
	v_mfma_f32_16x16x32_bf16 v[118:121], v[138:141], v[176:179], v[118:121]
	v_mfma_f32_16x16x32_bf16 v[114:117], v[156:159], v[176:179], v[114:117]
	v_mfma_f32_16x16x32_bf16 v[110:113], v[134:137], v[180:183], v[110:113]
	v_mfma_f32_16x16x32_bf16 v[106:109], v[152:155], v[180:183], v[106:109]
	v_mfma_f32_16x16x32_bf16 v[102:105], v[138:141], v[192:195], v[102:105]
	v_mfma_f32_16x16x32_bf16 v[98:101], v[156:159], v[192:195], v[98:101]
	v_mfma_f32_16x16x32_bf16 v[126:129], v[138:141], v[168:171], v[126:129]
	v_mfma_f32_16x16x32_bf16 v[130:133], v[138:141], v[184:187], v[110:113]
	v_mfma_f32_16x16x32_bf16 v[160:163], v[156:159], v[184:187], v[106:109]
	s_setprio 0
	s_barrier
	ds_read_b128 v[106:109], v151 offset:16384
	ds_read_b128 v[110:113], v151 offset:17408
	ds_read_b128 v[196:199], v151 offset:18432
	ds_read_b128 v[200:203], v151 offset:19456
	s_barrier
	s_waitcnt lgkmcnt(0)
	s_setprio 1
	s_waitcnt lgkmcnt(3)
	v_mfma_f32_16x16x32_bf16 v[86:89], v[106:109], v[172:175], v[86:89]
	s_waitcnt lgkmcnt(1)
	v_mfma_f32_16x16x32_bf16 v[70:73], v[196:199], v[172:175], v[70:73]
	v_mfma_f32_16x16x32_bf16 v[62:65], v[106:109], v[180:183], v[62:65]
	v_mfma_f32_16x16x32_bf16 v[58:61], v[196:199], v[180:183], v[58:61]
	v_mfma_f32_16x16x32_bf16 v[54:57], v[106:109], v[188:191], v[54:57]
	v_mfma_f32_16x16x32_bf16 v[50:53], v[196:199], v[188:191], v[50:53]
	v_mfma_f32_16x16x32_bf16 v[94:97], v[106:109], v[164:167], v[94:97]
	v_mfma_f32_16x16x32_bf16 v[90:93], v[196:199], v[164:167], v[90:93]
	v_mfma_f32_16x16x32_bf16 v[86:89], v[110:113], v[176:179], v[86:89]
	s_waitcnt lgkmcnt(0)
	v_mfma_f32_16x16x32_bf16 v[70:73], v[200:203], v[176:179], v[70:73]
	v_mfma_f32_16x16x32_bf16 v[62:65], v[110:113], v[184:187], v[62:65]
	v_mfma_f32_16x16x32_bf16 v[58:61], v[200:203], v[184:187], v[58:61]
	v_mfma_f32_16x16x32_bf16 v[54:57], v[110:113], v[192:195], v[54:57]
	v_mfma_f32_16x16x32_bf16 v[50:53], v[200:203], v[192:195], v[50:53]
	v_mfma_f32_16x16x32_bf16 v[222:225], v[110:113], v[168:171], v[94:97]
	v_mfma_f32_16x16x32_bf16 v[164:167], v[200:203], v[168:171], v[90:93]
	s_setprio 0
	s_barrier
	s_nop 0
	ds_read_b128 v[90:93], v0 offset:16384
	ds_read_b128 v[94:97], v0 offset:17408
	ds_read_b128 v[168:171], v0 offset:18432
	ds_read_b128 v[172:175], v0 offset:19456
	ds_read_b128 v[176:179], v0 offset:20480
	ds_read_b128 v[180:183], v0 offset:21504
	ds_read_b128 v[184:187], v0 offset:22528
	ds_read_b128 v[188:191], v0 offset:23552
	s_waitcnt vmcnt(4)
	s_barrier
	s_waitcnt lgkmcnt(0)
	s_setprio 1
	s_waitcnt lgkmcnt(7)
	v_mfma_f32_16x16x32_bf16 v[46:49], v[134:137], v[90:93], v[46:49]
	v_mfma_f32_16x16x32_bf16 v[42:45], v[152:155], v[90:93], v[42:45]
	s_waitcnt lgkmcnt(5)
	v_mfma_f32_16x16x32_bf16 v[38:41], v[134:137], v[168:171], v[38:41]
	v_mfma_f32_16x16x32_bf16 v[34:37], v[152:155], v[168:171], v[34:37]
	s_waitcnt lgkmcnt(3)
	v_mfma_f32_16x16x32_bf16 v[30:33], v[134:137], v[176:179], v[30:33]
	v_mfma_f32_16x16x32_bf16 v[26:29], v[152:155], v[176:179], v[26:29]
	s_waitcnt lgkmcnt(1)
	v_mfma_f32_16x16x32_bf16 v[22:25], v[134:137], v[184:187], v[22:25]
	v_mfma_f32_16x16x32_bf16 v[18:21], v[152:155], v[184:187], v[18:21]
	v_mfma_f32_16x16x32_bf16 v[46:49], v[138:141], v[94:97], v[46:49]
	v_mfma_f32_16x16x32_bf16 v[42:45], v[156:159], v[94:97], v[42:45]
	v_mfma_f32_16x16x32_bf16 v[38:41], v[138:141], v[172:175], v[38:41]
	v_mfma_f32_16x16x32_bf16 v[34:37], v[156:159], v[172:175], v[34:37]
	v_mfma_f32_16x16x32_bf16 v[30:33], v[138:141], v[180:183], v[30:33]
	v_mfma_f32_16x16x32_bf16 v[26:29], v[156:159], v[180:183], v[26:29]
	s_waitcnt lgkmcnt(0)
	v_mfma_f32_16x16x32_bf16 v[22:25], v[138:141], v[188:191], v[22:25]
	v_mfma_f32_16x16x32_bf16 v[18:21], v[156:159], v[188:191], v[18:21]
	s_setprio 0
	s_setprio 1
	v_mfma_f32_16x16x32_bf16 v[10:13], v[196:199], v[90:93], v[10:13]
	v_mfma_f32_16x16x32_bf16 v[152:155], v[200:203], v[94:97], v[10:13]
	v_mfma_f32_16x16x32_bf16 v[10:13], v[106:109], v[176:179], v[66:69]
	v_mfma_f32_16x16x32_bf16 v[156:159], v[110:113], v[180:183], v[10:13]
	v_mfma_f32_16x16x32_bf16 v[10:13], v[196:199], v[176:179], v[74:77]
	v_mfma_f32_16x16x32_bf16 v[6:9], v[106:109], v[168:171], v[6:9]
	v_mfma_f32_16x16x32_bf16 v[2:5], v[196:199], v[168:171], v[2:5]
	v_mfma_f32_16x16x32_bf16 v[168:171], v[200:203], v[180:183], v[10:13]
	v_mfma_f32_16x16x32_bf16 v[10:13], v[106:109], v[184:187], v[78:81]
	v_mfma_f32_16x16x32_bf16 v[14:17], v[106:109], v[90:93], v[14:17]
	v_mfma_f32_16x16x32_bf16 v[6:9], v[110:113], v[172:175], v[6:9]
	v_mfma_f32_16x16x32_bf16 v[2:5], v[200:203], v[172:175], v[2:5]
	v_mfma_f32_16x16x32_bf16 v[172:175], v[110:113], v[188:191], v[10:13]
	v_mfma_f32_16x16x32_bf16 v[10:13], v[196:199], v[184:187], v[82:85]
	v_mfma_f32_16x16x32_bf16 v[134:137], v[110:113], v[94:97], v[14:17]
	v_mfma_f32_16x16x32_bf16 v[176:179], v[200:203], v[188:191], v[10:13]
	s_setprio 0
	s_barrier
	s_nop 3
	ds_read_b128 v[10:13], v151 offset:32768
	ds_read_b128 v[14:17], v151 offset:33792
	ds_read_b128 v[180:183], v151 offset:34816
	ds_read_b128 v[184:187], v151 offset:35840
	ds_read_b128 v[66:69], v0 offset:32768
	ds_read_b128 v[82:85], v0 offset:33792
	ds_read_b128 v[188:191], v0 offset:34816
	ds_read_b128 v[192:195], v0 offset:35840
	ds_read_b128 v[196:199], v0 offset:36864
	ds_read_b128 v[200:203], v0 offset:37888
	ds_read_b128 v[232:235], v0 offset:38912
	ds_read_b128 v[236:239], v0 offset:39936
	s_waitcnt vmcnt(2)
	s_barrier
	s_waitcnt lgkmcnt(0)
	s_setprio 1
	s_waitcnt lgkmcnt(7)
	v_mfma_f32_16x16x32_bf16 v[74:77], v[10:13], v[66:69], v[126:129]
	s_waitcnt lgkmcnt(6)
	v_mfma_f32_16x16x32_bf16 v[138:141], v[14:17], v[82:85], v[74:77]
	v_mfma_f32_16x16x32_bf16 v[74:77], v[180:183], v[66:69], v[122:125]
	v_mfma_f32_16x16x32_bf16 v[122:125], v[184:187], v[82:85], v[74:77]
	s_waitcnt lgkmcnt(5)
	v_mfma_f32_16x16x32_bf16 v[74:77], v[10:13], v[188:191], v[118:121]
	s_waitcnt lgkmcnt(4)
	v_mfma_f32_16x16x32_bf16 v[110:113], v[14:17], v[192:195], v[74:77]
	v_mfma_f32_16x16x32_bf16 v[74:77], v[180:183], v[188:191], v[114:117]
	v_mfma_f32_16x16x32_bf16 v[106:109], v[184:187], v[192:195], v[74:77]
	s_waitcnt lgkmcnt(3)
	v_mfma_f32_16x16x32_bf16 v[74:77], v[10:13], v[196:199], v[130:133]
	s_waitcnt lgkmcnt(2)
	v_mfma_f32_16x16x32_bf16 v[94:97], v[14:17], v[200:203], v[74:77]
	v_mfma_f32_16x16x32_bf16 v[74:77], v[180:183], v[196:199], v[160:163]
	v_mfma_f32_16x16x32_bf16 v[90:93], v[184:187], v[200:203], v[74:77]
	s_waitcnt lgkmcnt(1)
	v_mfma_f32_16x16x32_bf16 v[74:77], v[10:13], v[232:235], v[102:105]
	s_waitcnt lgkmcnt(0)
	v_mfma_f32_16x16x32_bf16 v[78:81], v[14:17], v[236:239], v[74:77]
	v_mfma_f32_16x16x32_bf16 v[74:77], v[180:183], v[232:235], v[98:101]
	v_mfma_f32_16x16x32_bf16 v[74:77], v[184:187], v[236:239], v[74:77]
	s_setprio 0
	s_barrier
	ds_read_b128 v[126:129], v151 offset:49152
	ds_read_b128 v[130:133], v151 offset:50176
	ds_read_b128 v[160:163], v151 offset:51200
	ds_read_b128 v[148:151], v151 offset:52224
	s_waitcnt vmcnt(0)
	s_barrier
	s_waitcnt lgkmcnt(0)
	s_setprio 1
	s_waitcnt lgkmcnt(3)
	v_mfma_f32_16x16x32_bf16 v[98:101], v[126:129], v[66:69], v[222:225]
	s_waitcnt lgkmcnt(1)
	v_mfma_f32_16x16x32_bf16 v[66:69], v[160:163], v[66:69], v[164:167]
	s_waitcnt lgkmcnt(0)
	v_mfma_f32_16x16x32_bf16 v[114:117], v[148:151], v[82:85], v[66:69]
	v_mfma_f32_16x16x32_bf16 v[66:69], v[126:129], v[188:191], v[86:89]
	v_mfma_f32_16x16x32_bf16 v[102:105], v[130:133], v[192:195], v[66:69]
	v_mfma_f32_16x16x32_bf16 v[66:69], v[160:163], v[188:191], v[70:73]
	v_mfma_f32_16x16x32_bf16 v[62:65], v[126:129], v[196:199], v[62:65]
	v_mfma_f32_16x16x32_bf16 v[58:61], v[160:163], v[196:199], v[58:61]
	v_mfma_f32_16x16x32_bf16 v[54:57], v[126:129], v[232:235], v[54:57]
	v_mfma_f32_16x16x32_bf16 v[50:53], v[160:163], v[232:235], v[50:53]
	v_mfma_f32_16x16x32_bf16 v[118:121], v[130:133], v[82:85], v[98:101]
	v_mfma_f32_16x16x32_bf16 v[98:101], v[148:151], v[192:195], v[66:69]
	v_mfma_f32_16x16x32_bf16 v[86:89], v[130:133], v[200:203], v[62:65]
	v_mfma_f32_16x16x32_bf16 v[82:85], v[148:151], v[200:203], v[58:61]
	v_mfma_f32_16x16x32_bf16 v[70:73], v[130:133], v[236:239], v[54:57]
	v_mfma_f32_16x16x32_bf16 v[66:69], v[148:151], v[236:239], v[50:53]
	s_setprio 0
	s_barrier
	s_nop 0
	ds_read_b128 v[50:53], v0 offset:49152
	ds_read_b128 v[164:167], v0 offset:50176
	ds_read_b128 v[188:191], v0 offset:51200
	ds_read_b128 v[192:195], v0 offset:52224
	ds_read_b128 v[196:199], v0 offset:53248
	ds_read_b128 v[200:203], v0 offset:54272
	ds_read_b128 v[222:225], v0 offset:55296
	ds_read_b128 v[232:235], v0 offset:56320
	s_barrier
	s_waitcnt lgkmcnt(0)
	s_setprio 1
	s_waitcnt lgkmcnt(7)
	v_mfma_f32_16x16x32_bf16 v[46:49], v[10:13], v[50:53], v[46:49]
	s_waitcnt lgkmcnt(5)
	v_mfma_f32_16x16x32_bf16 v[38:41], v[10:13], v[188:191], v[38:41]
	s_waitcnt lgkmcnt(3)
	v_mfma_f32_16x16x32_bf16 v[30:33], v[10:13], v[196:199], v[30:33]
	s_waitcnt lgkmcnt(1)
	v_mfma_f32_16x16x32_bf16 v[10:13], v[10:13], v[222:225], v[22:25]
	v_mfma_f32_16x16x32_bf16 v[62:65], v[14:17], v[164:167], v[46:49]
	v_mfma_f32_16x16x32_bf16 v[42:45], v[180:183], v[50:53], v[42:45]
	v_mfma_f32_16x16x32_bf16 v[46:49], v[14:17], v[192:195], v[38:41]
	v_mfma_f32_16x16x32_bf16 v[34:37], v[180:183], v[188:191], v[34:37]
	v_mfma_f32_16x16x32_bf16 v[30:33], v[14:17], v[200:203], v[30:33]
	v_mfma_f32_16x16x32_bf16 v[26:29], v[180:183], v[196:199], v[26:29]
	s_waitcnt lgkmcnt(0)
	v_mfma_f32_16x16x32_bf16 v[14:17], v[14:17], v[232:235], v[10:13]
	v_mfma_f32_16x16x32_bf16 v[10:13], v[180:183], v[222:225], v[18:21]
	v_mfma_f32_16x16x32_bf16 v[58:61], v[184:187], v[164:167], v[42:45]
	v_mfma_f32_16x16x32_bf16 v[42:45], v[184:187], v[192:195], v[34:37]
	v_mfma_f32_16x16x32_bf16 v[26:29], v[184:187], v[200:203], v[26:29]
	v_mfma_f32_16x16x32_bf16 v[10:13], v[184:187], v[232:235], v[10:13]
	s_setprio 0
	s_setprio 1
	v_mfma_f32_16x16x32_bf16 v[2:5], v[160:163], v[188:191], v[2:5]
	v_mfma_f32_16x16x32_bf16 v[18:21], v[126:129], v[50:53], v[134:137]
	v_mfma_f32_16x16x32_bf16 v[34:37], v[148:151], v[192:195], v[2:5]
	v_mfma_f32_16x16x32_bf16 v[2:5], v[126:129], v[196:199], v[156:159]
	v_mfma_f32_16x16x32_bf16 v[54:57], v[130:133], v[164:167], v[18:21]
	v_mfma_f32_16x16x32_bf16 v[18:21], v[160:163], v[50:53], v[152:155]
	v_mfma_f32_16x16x32_bf16 v[22:25], v[130:133], v[200:203], v[2:5]
	v_mfma_f32_16x16x32_bf16 v[2:5], v[160:163], v[196:199], v[168:171]
	v_mfma_f32_16x16x32_bf16 v[50:53], v[148:151], v[164:167], v[18:21]
	v_mfma_f32_16x16x32_bf16 v[6:9], v[126:129], v[188:191], v[6:9]
	v_mfma_f32_16x16x32_bf16 v[18:21], v[148:151], v[200:203], v[2:5]
	v_mfma_f32_16x16x32_bf16 v[2:5], v[126:129], v[222:225], v[172:175]
	v_mfma_f32_16x16x32_bf16 v[38:41], v[130:133], v[192:195], v[6:9]
	v_mfma_f32_16x16x32_bf16 v[6:9], v[130:133], v[232:235], v[2:5]
	v_mfma_f32_16x16x32_bf16 v[2:5], v[160:163], v[222:225], v[176:179]
	v_mfma_f32_16x16x32_bf16 v[2:5], v[148:151], v[232:235], v[2:5]
	s_setprio 0
	s_movk_i32 s0, 0x100
	v_cmp_gt_u32_e32 vcc, s0, v142
	s_barrier
	s_and_saveexec_b64 s[0:1], vcc
	s_cbranch_execz .LBB0_37
	s_barrier

.LBB0_85:
	ds_read_b128 v[164:167], v151
	ds_read_b128 v[168:171], v151 offset:1024
	ds_read_b128 v[172:175], v151 offset:2048
	ds_read_b128 v[176:179], v151 offset:3072
	v_add_u32_e32 v162, 0xc000, v147
	v_lshl_add_u64 v[204:205], v[138:139], 0, s[10:11]
	v_lshl_add_u64 v[228:229], v[204:205], 0, s[60:61]
	s_add_i32 m0, s1, 0xc000
	v_add_u32_e32 v163, 0xe000, v147
	ds_read_b128 v[180:183], v0
	ds_read_b128 v[184:187], v0 offset:1024
	ds_read_b128 v[188:191], v0 offset:2048
	ds_read_b128 v[192:195], v0 offset:3072
	ds_read_b128 v[196:199], v0 offset:4096
	ds_read_b128 v[200:203], v0 offset:5120
	ds_read_b128 v[222:225], v0 offset:6144
	ds_read_b128 v[232:235], v0 offset:7168
	global_load_lds_dwordx4 v[228:229], off
	v_lshl_add_u64 v[210:211], v[140:141], 0, s[10:11]
	v_lshl_add_u64 v[152:153], v[210:211], 0, s[60:61]
	s_add_i32 m0, s1, 0xe000
	s_nop 0
	global_load_lds_dwordx4 v[152:153], off
	s_waitcnt lgkmcnt(8)
	s_barrier
	s_waitcnt lgkmcnt(0)
	s_setprio 1
	s_waitcnt lgkmcnt(0)
	v_mfma_f32_16x16x32_bf16 v[126:129], v[164:167], v[180:183], v[126:129]
	v_mfma_f32_16x16x32_bf16 v[122:125], v[172:175], v[180:183], v[122:125]
	v_mfma_f32_16x16x32_bf16 v[118:121], v[164:167], v[188:191], v[118:121]
	v_mfma_f32_16x16x32_bf16 v[114:117], v[172:175], v[188:191], v[114:117]
	v_mfma_f32_16x16x32_bf16 v[110:113], v[164:167], v[196:199], v[110:113]
	v_mfma_f32_16x16x32_bf16 v[106:109], v[172:175], v[196:199], v[106:109]
	v_mfma_f32_16x16x32_bf16 v[102:105], v[164:167], v[222:225], v[102:105]
	v_mfma_f32_16x16x32_bf16 v[98:101], v[172:175], v[222:225], v[98:101]
	v_mfma_f32_16x16x32_bf16 v[126:129], v[168:171], v[184:187], v[126:129]
	v_mfma_f32_16x16x32_bf16 v[122:125], v[176:179], v[184:187], v[122:125]
	v_mfma_f32_16x16x32_bf16 v[118:121], v[168:171], v[192:195], v[118:121]
	v_mfma_f32_16x16x32_bf16 v[114:117], v[176:179], v[192:195], v[114:117]
	v_mfma_f32_16x16x32_bf16 v[110:113], v[168:171], v[200:203], v[110:113]
	v_mfma_f32_16x16x32_bf16 v[106:109], v[176:179], v[200:203], v[106:109]
	v_mfma_f32_16x16x32_bf16 v[102:105], v[168:171], v[232:235], v[102:105]
	v_mfma_f32_16x16x32_bf16 v[98:101], v[176:179], v[232:235], v[98:101]
	s_setprio 0
	s_barrier
	v_lshl_add_u64 v[216:217], v[134:135], 0, s[10:11]
	s_add_i32 m0, s1, 0xff00
	ds_read_b128 v[236:239], v151 offset:16384
	ds_read_b128 v[240:243], v151 offset:17408
	ds_read_b128 v[244:247], v151 offset:18432
	ds_read_b128 v[248:251], v151 offset:19456
	global_load_lds_dwordx4 v[216:217], off offset:256
	v_lshl_add_u64 v[218:219], v[136:137], 0, s[10:11]
	s_add_i32 m0, s1, 0x11f00
	s_nop 0
	global_load_lds_dwordx4 v[218:219], off offset:256
	s_barrier
	s_waitcnt lgkmcnt(0)
	s_setprio 1
	s_waitcnt lgkmcnt(0)
	v_mfma_f32_16x16x32_bf16 v[94:97], v[236:239], v[180:183], v[94:97]
	v_mfma_f32_16x16x32_bf16 v[90:93], v[244:247], v[180:183], v[90:93]
	v_mfma_f32_16x16x32_bf16 v[86:89], v[236:239], v[188:191], v[86:89]
	v_mfma_f32_16x16x32_bf16 v[82:85], v[244:247], v[188:191], v[82:85]
	v_mfma_f32_16x16x32_bf16 v[78:81], v[236:239], v[196:199], v[78:81]
	v_mfma_f32_16x16x32_bf16 v[74:77], v[244:247], v[196:199], v[74:77]
	v_mfma_f32_16x16x32_bf16 v[70:73], v[236:239], v[222:225], v[70:73]
	v_mfma_f32_16x16x32_bf16 v[66:69], v[244:247], v[222:225], v[66:69]
	v_mfma_f32_16x16x32_bf16 v[94:97], v[240:243], v[184:187], v[94:97]
	v_mfma_f32_16x16x32_bf16 v[90:93], v[248:251], v[184:187], v[90:93]
	v_mfma_f32_16x16x32_bf16 v[86:89], v[240:243], v[192:195], v[86:89]
	v_mfma_f32_16x16x32_bf16 v[82:85], v[248:251], v[192:195], v[82:85]
	v_mfma_f32_16x16x32_bf16 v[78:81], v[240:243], v[200:203], v[78:81]
	v_mfma_f32_16x16x32_bf16 v[74:77], v[248:251], v[200:203], v[74:77]
	v_mfma_f32_16x16x32_bf16 v[70:73], v[240:243], v[232:235], v[70:73]
	v_mfma_f32_16x16x32_bf16 v[66:69], v[248:251], v[232:235], v[66:69]
	s_setprio 0
	v_lshl_add_u64 v[158:159], v[204:205], 0, s[74:75]
	s_mov_b32 m0, s1
	s_barrier
	ds_read_b128 v[180:183], v0 offset:16384
	ds_read_b128 v[184:187], v0 offset:17408
	ds_read_b128 v[188:191], v0 offset:18432
	ds_read_b128 v[192:195], v0 offset:19456
	ds_read_b128 v[196:199], v0 offset:20480
	ds_read_b128 v[200:203], v0 offset:21504
	ds_read_b128 v[222:225], v0 offset:22528
	ds_read_b128 v[232:235], v0 offset:23552
	global_load_lds_dwordx4 v[158:159], off
	s_add_i32 m0, s1, 0x1f00
	s_nop 0
	global_load_lds_dwordx4 v[210:211], off offset:256
	s_barrier
	s_waitcnt lgkmcnt(0)
	s_setprio 1
	s_waitcnt lgkmcnt(0)
	v_mfma_f32_16x16x32_bf16 v[62:65], v[164:167], v[180:183], v[62:65]
	v_mfma_f32_16x16x32_bf16 v[58:61], v[172:175], v[180:183], v[58:61]
	v_mfma_f32_16x16x32_bf16 v[54:57], v[164:167], v[188:191], v[54:57]
	v_mfma_f32_16x16x32_bf16 v[50:53], v[172:175], v[188:191], v[50:53]
	v_mfma_f32_16x16x32_bf16 v[46:49], v[164:167], v[196:199], v[46:49]
	v_mfma_f32_16x16x32_bf16 v[42:45], v[172:175], v[196:199], v[42:45]
	v_mfma_f32_16x16x32_bf16 v[38:41], v[164:167], v[222:225], v[38:41]
	v_mfma_f32_16x16x32_bf16 v[34:37], v[172:175], v[222:225], v[34:37]
	v_mfma_f32_16x16x32_bf16 v[62:65], v[168:171], v[184:187], v[62:65]
	v_mfma_f32_16x16x32_bf16 v[58:61], v[176:179], v[184:187], v[58:61]
	v_mfma_f32_16x16x32_bf16 v[54:57], v[168:171], v[192:195], v[54:57]
	v_mfma_f32_16x16x32_bf16 v[50:53], v[176:179], v[192:195], v[50:53]
	v_mfma_f32_16x16x32_bf16 v[46:49], v[168:171], v[200:203], v[46:49]
	v_mfma_f32_16x16x32_bf16 v[42:45], v[176:179], v[200:203], v[42:45]
	v_mfma_f32_16x16x32_bf16 v[38:41], v[168:171], v[232:235], v[38:41]
	v_mfma_f32_16x16x32_bf16 v[34:37], v[176:179], v[232:235], v[34:37]
	s_setprio 0
	s_barrier
	v_lshl_add_u64 v[154:155], v[216:217], 0, s[18:19]
	s_add_i32 m0, s1, 0x14000
	s_nop 0
	global_load_lds_dwordx4 v[154:155], off
	v_lshl_add_u64 v[156:157], v[218:219], 0, s[18:19]
	s_add_i32 m0, s1, 0x16000
	s_nop 0
	global_load_lds_dwordx4 v[156:157], off
	s_waitcnt vmcnt(6)
	s_barrier
	s_setprio 1
	v_mfma_f32_16x16x32_bf16 v[30:33], v[236:239], v[180:183], v[30:33]
	v_mfma_f32_16x16x32_bf16 v[26:29], v[244:247], v[180:183], v[26:29]
	v_mfma_f32_16x16x32_bf16 v[22:25], v[236:239], v[188:191], v[22:25]
	v_mfma_f32_16x16x32_bf16 v[18:21], v[244:247], v[188:191], v[18:21]
	v_mfma_f32_16x16x32_bf16 v[14:17], v[236:239], v[196:199], v[14:17]
	v_mfma_f32_16x16x32_bf16 v[10:13], v[244:247], v[196:199], v[10:13]
	v_mfma_f32_16x16x32_bf16 v[6:9], v[236:239], v[222:225], v[6:9]
	v_mfma_f32_16x16x32_bf16 v[2:5], v[244:247], v[222:225], v[2:5]
	v_mfma_f32_16x16x32_bf16 v[30:33], v[240:243], v[184:187], v[30:33]
	v_mfma_f32_16x16x32_bf16 v[26:29], v[248:251], v[184:187], v[26:29]
	v_mfma_f32_16x16x32_bf16 v[22:25], v[240:243], v[192:195], v[22:25]
	v_mfma_f32_16x16x32_bf16 v[18:21], v[248:251], v[192:195], v[18:21]
	v_mfma_f32_16x16x32_bf16 v[14:17], v[240:243], v[200:203], v[14:17]
	v_mfma_f32_16x16x32_bf16 v[10:13], v[248:251], v[200:203], v[10:13]
	v_mfma_f32_16x16x32_bf16 v[6:9], v[240:243], v[232:235], v[6:9]
	v_mfma_f32_16x16x32_bf16 v[2:5], v[248:251], v[232:235], v[2:5]
	s_setprio 0
	s_barrier
	ds_read_b128 v[164:167], v151 offset:32768
	ds_read_b128 v[168:171], v151 offset:33792
	ds_read_b128 v[172:175], v151 offset:34816
	ds_read_b128 v[176:179], v151 offset:35840
	s_add_i32 m0, s1, 0x3f80
	ds_read_b128 v[180:183], v0 offset:32768
	ds_read_b128 v[184:187], v0 offset:33792
	ds_read_b128 v[188:191], v0 offset:34816
	ds_read_b128 v[192:195], v0 offset:35840
	ds_read_b128 v[196:199], v0 offset:36864
	ds_read_b128 v[200:203], v0 offset:37888
	ds_read_b128 v[222:225], v0 offset:38912
	ds_read_b128 v[232:235], v0 offset:39936
	global_load_lds_dwordx4 v[228:229], off offset:128
	s_add_i32 m0, s1, 0x5f80
	s_nop 0
	global_load_lds_dwordx4 v[152:153], off offset:128
	s_waitcnt lgkmcnt(8)
	s_barrier
	s_waitcnt lgkmcnt(0)
	s_setprio 1
	s_waitcnt lgkmcnt(0)
	v_mfma_f32_16x16x32_bf16 v[126:129], v[164:167], v[180:183], v[126:129]
	v_mfma_f32_16x16x32_bf16 v[122:125], v[172:175], v[180:183], v[122:125]
	v_mfma_f32_16x16x32_bf16 v[118:121], v[164:167], v[188:191], v[118:121]
	v_mfma_f32_16x16x32_bf16 v[114:117], v[172:175], v[188:191], v[114:117]
	v_mfma_f32_16x16x32_bf16 v[110:113], v[164:167], v[196:199], v[110:113]
	v_mfma_f32_16x16x32_bf16 v[106:109], v[172:175], v[196:199], v[106:109]
	v_mfma_f32_16x16x32_bf16 v[102:105], v[164:167], v[222:225], v[102:105]
	v_mfma_f32_16x16x32_bf16 v[98:101], v[172:175], v[222:225], v[98:101]
	v_mfma_f32_16x16x32_bf16 v[126:129], v[168:171], v[184:187], v[126:129]
	v_mfma_f32_16x16x32_bf16 v[122:125], v[176:179], v[184:187], v[122:125]
	v_mfma_f32_16x16x32_bf16 v[118:121], v[168:171], v[192:195], v[118:121]
	v_mfma_f32_16x16x32_bf16 v[114:117], v[176:179], v[192:195], v[114:117]
	v_mfma_f32_16x16x32_bf16 v[110:113], v[168:171], v[200:203], v[110:113]
	v_mfma_f32_16x16x32_bf16 v[106:109], v[176:179], v[200:203], v[106:109]
	v_mfma_f32_16x16x32_bf16 v[102:105], v[168:171], v[232:235], v[102:105]
	v_mfma_f32_16x16x32_bf16 v[98:101], v[176:179], v[232:235], v[98:101]
	s_setprio 0
	s_barrier
	s_add_i32 m0, s1, 0x17e80
	ds_read_b128 v[236:239], v151 offset:49152
	ds_read_b128 v[240:243], v151 offset:50176
	ds_read_b128 v[244:247], v151 offset:51200
	ds_read_b128 v[248:251], v151 offset:52224
	global_load_lds_dwordx4 v[216:217], off offset:384
	s_add_i32 m0, s1, 0x19e80
	s_nop 0
	global_load_lds_dwordx4 v[218:219], off offset:384
	s_barrier
	s_waitcnt lgkmcnt(0)
	s_setprio 1
	s_waitcnt lgkmcnt(0)
	v_mfma_f32_16x16x32_bf16 v[94:97], v[236:239], v[180:183], v[94:97]
	v_mfma_f32_16x16x32_bf16 v[90:93], v[244:247], v[180:183], v[90:93]
	v_mfma_f32_16x16x32_bf16 v[86:89], v[236:239], v[188:191], v[86:89]
	v_mfma_f32_16x16x32_bf16 v[82:85], v[244:247], v[188:191], v[82:85]
	v_mfma_f32_16x16x32_bf16 v[78:81], v[236:239], v[196:199], v[78:81]
	v_mfma_f32_16x16x32_bf16 v[74:77], v[244:247], v[196:199], v[74:77]
	v_mfma_f32_16x16x32_bf16 v[70:73], v[236:239], v[222:225], v[70:73]
	v_mfma_f32_16x16x32_bf16 v[66:69], v[244:247], v[222:225], v[66:69]
	v_mfma_f32_16x16x32_bf16 v[94:97], v[240:243], v[184:187], v[94:97]
	v_mfma_f32_16x16x32_bf16 v[90:93], v[248:251], v[184:187], v[90:93]
	v_mfma_f32_16x16x32_bf16 v[86:89], v[240:243], v[192:195], v[86:89]
	v_mfma_f32_16x16x32_bf16 v[82:85], v[248:251], v[192:195], v[82:85]
	v_mfma_f32_16x16x32_bf16 v[78:81], v[240:243], v[200:203], v[78:81]
	v_mfma_f32_16x16x32_bf16 v[74:77], v[248:251], v[200:203], v[74:77]
	v_mfma_f32_16x16x32_bf16 v[70:73], v[240:243], v[232:235], v[70:73]
	v_mfma_f32_16x16x32_bf16 v[66:69], v[248:251], v[232:235], v[66:69]
	s_setprio 0
	s_add_i32 m0, s1, 0x7e80
	s_barrier
	ds_read_b128 v[180:183], v0 offset:49152
	ds_read_b128 v[184:187], v0 offset:50176
	ds_read_b128 v[188:191], v0 offset:51200
	ds_read_b128 v[192:195], v0 offset:52224
	ds_read_b128 v[196:199], v0 offset:53248
	ds_read_b128 v[200:203], v0 offset:54272
	ds_read_b128 v[222:225], v0 offset:55296
	ds_read_b128 v[232:235], v0 offset:56320
	global_load_lds_dwordx4 v[204:205], off offset:384
	s_add_i32 m0, s1, 0x9e80
	s_nop 0
	global_load_lds_dwordx4 v[210:211], off offset:384
	s_barrier
	s_waitcnt lgkmcnt(0)
	s_setprio 1
	s_waitcnt lgkmcnt(0)
	v_mfma_f32_16x16x32_bf16 v[62:65], v[164:167], v[180:183], v[62:65]
	v_mfma_f32_16x16x32_bf16 v[58:61], v[172:175], v[180:183], v[58:61]
	v_mfma_f32_16x16x32_bf16 v[54:57], v[164:167], v[188:191], v[54:57]
	v_mfma_f32_16x16x32_bf16 v[50:53], v[172:175], v[188:191], v[50:53]
	v_mfma_f32_16x16x32_bf16 v[46:49], v[164:167], v[196:199], v[46:49]
	v_mfma_f32_16x16x32_bf16 v[42:45], v[172:175], v[196:199], v[42:45]
	v_mfma_f32_16x16x32_bf16 v[38:41], v[164:167], v[222:225], v[38:41]
	v_mfma_f32_16x16x32_bf16 v[34:37], v[172:175], v[222:225], v[34:37]
	v_mfma_f32_16x16x32_bf16 v[62:65], v[168:171], v[184:187], v[62:65]
	v_mfma_f32_16x16x32_bf16 v[58:61], v[176:179], v[184:187], v[58:61]
	v_mfma_f32_16x16x32_bf16 v[54:57], v[168:171], v[192:195], v[54:57]
	v_mfma_f32_16x16x32_bf16 v[50:53], v[176:179], v[192:195], v[50:53]
	v_mfma_f32_16x16x32_bf16 v[46:49], v[168:171], v[200:203], v[46:49]
	v_mfma_f32_16x16x32_bf16 v[42:45], v[176:179], v[200:203], v[42:45]
	v_mfma_f32_16x16x32_bf16 v[38:41], v[168:171], v[232:235], v[38:41]
	v_mfma_f32_16x16x32_bf16 v[34:37], v[176:179], v[232:235], v[34:37]
	s_setprio 0
	s_barrier
	s_add_i32 m0, s1, 0x1bf80
	s_nop 0
	global_load_lds_dwordx4 v[154:155], off offset:128
	s_add_i32 m0, s1, 0x1df80
	s_nop 0
	global_load_lds_dwordx4 v[156:157], off offset:128
	s_waitcnt vmcnt(6)
	s_barrier
	s_setprio 1
	v_mfma_f32_16x16x32_bf16 v[30:33], v[236:239], v[180:183], v[30:33]
	v_mfma_f32_16x16x32_bf16 v[26:29], v[244:247], v[180:183], v[26:29]
	v_mfma_f32_16x16x32_bf16 v[22:25], v[236:239], v[188:191], v[22:25]
	v_mfma_f32_16x16x32_bf16 v[18:21], v[244:247], v[188:191], v[18:21]
	v_mfma_f32_16x16x32_bf16 v[14:17], v[236:239], v[196:199], v[14:17]
	v_mfma_f32_16x16x32_bf16 v[10:13], v[244:247], v[196:199], v[10:13]
	v_mfma_f32_16x16x32_bf16 v[6:9], v[236:239], v[222:225], v[6:9]
	v_mfma_f32_16x16x32_bf16 v[2:5], v[244:247], v[222:225], v[2:5]
	v_mfma_f32_16x16x32_bf16 v[30:33], v[240:243], v[184:187], v[30:33]
	v_mfma_f32_16x16x32_bf16 v[26:29], v[248:251], v[184:187], v[26:29]
	v_mfma_f32_16x16x32_bf16 v[22:25], v[240:243], v[192:195], v[22:25]
	v_mfma_f32_16x16x32_bf16 v[18:21], v[248:251], v[192:195], v[18:21]
	v_mfma_f32_16x16x32_bf16 v[14:17], v[240:243], v[200:203], v[14:17]
	v_mfma_f32_16x16x32_bf16 v[10:13], v[248:251], v[200:203], v[10:13]
	v_mfma_f32_16x16x32_bf16 v[6:9], v[240:243], v[232:235], v[6:9]
	v_mfma_f32_16x16x32_bf16 v[2:5], v[248:251], v[232:235], v[2:5]
	s_setprio 0
	s_add_i32 s0, s0, 2
	s_add_u32 s10, s10, 0x100
	s_addc_u32 s11, s11, 0
	s_cmp_lt_u32 s0, 28
	s_barrier
	s_cbranch_scc1 .LBB0_85
	s_add_i32 s1, s1, 0x1e000
	s_mov_b64 s[10:11], 0xf80
	v_readfirstlane_b32 s0, v162
	v_lshl_add_u64 v[132:133], v[132:133], 0, s[10:11]
	s_mov_b32 m0, s0
	v_readfirstlane_b32 s0, v163
	ds_read_b128 v[134:137], v151
	ds_read_b128 v[138:141], v151 offset:1024
	ds_read_b128 v[152:155], v151 offset:2048
	ds_read_b128 v[156:159], v151 offset:3072
	ds_read_b128 v[164:167], v0
	ds_read_b128 v[168:171], v0 offset:1024
	ds_read_b128 v[172:175], v0 offset:2048
	ds_read_b128 v[176:179], v0 offset:3072
	ds_read_b128 v[180:183], v0 offset:4096
	ds_read_b128 v[184:187], v0 offset:5120
	ds_read_b128 v[188:191], v0 offset:6144
	ds_read_b128 v[192:195], v0 offset:7168
	global_load_lds_dwordx4 v[132:133], off
	v_lshl_add_u64 v[130:131], v[130:131], 0, s[10:11]
	s_mov_b32 m0, s0
	s_nop 0
	global_load_lds_dwordx4 v[130:131], off
	s_barrier
	s_waitcnt lgkmcnt(0)
	s_setprio 1
	s_waitcnt lgkmcnt(0)
	v_mfma_f32_16x16x32_bf16 v[126:129], v[134:137], v[164:167], v[126:129]
	v_mfma_f32_16x16x32_bf16 v[122:125], v[152:155], v[164:167], v[122:125]
	v_mfma_f32_16x16x32_bf16 v[114:117], v[152:155], v[172:175], v[114:117]
	v_mfma_f32_16x16x32_bf16 v[106:109], v[152:155], v[180:183], v[106:109]
	v_mfma_f32_16x16x32_bf16 v[98:101], v[152:155], v[188:191], v[98:101]
	v_mfma_f32_16x16x32_bf16 v[126:129], v[138:141], v[168:171], v[126:129]
	v_mfma_f32_16x16x32_bf16 v[122:125], v[156:159], v[168:171], v[122:125]
	v_mfma_f32_16x16x32_bf16 v[118:121], v[134:137], v[172:175], v[118:121]
	v_mfma_f32_16x16x32_bf16 v[114:117], v[156:159], v[176:179], v[114:117]
	v_mfma_f32_16x16x32_bf16 v[110:113], v[134:137], v[180:183], v[110:113]
	v_mfma_f32_16x16x32_bf16 v[106:109], v[156:159], v[184:187], v[106:109]
	v_mfma_f32_16x16x32_bf16 v[102:105], v[134:137], v[188:191], v[102:105]
	v_mfma_f32_16x16x32_bf16 v[98:101], v[156:159], v[192:195], v[98:101]
	v_mfma_f32_16x16x32_bf16 v[130:133], v[138:141], v[176:179], v[118:121]
	v_mfma_f32_16x16x32_bf16 v[160:163], v[138:141], v[184:187], v[110:113]
	v_mfma_f32_16x16x32_bf16 v[196:199], v[138:141], v[192:195], v[102:105]
	s_setprio 0
	s_barrier
	s_nop 0
	ds_read_b128 v[102:105], v151 offset:16384
	ds_read_b128 v[110:113], v151 offset:17408
	ds_read_b128 v[118:121], v151 offset:18432
	ds_read_b128 v[200:203], v151 offset:19456
	s_barrier
	s_waitcnt lgkmcnt(0)
	s_setprio 1
	s_waitcnt lgkmcnt(1)
	v_mfma_f32_16x16x32_bf16 v[90:93], v[118:121], v[164:167], v[90:93]
	v_mfma_f32_16x16x32_bf16 v[86:89], v[102:105], v[172:175], v[86:89]
	v_mfma_f32_16x16x32_bf16 v[82:85], v[118:121], v[172:175], v[82:85]
	v_mfma_f32_16x16x32_bf16 v[78:81], v[102:105], v[180:183], v[78:81]
	v_mfma_f32_16x16x32_bf16 v[70:73], v[102:105], v[188:191], v[70:73]
	v_mfma_f32_16x16x32_bf16 v[94:97], v[102:105], v[164:167], v[94:97]
	s_waitcnt lgkmcnt(0)
	v_mfma_f32_16x16x32_bf16 v[90:93], v[200:203], v[168:171], v[90:93]
	v_mfma_f32_16x16x32_bf16 v[86:89], v[110:113], v[176:179], v[86:89]
	v_mfma_f32_16x16x32_bf16 v[82:85], v[200:203], v[176:179], v[82:85]
	v_mfma_f32_16x16x32_bf16 v[78:81], v[110:113], v[184:187], v[78:81]
	v_mfma_f32_16x16x32_bf16 v[74:77], v[118:121], v[180:183], v[74:77]
	v_mfma_f32_16x16x32_bf16 v[70:73], v[110:113], v[192:195], v[70:73]
	v_mfma_f32_16x16x32_bf16 v[66:69], v[118:121], v[188:191], v[66:69]
	v_mfma_f32_16x16x32_bf16 v[222:225], v[110:113], v[168:171], v[94:97]
	v_mfma_f32_16x16x32_bf16 v[164:167], v[200:203], v[184:187], v[74:77]
	v_mfma_f32_16x16x32_bf16 v[168:171], v[200:203], v[192:195], v[66:69]
	s_setprio 0
	s_barrier
	s_nop 2
	ds_read_b128 v[66:69], v0 offset:16384
	ds_read_b128 v[74:77], v0 offset:17408
	ds_read_b128 v[94:97], v0 offset:18432
	ds_read_b128 v[172:175], v0 offset:19456
	ds_read_b128 v[176:179], v0 offset:20480
	ds_read_b128 v[180:183], v0 offset:21504
	ds_read_b128 v[184:187], v0 offset:22528
	ds_read_b128 v[188:191], v0 offset:23552
	s_waitcnt vmcnt(4)
	s_barrier
	s_waitcnt lgkmcnt(0)
	s_setprio 1
	s_waitcnt lgkmcnt(5)
	v_mfma_f32_16x16x32_bf16 v[54:57], v[134:137], v[94:97], v[54:57]
	v_mfma_f32_16x16x32_bf16 v[50:53], v[152:155], v[94:97], v[50:53]
	v_mfma_f32_16x16x32_bf16 v[62:65], v[134:137], v[66:69], v[62:65]
	v_mfma_f32_16x16x32_bf16 v[58:61], v[152:155], v[66:69], v[58:61]
	s_waitcnt lgkmcnt(4)
	v_mfma_f32_16x16x32_bf16 v[54:57], v[138:141], v[172:175], v[54:57]
	v_mfma_f32_16x16x32_bf16 v[50:53], v[156:159], v[172:175], v[50:53]
	s_waitcnt lgkmcnt(3)
	v_mfma_f32_16x16x32_bf16 v[46:49], v[134:137], v[176:179], v[46:49]
	v_mfma_f32_16x16x32_bf16 v[42:45], v[152:155], v[176:179], v[42:45]
	s_waitcnt lgkmcnt(1)
	v_mfma_f32_16x16x32_bf16 v[38:41], v[134:137], v[184:187], v[38:41]
	v_mfma_f32_16x16x32_bf16 v[34:37], v[152:155], v[184:187], v[34:37]
	v_mfma_f32_16x16x32_bf16 v[192:195], v[138:141], v[74:77], v[62:65]
	v_mfma_f32_16x16x32_bf16 v[232:235], v[156:159], v[74:77], v[58:61]
	v_mfma_f32_16x16x32_bf16 v[236:239], v[138:141], v[180:183], v[46:49]
	v_mfma_f32_16x16x32_bf16 v[240:243], v[156:159], v[180:183], v[42:45]
	s_waitcnt lgkmcnt(0)
	v_mfma_f32_16x16x32_bf16 v[134:137], v[138:141], v[188:191], v[38:41]
	v_mfma_f32_16x16x32_bf16 v[138:141], v[156:159], v[188:191], v[34:37]
	s_setprio 0
	s_setprio 1
	v_mfma_f32_16x16x32_bf16 v[30:33], v[102:105], v[66:69], v[30:33]
	v_mfma_f32_16x16x32_bf16 v[26:29], v[118:121], v[66:69], v[26:29]
	v_mfma_f32_16x16x32_bf16 v[14:17], v[102:105], v[176:179], v[14:17]
	v_mfma_f32_16x16x32_bf16 v[10:13], v[118:121], v[176:179], v[10:13]
	v_mfma_f32_16x16x32_bf16 v[30:33], v[110:113], v[74:77], v[30:33]
	v_mfma_f32_16x16x32_bf16 v[26:29], v[200:203], v[74:77], v[26:29]
	v_mfma_f32_16x16x32_bf16 v[22:25], v[102:105], v[94:97], v[22:25]
	v_mfma_f32_16x16x32_bf16 v[18:21], v[118:121], v[94:97], v[18:21]
	v_mfma_f32_16x16x32_bf16 v[14:17], v[110:113], v[180:183], v[14:17]
	v_mfma_f32_16x16x32_bf16 v[10:13], v[200:203], v[180:183], v[10:13]
	v_mfma_f32_16x16x32_bf16 v[6:9], v[102:105], v[184:187], v[6:9]
	v_mfma_f32_16x16x32_bf16 v[2:5], v[118:121], v[184:187], v[2:5]
	v_mfma_f32_16x16x32_bf16 v[152:155], v[110:113], v[172:175], v[22:25]
	v_mfma_f32_16x16x32_bf16 v[156:159], v[200:203], v[172:175], v[18:21]
	v_mfma_f32_16x16x32_bf16 v[172:175], v[110:113], v[188:191], v[6:9]
	v_mfma_f32_16x16x32_bf16 v[176:179], v[200:203], v[188:191], v[2:5]
	s_setprio 0
	s_barrier
	s_nop 1
	ds_read_b128 v[2:5], v151 offset:32768
	ds_read_b128 v[6:9], v151 offset:33792
	ds_read_b128 v[180:183], v151 offset:34816
	ds_read_b128 v[184:187], v151 offset:35840
	ds_read_b128 v[18:21], v0 offset:32768
	ds_read_b128 v[22:25], v0 offset:33792
	ds_read_b128 v[38:41], v0 offset:34816
	ds_read_b128 v[46:49], v0 offset:35840
	ds_read_b128 v[58:61], v0 offset:36864
	ds_read_b128 v[66:69], v0 offset:37888
	ds_read_b128 v[188:191], v0 offset:38912
	ds_read_b128 v[200:203], v0 offset:39936
	s_waitcnt vmcnt(2)
	s_barrier
	s_waitcnt lgkmcnt(0)
	s_setprio 1
	s_waitcnt lgkmcnt(7)
	v_mfma_f32_16x16x32_bf16 v[34:37], v[2:5], v[18:21], v[126:129]
	s_waitcnt lgkmcnt(6)
	v_mfma_f32_16x16x32_bf16 v[118:121], v[6:9], v[22:25], v[34:37]
	v_mfma_f32_16x16x32_bf16 v[34:37], v[180:183], v[18:21], v[122:125]
	v_mfma_f32_16x16x32_bf16 v[110:113], v[184:187], v[22:25], v[34:37]
	s_waitcnt lgkmcnt(5)
	v_mfma_f32_16x16x32_bf16 v[34:37], v[2:5], v[38:41], v[130:133]
	s_waitcnt lgkmcnt(4)
	v_mfma_f32_16x16x32_bf16 v[102:105], v[6:9], v[46:49], v[34:37]
	v_mfma_f32_16x16x32_bf16 v[34:37], v[180:183], v[38:41], v[114:117]
	v_mfma_f32_16x16x32_bf16 v[94:97], v[184:187], v[46:49], v[34:37]
	s_waitcnt lgkmcnt(3)
	v_mfma_f32_16x16x32_bf16 v[34:37], v[2:5], v[58:61], v[160:163]
	s_waitcnt lgkmcnt(2)
	v_mfma_f32_16x16x32_bf16 v[74:77], v[6:9], v[66:69], v[34:37]
	v_mfma_f32_16x16x32_bf16 v[34:37], v[180:183], v[58:61], v[106:109]
	v_mfma_f32_16x16x32_bf16 v[62:65], v[184:187], v[66:69], v[34:37]
	s_waitcnt lgkmcnt(1)
	v_mfma_f32_16x16x32_bf16 v[34:37], v[2:5], v[188:191], v[196:199]
	s_waitcnt lgkmcnt(0)
	v_mfma_f32_16x16x32_bf16 v[42:45], v[6:9], v[200:203], v[34:37]
	v_mfma_f32_16x16x32_bf16 v[34:37], v[180:183], v[188:191], v[98:101]
	v_mfma_f32_16x16x32_bf16 v[34:37], v[184:187], v[200:203], v[34:37]
	s_setprio 0
	s_barrier
	ds_read_b128 v[130:133], v151 offset:49152
	ds_read_b128 v[160:163], v151 offset:50176
	ds_read_b128 v[196:199], v151 offset:51200
	ds_read_b128 v[148:151], v151 offset:52224
	s_waitcnt vmcnt(0)
	s_barrier
	s_waitcnt lgkmcnt(0)
	s_setprio 1
	s_waitcnt lgkmcnt(3)
	v_mfma_f32_16x16x32_bf16 v[98:101], v[130:133], v[18:21], v[222:225]
	s_waitcnt lgkmcnt(1)
	v_mfma_f32_16x16x32_bf16 v[18:21], v[196:199], v[18:21], v[90:93]
	s_waitcnt lgkmcnt(0)
	v_mfma_f32_16x16x32_bf16 v[122:125], v[148:151], v[22:25], v[18:21]
	v_mfma_f32_16x16x32_bf16 v[18:21], v[130:133], v[38:41], v[86:89]
	v_mfma_f32_16x16x32_bf16 v[114:117], v[160:163], v[46:49], v[18:21]
	v_mfma_f32_16x16x32_bf16 v[18:21], v[196:199], v[38:41], v[82:85]
	v_mfma_f32_16x16x32_bf16 v[106:109], v[148:151], v[46:49], v[18:21]
	v_mfma_f32_16x16x32_bf16 v[18:21], v[130:133], v[58:61], v[78:81]
	v_mfma_f32_16x16x32_bf16 v[126:129], v[160:163], v[22:25], v[98:101]
	v_mfma_f32_16x16x32_bf16 v[98:101], v[160:163], v[66:69], v[18:21]
	v_mfma_f32_16x16x32_bf16 v[18:21], v[196:199], v[58:61], v[164:167]
	v_mfma_f32_16x16x32_bf16 v[90:93], v[148:151], v[66:69], v[18:21]
	v_mfma_f32_16x16x32_bf16 v[18:21], v[130:133], v[188:191], v[70:73]
	v_mfma_f32_16x16x32_bf16 v[66:69], v[160:163], v[200:203], v[18:21]
	v_mfma_f32_16x16x32_bf16 v[18:21], v[196:199], v[188:191], v[168:171]
	v_mfma_f32_16x16x32_bf16 v[58:61], v[148:151], v[200:203], v[18:21]
	s_setprio 0
	s_barrier
	ds_read_b128 v[82:85], v0 offset:49152
	ds_read_b128 v[164:167], v0 offset:50176
	ds_read_b128 v[168:171], v0 offset:51200
	ds_read_b128 v[188:191], v0 offset:52224
	ds_read_b128 v[200:203], v0 offset:53248
	ds_read_b128 v[222:225], v0 offset:54272
	ds_read_b128 v[244:247], v0 offset:55296
	ds_read_b128 v[248:251], v0 offset:56320
	s_barrier
	s_waitcnt lgkmcnt(0)
	s_setprio 1
	s_waitcnt lgkmcnt(7)
	v_mfma_f32_16x16x32_bf16 v[18:21], v[2:5], v[82:85], v[192:195]
	s_waitcnt lgkmcnt(6)
	v_mfma_f32_16x16x32_bf16 v[78:81], v[6:9], v[164:167], v[18:21]
	v_mfma_f32_16x16x32_bf16 v[18:21], v[180:183], v[82:85], v[232:235]
	v_mfma_f32_16x16x32_bf16 v[70:73], v[184:187], v[164:167], v[18:21]
	s_waitcnt lgkmcnt(5)
	v_mfma_f32_16x16x32_bf16 v[18:21], v[2:5], v[168:171], v[54:57]
	s_waitcnt lgkmcnt(4)
	v_mfma_f32_16x16x32_bf16 v[46:49], v[6:9], v[188:191], v[18:21]
	v_mfma_f32_16x16x32_bf16 v[18:21], v[180:183], v[168:171], v[50:53]
	v_mfma_f32_16x16x32_bf16 v[38:41], v[184:187], v[188:191], v[18:21]
	s_waitcnt lgkmcnt(3)
	v_mfma_f32_16x16x32_bf16 v[18:21], v[2:5], v[200:203], v[236:239]
	s_waitcnt lgkmcnt(1)
	v_mfma_f32_16x16x32_bf16 v[2:5], v[2:5], v[244:247], v[134:137]
	v_mfma_f32_16x16x32_bf16 v[22:25], v[6:9], v[222:225], v[18:21]
	v_mfma_f32_16x16x32_bf16 v[18:21], v[180:183], v[200:203], v[240:243]
	s_waitcnt lgkmcnt(0)
	v_mfma_f32_16x16x32_bf16 v[6:9], v[6:9], v[248:251], v[2:5]
	v_mfma_f32_16x16x32_bf16 v[2:5], v[180:183], v[244:247], v[138:141]
	v_mfma_f32_16x16x32_bf16 v[18:21], v[184:187], v[222:225], v[18:21]
	v_mfma_f32_16x16x32_bf16 v[2:5], v[184:187], v[248:251], v[2:5]
	s_setprio 0
	s_setprio 1
	v_mfma_f32_16x16x32_bf16 v[26:29], v[196:199], v[82:85], v[26:29]
	v_mfma_f32_16x16x32_bf16 v[30:33], v[130:133], v[82:85], v[30:33]
	v_mfma_f32_16x16x32_bf16 v[82:85], v[148:151], v[164:167], v[26:29]
	v_mfma_f32_16x16x32_bf16 v[26:29], v[130:133], v[168:171], v[152:155]
	v_mfma_f32_16x16x32_bf16 v[54:57], v[160:163], v[188:191], v[26:29]
	v_mfma_f32_16x16x32_bf16 v[26:29], v[196:199], v[168:171], v[156:159]
	v_mfma_f32_16x16x32_bf16 v[10:13], v[196:199], v[200:203], v[10:13]
	v_mfma_f32_16x16x32_bf16 v[50:53], v[148:151], v[188:191], v[26:29]
	v_mfma_f32_16x16x32_bf16 v[14:17], v[130:133], v[200:203], v[14:17]
	v_mfma_f32_16x16x32_bf16 v[26:29], v[148:151], v[222:225], v[10:13]
	v_mfma_f32_16x16x32_bf16 v[10:13], v[130:133], v[244:247], v[172:175]
	v_mfma_f32_16x16x32_bf16 v[86:89], v[160:163], v[164:167], v[30:33]
	v_mfma_f32_16x16x32_bf16 v[30:33], v[160:163], v[222:225], v[14:17]
	v_mfma_f32_16x16x32_bf16 v[14:17], v[160:163], v[248:251], v[10:13]
	v_mfma_f32_16x16x32_bf16 v[10:13], v[196:199], v[244:247], v[176:179]
	v_mfma_f32_16x16x32_bf16 v[10:13], v[148:151], v[248:251], v[10:13]
	s_setprio 0
	s_movk_i32 s0, 0x100
	v_cmp_gt_u32_e32 vcc, s0, v142
	s_barrier
	s_and_saveexec_b64 s[0:1], vcc
	s_cbranch_execz .LBB0_81
	s_barrier
	s_branch .LBB0_81

.LBB0_108:
	ds_read_b128 v[104:107], v99
	ds_read_b128 v[108:111], v99 offset:1024
	ds_read_b128 v[112:115], v99 offset:2048
	ds_read_b128 v[116:119], v99 offset:3072
	v_add_u32_e32 v102, 0xc000, v87
	v_lshl_add_u64 v[152:153], v[74:75], 0, s[10:11]
	v_lshl_add_u64 v[154:155], v[152:153], 0, s[60:61]
	s_add_i32 m0, s1, 0xc000
	v_add_u32_e32 v103, 0xe000, v87
	ds_read_b128 v[120:123], v0
	ds_read_b128 v[124:127], v0 offset:1024
	ds_read_b128 v[128:131], v0 offset:2048
	ds_read_b128 v[132:135], v0 offset:3072
	ds_read_b128 v[136:139], v0 offset:4096
	ds_read_b128 v[140:143], v0 offset:5120
	ds_read_b128 v[144:147], v0 offset:6144
	ds_read_b128 v[148:151], v0 offset:7168
	global_load_lds_dwordx4 v[154:155], off
	v_lshl_add_u64 v[154:155], v[76:77], 0, s[10:11]
	v_lshl_add_u64 v[156:157], v[154:155], 0, s[60:61]
	s_add_i32 m0, s1, 0xe000
	s_nop 0
	global_load_lds_dwordx4 v[156:157], off
	s_waitcnt lgkmcnt(8)
	s_barrier
	s_waitcnt lgkmcnt(0)
	s_setprio 1
	s_waitcnt lgkmcnt(0)
	v_mfma_f32_16x16x32_bf16 v[62:65], v[104:107], v[120:123], v[62:65]
	v_mfma_f32_16x16x32_bf16 v[58:61], v[112:115], v[120:123], v[58:61]
	v_mfma_f32_16x16x32_bf16 v[54:57], v[104:107], v[128:131], v[54:57]
	v_mfma_f32_16x16x32_bf16 v[50:53], v[112:115], v[128:131], v[50:53]
	v_mfma_f32_16x16x32_bf16 v[46:49], v[104:107], v[136:139], v[46:49]
	v_mfma_f32_16x16x32_bf16 v[42:45], v[112:115], v[136:139], v[42:45]
	v_mfma_f32_16x16x32_bf16 v[38:41], v[104:107], v[144:147], v[38:41]
	v_mfma_f32_16x16x32_bf16 v[34:37], v[112:115], v[144:147], v[34:37]
	v_mfma_f32_16x16x32_bf16 v[62:65], v[108:111], v[124:127], v[62:65]
	v_mfma_f32_16x16x32_bf16 v[58:61], v[116:119], v[124:127], v[58:61]
	v_mfma_f32_16x16x32_bf16 v[54:57], v[108:111], v[132:135], v[54:57]
	v_mfma_f32_16x16x32_bf16 v[50:53], v[116:119], v[132:135], v[50:53]
	v_mfma_f32_16x16x32_bf16 v[46:49], v[108:111], v[140:143], v[46:49]
	v_mfma_f32_16x16x32_bf16 v[42:45], v[116:119], v[140:143], v[42:45]
	v_mfma_f32_16x16x32_bf16 v[38:41], v[108:111], v[148:151], v[38:41]
	v_mfma_f32_16x16x32_bf16 v[34:37], v[116:119], v[148:151], v[34:37]
	s_setprio 0
	s_barrier
	v_lshl_add_u64 v[156:157], v[70:71], 0, s[10:11]
	v_lshl_add_u64 v[120:121], v[156:157], 0, s[74:75]
	s_add_i32 m0, s1, 0x10000
	v_lshl_add_u64 v[158:159], v[72:73], 0, s[10:11]
	global_load_lds_dwordx4 v[120:121], off
	v_lshl_add_u64 v[120:121], v[158:159], 0, s[74:75]
	s_add_i32 m0, s1, 0x12000
	s_nop 0
	global_load_lds_dwordx4 v[120:121], off
	v_lshl_add_u64 v[160:161], v[152:153], 0, s[74:75]
	s_mov_b32 m0, s1
	s_barrier
	s_waitcnt lgkmcnt(0)
	s_barrier
	ds_read_b128 v[120:123], v0 offset:16384
	ds_read_b128 v[124:127], v0 offset:17408
	ds_read_b128 v[128:131], v0 offset:18432
	ds_read_b128 v[132:135], v0 offset:19456
	ds_read_b128 v[136:139], v0 offset:20480
	ds_read_b128 v[140:143], v0 offset:21504
	ds_read_b128 v[144:147], v0 offset:22528
	ds_read_b128 v[148:151], v0 offset:23552
	global_load_lds_dwordx4 v[160:161], off
	v_lshl_add_u64 v[160:161], v[154:155], 0, s[74:75]
	s_add_i32 m0, s1, 0x2000
	s_nop 0
	global_load_lds_dwordx4 v[160:161], off
	s_barrier
	s_waitcnt lgkmcnt(0)
	s_setprio 1
	s_waitcnt lgkmcnt(0)
	v_mfma_f32_16x16x32_bf16 v[2:5], v[104:107], v[120:123], v[2:5]
	v_mfma_f32_16x16x32_bf16 v[6:9], v[112:115], v[120:123], v[6:9]
	v_mfma_f32_16x16x32_bf16 v[10:13], v[104:107], v[128:131], v[10:13]
	v_mfma_f32_16x16x32_bf16 v[14:17], v[112:115], v[128:131], v[14:17]
	v_mfma_f32_16x16x32_bf16 v[18:21], v[104:107], v[136:139], v[18:21]
	v_mfma_f32_16x16x32_bf16 v[22:25], v[112:115], v[136:139], v[22:25]
	v_mfma_f32_16x16x32_bf16 v[26:29], v[104:107], v[144:147], v[26:29]
	v_mfma_f32_16x16x32_bf16 v[30:33], v[112:115], v[144:147], v[30:33]
	v_mfma_f32_16x16x32_bf16 v[2:5], v[108:111], v[124:127], v[2:5]
	v_mfma_f32_16x16x32_bf16 v[6:9], v[116:119], v[124:127], v[6:9]
	v_mfma_f32_16x16x32_bf16 v[10:13], v[108:111], v[132:135], v[10:13]
	v_mfma_f32_16x16x32_bf16 v[14:17], v[116:119], v[132:135], v[14:17]
	v_mfma_f32_16x16x32_bf16 v[18:21], v[108:111], v[140:143], v[18:21]
	v_mfma_f32_16x16x32_bf16 v[22:25], v[116:119], v[140:143], v[22:25]
	v_mfma_f32_16x16x32_bf16 v[26:29], v[108:111], v[148:151], v[26:29]
	v_mfma_f32_16x16x32_bf16 v[30:33], v[116:119], v[148:151], v[30:33]
	s_setprio 0
	s_barrier
	v_lshl_add_u64 v[160:161], v[78:79], 0, s[10:11]
	v_lshl_add_u64 v[104:105], v[160:161], 0, s[74:75]
	s_add_i32 m0, s1, 0x14000
	v_lshl_add_u64 v[162:163], v[80:81], 0, s[10:11]
	global_load_lds_dwordx4 v[104:105], off
	v_lshl_add_u64 v[104:105], v[162:163], 0, s[74:75]
	s_add_i32 m0, s1, 0x16000
	s_nop 0
	global_load_lds_dwordx4 v[104:105], off
	s_waitcnt vmcnt(6)
	s_barrier
	s_barrier
	ds_read_b128 v[104:107], v99 offset:32768
	ds_read_b128 v[108:111], v99 offset:33792
	ds_read_b128 v[112:115], v99 offset:34816
	ds_read_b128 v[116:119], v99 offset:35840
	v_lshl_add_u64 v[164:165], v[152:153], 0, s[18:19]
	s_add_i32 m0, s1, 0x4000
	ds_read_b128 v[120:123], v0 offset:32768
	ds_read_b128 v[124:127], v0 offset:33792
	ds_read_b128 v[128:131], v0 offset:34816
	ds_read_b128 v[132:135], v0 offset:35840
	ds_read_b128 v[136:139], v0 offset:36864
	ds_read_b128 v[140:143], v0 offset:37888
	ds_read_b128 v[144:147], v0 offset:38912
	ds_read_b128 v[148:151], v0 offset:39936
	global_load_lds_dwordx4 v[164:165], off
	v_lshl_add_u64 v[164:165], v[154:155], 0, s[18:19]
	s_add_i32 m0, s1, 0x6000
	s_nop 0
	global_load_lds_dwordx4 v[164:165], off
	s_waitcnt lgkmcnt(8)
	s_barrier
	s_waitcnt lgkmcnt(0)
	s_setprio 1
	s_waitcnt lgkmcnt(0)
	v_mfma_f32_16x16x32_bf16 v[62:65], v[104:107], v[120:123], v[62:65]
	v_mfma_f32_16x16x32_bf16 v[58:61], v[112:115], v[120:123], v[58:61]
	v_mfma_f32_16x16x32_bf16 v[54:57], v[104:107], v[128:131], v[54:57]
	v_mfma_f32_16x16x32_bf16 v[50:53], v[112:115], v[128:131], v[50:53]
	v_mfma_f32_16x16x32_bf16 v[46:49], v[104:107], v[136:139], v[46:49]
	v_mfma_f32_16x16x32_bf16 v[42:45], v[112:115], v[136:139], v[42:45]
	v_mfma_f32_16x16x32_bf16 v[38:41], v[104:107], v[144:147], v[38:41]
	v_mfma_f32_16x16x32_bf16 v[34:37], v[112:115], v[144:147], v[34:37]
	v_mfma_f32_16x16x32_bf16 v[62:65], v[108:111], v[124:127], v[62:65]
	v_mfma_f32_16x16x32_bf16 v[58:61], v[116:119], v[124:127], v[58:61]
	v_mfma_f32_16x16x32_bf16 v[54:57], v[108:111], v[132:135], v[54:57]
	v_mfma_f32_16x16x32_bf16 v[50:53], v[116:119], v[132:135], v[50:53]
	v_mfma_f32_16x16x32_bf16 v[46:49], v[108:111], v[140:143], v[46:49]
	v_mfma_f32_16x16x32_bf16 v[42:45], v[116:119], v[140:143], v[42:45]
	v_mfma_f32_16x16x32_bf16 v[38:41], v[108:111], v[148:151], v[38:41]
	v_mfma_f32_16x16x32_bf16 v[34:37], v[116:119], v[148:151], v[34:37]
	s_setprio 0
	s_barrier
	v_lshl_add_u64 v[120:121], v[156:157], 0, s[28:29]
	s_add_i32 m0, s1, 0x18000
	s_nop 0
	global_load_lds_dwordx4 v[120:121], off
	v_lshl_add_u64 v[120:121], v[158:159], 0, s[28:29]
	s_add_i32 m0, s1, 0x1a000
	s_nop 0
	global_load_lds_dwordx4 v[120:121], off
	v_lshl_add_u64 v[152:153], v[152:153], 0, s[28:29]
	s_add_i32 m0, s1, 0x8000
	s_barrier
	s_waitcnt lgkmcnt(0)
	s_barrier
	ds_read_b128 v[120:123], v0 offset:49152
	ds_read_b128 v[124:127], v0 offset:50176
	ds_read_b128 v[128:131], v0 offset:51200
	ds_read_b128 v[132:135], v0 offset:52224
	ds_read_b128 v[136:139], v0 offset:53248
	ds_read_b128 v[140:143], v0 offset:54272
	ds_read_b128 v[144:147], v0 offset:55296
	ds_read_b128 v[148:151], v0 offset:56320
	global_load_lds_dwordx4 v[152:153], off
	v_lshl_add_u64 v[152:153], v[154:155], 0, s[28:29]
	s_add_i32 m0, s1, 0xa000
	s_nop 0
	global_load_lds_dwordx4 v[152:153], off
	s_barrier
	s_waitcnt lgkmcnt(0)
	s_setprio 1
	s_waitcnt lgkmcnt(0)
	v_mfma_f32_16x16x32_bf16 v[2:5], v[104:107], v[120:123], v[2:5]
	v_mfma_f32_16x16x32_bf16 v[6:9], v[112:115], v[120:123], v[6:9]
	v_mfma_f32_16x16x32_bf16 v[10:13], v[104:107], v[128:131], v[10:13]
	v_mfma_f32_16x16x32_bf16 v[14:17], v[112:115], v[128:131], v[14:17]
	v_mfma_f32_16x16x32_bf16 v[18:21], v[104:107], v[136:139], v[18:21]
	v_mfma_f32_16x16x32_bf16 v[22:25], v[112:115], v[136:139], v[22:25]
	v_mfma_f32_16x16x32_bf16 v[26:29], v[104:107], v[144:147], v[26:29]
	v_mfma_f32_16x16x32_bf16 v[30:33], v[112:115], v[144:147], v[30:33]
	v_mfma_f32_16x16x32_bf16 v[2:5], v[108:111], v[124:127], v[2:5]
	v_mfma_f32_16x16x32_bf16 v[6:9], v[116:119], v[124:127], v[6:9]
	v_mfma_f32_16x16x32_bf16 v[10:13], v[108:111], v[132:135], v[10:13]
	v_mfma_f32_16x16x32_bf16 v[14:17], v[116:119], v[132:135], v[14:17]
	v_mfma_f32_16x16x32_bf16 v[18:21], v[108:111], v[140:143], v[18:21]
	v_mfma_f32_16x16x32_bf16 v[22:25], v[116:119], v[140:143], v[22:25]
	v_mfma_f32_16x16x32_bf16 v[26:29], v[108:111], v[148:151], v[26:29]
	v_mfma_f32_16x16x32_bf16 v[30:33], v[116:119], v[148:151], v[30:33]
	s_setprio 0
	s_barrier
	v_lshl_add_u64 v[104:105], v[160:161], 0, s[28:29]
	s_add_i32 m0, s1, 0x1c000
	s_nop 0
	global_load_lds_dwordx4 v[104:105], off
	v_lshl_add_u64 v[104:105], v[162:163], 0, s[28:29]
	s_add_i32 m0, s1, 0x1e000
	s_add_i32 s0, s0, 2
	global_load_lds_dwordx4 v[104:105], off
	s_waitcnt vmcnt(6)
	s_add_u32 s10, s10, 0x100
	s_addc_u32 s11, s11, 0
	s_cmp_lt_u32 s0, 28
	s_barrier
	s_barrier
	s_cbranch_scc1 .LBB0_108
	s_add_i32 s1, s1, 0x1e000
	s_mov_b64 s[10:11], 0xf80
	v_readfirstlane_b32 s0, v102
	v_lshl_add_u64 v[68:69], v[68:69], 0, s[10:11]
	s_mov_b32 m0, s0
	v_readfirstlane_b32 s0, v103
	ds_read_b128 v[70:73], v99
	ds_read_b128 v[74:77], v99 offset:1024
	ds_read_b128 v[78:81], v99 offset:2048
	ds_read_b128 v[88:91], v99 offset:3072
	ds_read_b128 v[92:95], v0
	ds_read_b128 v[104:107], v0 offset:1024
	ds_read_b128 v[108:111], v0 offset:2048
	ds_read_b128 v[112:115], v0 offset:3072
	ds_read_b128 v[116:119], v0 offset:4096
	ds_read_b128 v[120:123], v0 offset:5120
	ds_read_b128 v[124:127], v0 offset:6144
	ds_read_b128 v[128:131], v0 offset:7168
	global_load_lds_dwordx4 v[68:69], off
	v_lshl_add_u64 v[66:67], v[66:67], 0, s[10:11]
	s_mov_b32 m0, s0
	s_nop 0
	global_load_lds_dwordx4 v[66:67], off
	s_barrier
	s_waitcnt lgkmcnt(0)
	s_setprio 1
	s_waitcnt lgkmcnt(0)
	v_mfma_f32_16x16x32_bf16 v[62:65], v[70:73], v[92:95], v[62:65]
	v_mfma_f32_16x16x32_bf16 v[58:61], v[78:81], v[92:95], v[58:61]
	v_mfma_f32_16x16x32_bf16 v[54:57], v[70:73], v[108:111], v[54:57]
	v_mfma_f32_16x16x32_bf16 v[50:53], v[78:81], v[108:111], v[50:53]
	v_mfma_f32_16x16x32_bf16 v[46:49], v[70:73], v[116:119], v[46:49]
	v_mfma_f32_16x16x32_bf16 v[42:45], v[78:81], v[116:119], v[42:45]
	v_mfma_f32_16x16x32_bf16 v[38:41], v[70:73], v[124:127], v[38:41]
	v_mfma_f32_16x16x32_bf16 v[34:37], v[78:81], v[124:127], v[34:37]
	v_mfma_f32_16x16x32_bf16 v[62:65], v[74:77], v[104:107], v[62:65]
	v_mfma_f32_16x16x32_bf16 v[58:61], v[88:91], v[104:107], v[58:61]
	v_mfma_f32_16x16x32_bf16 v[54:57], v[74:77], v[112:115], v[54:57]
	v_mfma_f32_16x16x32_bf16 v[50:53], v[88:91], v[112:115], v[50:53]
	v_mfma_f32_16x16x32_bf16 v[46:49], v[74:77], v[120:123], v[46:49]
	v_mfma_f32_16x16x32_bf16 v[42:45], v[88:91], v[120:123], v[42:45]
	v_mfma_f32_16x16x32_bf16 v[38:41], v[74:77], v[128:131], v[38:41]
	v_mfma_f32_16x16x32_bf16 v[34:37], v[88:91], v[128:131], v[34:37]
	s_setprio 0
	s_barrier
	s_barrier
	s_waitcnt lgkmcnt(0)
	s_barrier
	ds_read_b128 v[66:69], v0 offset:16384
	ds_read_b128 v[92:95], v0 offset:17408
	ds_read_b128 v[100:103], v0 offset:18432
	ds_read_b128 v[104:107], v0 offset:19456
	ds_read_b128 v[108:111], v0 offset:20480
	ds_read_b128 v[112:115], v0 offset:21504
	ds_read_b128 v[116:119], v0 offset:22528
	ds_read_b128 v[120:123], v0 offset:23552
	s_waitcnt vmcnt(4)
	s_barrier
	s_waitcnt lgkmcnt(0)
	s_setprio 1
	s_waitcnt lgkmcnt(3)
	v_mfma_f32_16x16x32_bf16 v[18:21], v[70:73], v[108:111], v[18:21]
	v_mfma_f32_16x16x32_bf16 v[2:5], v[70:73], v[66:69], v[2:5]
	v_mfma_f32_16x16x32_bf16 v[6:9], v[78:81], v[66:69], v[6:9]
	s_waitcnt lgkmcnt(2)
	v_mfma_f32_16x16x32_bf16 v[66:69], v[74:77], v[112:115], v[18:21]
	v_mfma_f32_16x16x32_bf16 v[18:21], v[78:81], v[108:111], v[22:25]
	v_mfma_f32_16x16x32_bf16 v[2:5], v[74:77], v[92:95], v[2:5]
	v_mfma_f32_16x16x32_bf16 v[6:9], v[88:91], v[92:95], v[6:9]
	v_mfma_f32_16x16x32_bf16 v[10:13], v[70:73], v[100:103], v[10:13]
	v_mfma_f32_16x16x32_bf16 v[14:17], v[78:81], v[100:103], v[14:17]
	v_mfma_f32_16x16x32_bf16 v[92:95], v[88:91], v[112:115], v[18:21]
	s_waitcnt lgkmcnt(1)
	v_mfma_f32_16x16x32_bf16 v[18:21], v[70:73], v[116:119], v[26:29]
	v_mfma_f32_16x16x32_bf16 v[10:13], v[74:77], v[104:107], v[10:13]
	v_mfma_f32_16x16x32_bf16 v[14:17], v[88:91], v[104:107], v[14:17]
	s_waitcnt lgkmcnt(0)
	v_mfma_f32_16x16x32_bf16 v[70:73], v[74:77], v[120:123], v[18:21]
	v_mfma_f32_16x16x32_bf16 v[18:21], v[78:81], v[116:119], v[30:33]
	v_mfma_f32_16x16x32_bf16 v[74:77], v[88:91], v[120:123], v[18:21]
	s_setprio 0
	s_barrier
	ds_read_b128 v[78:81], v99 offset:32768
	ds_read_b128 v[88:91], v99 offset:33792
	ds_read_b128 v[100:103], v99 offset:34816
	ds_read_b128 v[96:99], v99 offset:35840
	s_nop 0
	ds_read_b128 v[18:21], v0 offset:32768
	ds_read_b128 v[22:25], v0 offset:33792
	ds_read_b128 v[26:29], v0 offset:34816
	ds_read_b128 v[30:33], v0 offset:35840
	ds_read_b128 v[104:107], v0 offset:36864
	ds_read_b128 v[108:111], v0 offset:37888
	ds_read_b128 v[112:115], v0 offset:38912
	ds_read_b128 v[116:119], v0 offset:39936
	s_waitcnt vmcnt(2)
	s_barrier
	s_waitcnt lgkmcnt(0)
	s_setprio 1
	s_waitcnt lgkmcnt(7)
	v_mfma_f32_16x16x32_bf16 v[62:65], v[78:81], v[18:21], v[62:65]
	v_mfma_f32_16x16x32_bf16 v[18:21], v[100:103], v[18:21], v[58:61]
	s_waitcnt lgkmcnt(6)
	v_mfma_f32_16x16x32_bf16 v[58:61], v[96:99], v[22:25], v[18:21]
	s_waitcnt lgkmcnt(5)
	v_mfma_f32_16x16x32_bf16 v[18:21], v[78:81], v[26:29], v[54:57]
	s_waitcnt lgkmcnt(4)
	v_mfma_f32_16x16x32_bf16 v[54:57], v[88:91], v[30:33], v[18:21]
	v_mfma_f32_16x16x32_bf16 v[18:21], v[100:103], v[26:29], v[50:53]
	v_mfma_f32_16x16x32_bf16 v[50:53], v[96:99], v[30:33], v[18:21]
	s_waitcnt lgkmcnt(3)
	v_mfma_f32_16x16x32_bf16 v[18:21], v[78:81], v[104:107], v[46:49]
	s_waitcnt lgkmcnt(2)
	v_mfma_f32_16x16x32_bf16 v[46:49], v[88:91], v[108:111], v[18:21]
	v_mfma_f32_16x16x32_bf16 v[18:21], v[100:103], v[104:107], v[42:45]
	v_mfma_f32_16x16x32_bf16 v[42:45], v[96:99], v[108:111], v[18:21]
	s_waitcnt lgkmcnt(1)
	v_mfma_f32_16x16x32_bf16 v[18:21], v[78:81], v[112:115], v[38:41]
	s_waitcnt lgkmcnt(0)
	v_mfma_f32_16x16x32_bf16 v[38:41], v[88:91], v[116:119], v[18:21]
	v_mfma_f32_16x16x32_bf16 v[18:21], v[100:103], v[112:115], v[34:37]
	v_mfma_f32_16x16x32_bf16 v[62:65], v[88:91], v[22:25], v[62:65]
	v_mfma_f32_16x16x32_bf16 v[34:37], v[96:99], v[116:119], v[18:21]
	s_setprio 0
	s_barrier
	s_waitcnt vmcnt(0)
	s_barrier
	s_waitcnt lgkmcnt(0)
	s_barrier
	s_nop 1
	ds_read_b128 v[18:21], v0 offset:49152
	ds_read_b128 v[22:25], v0 offset:50176
	ds_read_b128 v[104:107], v0 offset:51200
	ds_read_b128 v[108:111], v0 offset:52224
	ds_read_b128 v[112:115], v0 offset:53248
	ds_read_b128 v[116:119], v0 offset:54272
	ds_read_b128 v[120:123], v0 offset:55296
	ds_read_b128 v[124:127], v0 offset:56320
	s_barrier
	s_waitcnt lgkmcnt(0)
	s_setprio 1
	s_waitcnt lgkmcnt(7)
	v_mfma_f32_16x16x32_bf16 v[2:5], v[78:81], v[18:21], v[2:5]
	s_waitcnt lgkmcnt(6)
	v_mfma_f32_16x16x32_bf16 v[30:33], v[88:91], v[22:25], v[2:5]
	v_mfma_f32_16x16x32_bf16 v[2:5], v[100:103], v[18:21], v[6:9]
	v_mfma_f32_16x16x32_bf16 v[26:29], v[96:99], v[22:25], v[2:5]
	s_waitcnt lgkmcnt(5)
	v_mfma_f32_16x16x32_bf16 v[2:5], v[78:81], v[104:107], v[10:13]
	s_waitcnt lgkmcnt(4)
	v_mfma_f32_16x16x32_bf16 v[22:25], v[88:91], v[108:111], v[2:5]
	v_mfma_f32_16x16x32_bf16 v[2:5], v[100:103], v[104:107], v[14:17]
	v_mfma_f32_16x16x32_bf16 v[18:21], v[96:99], v[108:111], v[2:5]
	s_waitcnt lgkmcnt(3)
	v_mfma_f32_16x16x32_bf16 v[2:5], v[78:81], v[112:115], v[66:69]
	s_waitcnt lgkmcnt(2)
	v_mfma_f32_16x16x32_bf16 v[14:17], v[88:91], v[116:119], v[2:5]
	v_mfma_f32_16x16x32_bf16 v[2:5], v[100:103], v[112:115], v[92:95]
	v_mfma_f32_16x16x32_bf16 v[10:13], v[96:99], v[116:119], v[2:5]
	s_waitcnt lgkmcnt(1)
	v_mfma_f32_16x16x32_bf16 v[2:5], v[78:81], v[120:123], v[70:73]
	s_waitcnt lgkmcnt(0)
	v_mfma_f32_16x16x32_bf16 v[6:9], v[88:91], v[124:127], v[2:5]
	v_mfma_f32_16x16x32_bf16 v[2:5], v[100:103], v[120:123], v[74:77]
	v_mfma_f32_16x16x32_bf16 v[2:5], v[96:99], v[124:127], v[2:5]
	s_setprio 0
	s_movk_i32 s0, 0x100
	v_cmp_gt_u32_e32 vcc, s0, v82
	s_barrier
	s_and_saveexec_b64 s[0:1], vcc
	s_cbranch_execz .LBB0_111
	s_barrier

.LBB0_180:
	ds_read_b128 v[164:167], v151
	ds_read_b128 v[168:171], v151 offset:1024
	ds_read_b128 v[172:175], v151 offset:2048
	ds_read_b128 v[176:179], v151 offset:3072
	v_add_u32_e32 v162, 0xc000, v147
	v_lshl_add_u64 v[204:205], v[138:139], 0, s[12:13]
	v_lshl_add_u64 v[228:229], v[204:205], 0, s[60:61]
	s_add_i32 m0, s1, 0xc000
	v_add_u32_e32 v163, 0xe000, v147
	ds_read_b128 v[180:183], v0
	ds_read_b128 v[184:187], v0 offset:1024
	ds_read_b128 v[188:191], v0 offset:2048
	ds_read_b128 v[192:195], v0 offset:3072
	ds_read_b128 v[196:199], v0 offset:4096
	ds_read_b128 v[200:203], v0 offset:5120
	ds_read_b128 v[222:225], v0 offset:6144
	ds_read_b128 v[232:235], v0 offset:7168
	global_load_lds_dwordx4 v[228:229], off
	v_lshl_add_u64 v[210:211], v[140:141], 0, s[12:13]
	v_lshl_add_u64 v[152:153], v[210:211], 0, s[60:61]
	s_add_i32 m0, s1, 0xe000
	s_nop 0
	global_load_lds_dwordx4 v[152:153], off
	s_waitcnt lgkmcnt(8)
	s_barrier
	s_waitcnt lgkmcnt(0)
	s_setprio 1
	s_waitcnt lgkmcnt(0)
	v_mfma_f32_16x16x32_bf16 v[126:129], v[164:167], v[180:183], v[126:129]
	v_mfma_f32_16x16x32_bf16 v[122:125], v[172:175], v[180:183], v[122:125]
	v_mfma_f32_16x16x32_bf16 v[118:121], v[164:167], v[188:191], v[118:121]
	v_mfma_f32_16x16x32_bf16 v[114:117], v[172:175], v[188:191], v[114:117]
	v_mfma_f32_16x16x32_bf16 v[110:113], v[164:167], v[196:199], v[110:113]
	v_mfma_f32_16x16x32_bf16 v[106:109], v[172:175], v[196:199], v[106:109]
	v_mfma_f32_16x16x32_bf16 v[102:105], v[164:167], v[222:225], v[102:105]
	v_mfma_f32_16x16x32_bf16 v[98:101], v[172:175], v[222:225], v[98:101]
	v_mfma_f32_16x16x32_bf16 v[126:129], v[168:171], v[184:187], v[126:129]
	v_mfma_f32_16x16x32_bf16 v[122:125], v[176:179], v[184:187], v[122:125]
	v_mfma_f32_16x16x32_bf16 v[118:121], v[168:171], v[192:195], v[118:121]
	v_mfma_f32_16x16x32_bf16 v[114:117], v[176:179], v[192:195], v[114:117]
	v_mfma_f32_16x16x32_bf16 v[110:113], v[168:171], v[200:203], v[110:113]
	v_mfma_f32_16x16x32_bf16 v[106:109], v[176:179], v[200:203], v[106:109]
	v_mfma_f32_16x16x32_bf16 v[102:105], v[168:171], v[232:235], v[102:105]
	v_mfma_f32_16x16x32_bf16 v[98:101], v[176:179], v[232:235], v[98:101]
	s_setprio 0
	s_barrier
	v_lshl_add_u64 v[216:217], v[134:135], 0, s[12:13]
	s_add_i32 m0, s1, 0xff00
	ds_read_b128 v[236:239], v151 offset:16384
	ds_read_b128 v[240:243], v151 offset:17408
	ds_read_b128 v[244:247], v151 offset:18432
	ds_read_b128 v[248:251], v151 offset:19456
	global_load_lds_dwordx4 v[216:217], off offset:256
	v_lshl_add_u64 v[218:219], v[136:137], 0, s[12:13]
	s_add_i32 m0, s1, 0x11f00
	s_nop 0
	global_load_lds_dwordx4 v[218:219], off offset:256
	s_barrier
	s_waitcnt lgkmcnt(0)
	s_setprio 1
	s_waitcnt lgkmcnt(0)
	v_mfma_f32_16x16x32_bf16 v[94:97], v[236:239], v[180:183], v[94:97]
	v_mfma_f32_16x16x32_bf16 v[90:93], v[244:247], v[180:183], v[90:93]
	v_mfma_f32_16x16x32_bf16 v[86:89], v[236:239], v[188:191], v[86:89]
	v_mfma_f32_16x16x32_bf16 v[82:85], v[244:247], v[188:191], v[82:85]
	v_mfma_f32_16x16x32_bf16 v[78:81], v[236:239], v[196:199], v[78:81]
	v_mfma_f32_16x16x32_bf16 v[74:77], v[244:247], v[196:199], v[74:77]
	v_mfma_f32_16x16x32_bf16 v[70:73], v[236:239], v[222:225], v[70:73]
	v_mfma_f32_16x16x32_bf16 v[66:69], v[244:247], v[222:225], v[66:69]
	v_mfma_f32_16x16x32_bf16 v[94:97], v[240:243], v[184:187], v[94:97]
	v_mfma_f32_16x16x32_bf16 v[90:93], v[248:251], v[184:187], v[90:93]
	v_mfma_f32_16x16x32_bf16 v[86:89], v[240:243], v[192:195], v[86:89]
	v_mfma_f32_16x16x32_bf16 v[82:85], v[248:251], v[192:195], v[82:85]
	v_mfma_f32_16x16x32_bf16 v[78:81], v[240:243], v[200:203], v[78:81]
	v_mfma_f32_16x16x32_bf16 v[74:77], v[248:251], v[200:203], v[74:77]
	v_mfma_f32_16x16x32_bf16 v[70:73], v[240:243], v[232:235], v[70:73]
	v_mfma_f32_16x16x32_bf16 v[66:69], v[248:251], v[232:235], v[66:69]
	s_setprio 0
	v_lshl_add_u64 v[158:159], v[204:205], 0, s[74:75]
	s_mov_b32 m0, s1
	s_barrier
	ds_read_b128 v[180:183], v0 offset:16384
	ds_read_b128 v[184:187], v0 offset:17408
	ds_read_b128 v[188:191], v0 offset:18432
	ds_read_b128 v[192:195], v0 offset:19456
	ds_read_b128 v[196:199], v0 offset:20480
	ds_read_b128 v[200:203], v0 offset:21504
	ds_read_b128 v[222:225], v0 offset:22528
	ds_read_b128 v[232:235], v0 offset:23552
	global_load_lds_dwordx4 v[158:159], off
	s_add_i32 m0, s1, 0x1f00
	s_nop 0
	global_load_lds_dwordx4 v[210:211], off offset:256
	s_barrier
	s_waitcnt lgkmcnt(0)
	s_setprio 1
	s_waitcnt lgkmcnt(0)
	v_mfma_f32_16x16x32_bf16 v[62:65], v[164:167], v[180:183], v[62:65]
	v_mfma_f32_16x16x32_bf16 v[58:61], v[172:175], v[180:183], v[58:61]
	v_mfma_f32_16x16x32_bf16 v[54:57], v[164:167], v[188:191], v[54:57]
	v_mfma_f32_16x16x32_bf16 v[50:53], v[172:175], v[188:191], v[50:53]
	v_mfma_f32_16x16x32_bf16 v[46:49], v[164:167], v[196:199], v[46:49]
	v_mfma_f32_16x16x32_bf16 v[42:45], v[172:175], v[196:199], v[42:45]
	v_mfma_f32_16x16x32_bf16 v[38:41], v[164:167], v[222:225], v[38:41]
	v_mfma_f32_16x16x32_bf16 v[34:37], v[172:175], v[222:225], v[34:37]
	v_mfma_f32_16x16x32_bf16 v[62:65], v[168:171], v[184:187], v[62:65]
	v_mfma_f32_16x16x32_bf16 v[58:61], v[176:179], v[184:187], v[58:61]
	v_mfma_f32_16x16x32_bf16 v[54:57], v[168:171], v[192:195], v[54:57]
	v_mfma_f32_16x16x32_bf16 v[50:53], v[176:179], v[192:195], v[50:53]
	v_mfma_f32_16x16x32_bf16 v[46:49], v[168:171], v[200:203], v[46:49]
	v_mfma_f32_16x16x32_bf16 v[42:45], v[176:179], v[200:203], v[42:45]
	v_mfma_f32_16x16x32_bf16 v[38:41], v[168:171], v[232:235], v[38:41]
	v_mfma_f32_16x16x32_bf16 v[34:37], v[176:179], v[232:235], v[34:37]
	s_setprio 0
	s_barrier
	v_lshl_add_u64 v[154:155], v[216:217], 0, s[18:19]
	s_add_i32 m0, s1, 0x14000
	s_nop 0
	global_load_lds_dwordx4 v[154:155], off
	v_lshl_add_u64 v[156:157], v[218:219], 0, s[18:19]
	s_add_i32 m0, s1, 0x16000
	s_nop 0
	global_load_lds_dwordx4 v[156:157], off
	s_waitcnt vmcnt(6)
	s_barrier
	s_setprio 1
	v_mfma_f32_16x16x32_bf16 v[30:33], v[236:239], v[180:183], v[30:33]
	v_mfma_f32_16x16x32_bf16 v[26:29], v[244:247], v[180:183], v[26:29]
	v_mfma_f32_16x16x32_bf16 v[22:25], v[236:239], v[188:191], v[22:25]
	v_mfma_f32_16x16x32_bf16 v[18:21], v[244:247], v[188:191], v[18:21]
	v_mfma_f32_16x16x32_bf16 v[14:17], v[236:239], v[196:199], v[14:17]
	v_mfma_f32_16x16x32_bf16 v[10:13], v[244:247], v[196:199], v[10:13]
	v_mfma_f32_16x16x32_bf16 v[6:9], v[236:239], v[222:225], v[6:9]
	v_mfma_f32_16x16x32_bf16 v[2:5], v[244:247], v[222:225], v[2:5]
	v_mfma_f32_16x16x32_bf16 v[30:33], v[240:243], v[184:187], v[30:33]
	v_mfma_f32_16x16x32_bf16 v[26:29], v[248:251], v[184:187], v[26:29]
	v_mfma_f32_16x16x32_bf16 v[22:25], v[240:243], v[192:195], v[22:25]
	v_mfma_f32_16x16x32_bf16 v[18:21], v[248:251], v[192:195], v[18:21]
	v_mfma_f32_16x16x32_bf16 v[14:17], v[240:243], v[200:203], v[14:17]
	v_mfma_f32_16x16x32_bf16 v[10:13], v[248:251], v[200:203], v[10:13]
	v_mfma_f32_16x16x32_bf16 v[6:9], v[240:243], v[232:235], v[6:9]
	v_mfma_f32_16x16x32_bf16 v[2:5], v[248:251], v[232:235], v[2:5]
	s_setprio 0
	s_barrier
	ds_read_b128 v[164:167], v151 offset:32768
	ds_read_b128 v[168:171], v151 offset:33792
	ds_read_b128 v[172:175], v151 offset:34816
	ds_read_b128 v[176:179], v151 offset:35840
	s_add_i32 m0, s1, 0x3f80
	ds_read_b128 v[180:183], v0 offset:32768
	ds_read_b128 v[184:187], v0 offset:33792
	ds_read_b128 v[188:191], v0 offset:34816
	ds_read_b128 v[192:195], v0 offset:35840
	ds_read_b128 v[196:199], v0 offset:36864
	ds_read_b128 v[200:203], v0 offset:37888
	ds_read_b128 v[222:225], v0 offset:38912
	ds_read_b128 v[232:235], v0 offset:39936
	global_load_lds_dwordx4 v[228:229], off offset:128
	s_add_i32 m0, s1, 0x5f80
	s_nop 0
	global_load_lds_dwordx4 v[152:153], off offset:128
	s_waitcnt lgkmcnt(8)
	s_barrier
	s_waitcnt lgkmcnt(0)
	s_setprio 1
	s_waitcnt lgkmcnt(0)
	v_mfma_f32_16x16x32_bf16 v[126:129], v[164:167], v[180:183], v[126:129]
	v_mfma_f32_16x16x32_bf16 v[122:125], v[172:175], v[180:183], v[122:125]
	v_mfma_f32_16x16x32_bf16 v[118:121], v[164:167], v[188:191], v[118:121]
	v_mfma_f32_16x16x32_bf16 v[114:117], v[172:175], v[188:191], v[114:117]
	v_mfma_f32_16x16x32_bf16 v[110:113], v[164:167], v[196:199], v[110:113]
	v_mfma_f32_16x16x32_bf16 v[106:109], v[172:175], v[196:199], v[106:109]
	v_mfma_f32_16x16x32_bf16 v[102:105], v[164:167], v[222:225], v[102:105]
	v_mfma_f32_16x16x32_bf16 v[98:101], v[172:175], v[222:225], v[98:101]
	v_mfma_f32_16x16x32_bf16 v[126:129], v[168:171], v[184:187], v[126:129]
	v_mfma_f32_16x16x32_bf16 v[122:125], v[176:179], v[184:187], v[122:125]
	v_mfma_f32_16x16x32_bf16 v[118:121], v[168:171], v[192:195], v[118:121]
	v_mfma_f32_16x16x32_bf16 v[114:117], v[176:179], v[192:195], v[114:117]
	v_mfma_f32_16x16x32_bf16 v[110:113], v[168:171], v[200:203], v[110:113]
	v_mfma_f32_16x16x32_bf16 v[106:109], v[176:179], v[200:203], v[106:109]
	v_mfma_f32_16x16x32_bf16 v[102:105], v[168:171], v[232:235], v[102:105]
	v_mfma_f32_16x16x32_bf16 v[98:101], v[176:179], v[232:235], v[98:101]
	s_setprio 0
	s_barrier
	s_add_i32 m0, s1, 0x17e80
	ds_read_b128 v[236:239], v151 offset:49152
	ds_read_b128 v[240:243], v151 offset:50176
	ds_read_b128 v[244:247], v151 offset:51200
	ds_read_b128 v[248:251], v151 offset:52224
	global_load_lds_dwordx4 v[216:217], off offset:384
	s_add_i32 m0, s1, 0x19e80
	s_nop 0
	global_load_lds_dwordx4 v[218:219], off offset:384
	s_barrier
	s_waitcnt lgkmcnt(0)
	s_setprio 1
	s_waitcnt lgkmcnt(0)
	v_mfma_f32_16x16x32_bf16 v[94:97], v[236:239], v[180:183], v[94:97]
	v_mfma_f32_16x16x32_bf16 v[90:93], v[244:247], v[180:183], v[90:93]
	v_mfma_f32_16x16x32_bf16 v[86:89], v[236:239], v[188:191], v[86:89]
	v_mfma_f32_16x16x32_bf16 v[82:85], v[244:247], v[188:191], v[82:85]
	v_mfma_f32_16x16x32_bf16 v[78:81], v[236:239], v[196:199], v[78:81]
	v_mfma_f32_16x16x32_bf16 v[74:77], v[244:247], v[196:199], v[74:77]
	v_mfma_f32_16x16x32_bf16 v[70:73], v[236:239], v[222:225], v[70:73]
	v_mfma_f32_16x16x32_bf16 v[66:69], v[244:247], v[222:225], v[66:69]
	v_mfma_f32_16x16x32_bf16 v[94:97], v[240:243], v[184:187], v[94:97]
	v_mfma_f32_16x16x32_bf16 v[90:93], v[248:251], v[184:187], v[90:93]
	v_mfma_f32_16x16x32_bf16 v[86:89], v[240:243], v[192:195], v[86:89]
	v_mfma_f32_16x16x32_bf16 v[82:85], v[248:251], v[192:195], v[82:85]
	v_mfma_f32_16x16x32_bf16 v[78:81], v[240:243], v[200:203], v[78:81]
	v_mfma_f32_16x16x32_bf16 v[74:77], v[248:251], v[200:203], v[74:77]
	v_mfma_f32_16x16x32_bf16 v[70:73], v[240:243], v[232:235], v[70:73]
	v_mfma_f32_16x16x32_bf16 v[66:69], v[248:251], v[232:235], v[66:69]
	s_setprio 0
	s_add_i32 m0, s1, 0x7e80
	s_barrier
	ds_read_b128 v[180:183], v0 offset:49152
	ds_read_b128 v[184:187], v0 offset:50176
	ds_read_b128 v[188:191], v0 offset:51200
	ds_read_b128 v[192:195], v0 offset:52224
	ds_read_b128 v[196:199], v0 offset:53248
	ds_read_b128 v[200:203], v0 offset:54272
	ds_read_b128 v[222:225], v0 offset:55296
	ds_read_b128 v[232:235], v0 offset:56320
	global_load_lds_dwordx4 v[204:205], off offset:384
	s_add_i32 m0, s1, 0x9e80
	s_nop 0
	global_load_lds_dwordx4 v[210:211], off offset:384
	s_barrier
	s_waitcnt lgkmcnt(0)
	s_setprio 1
	s_waitcnt lgkmcnt(0)
	v_mfma_f32_16x16x32_bf16 v[62:65], v[164:167], v[180:183], v[62:65]
	v_mfma_f32_16x16x32_bf16 v[58:61], v[172:175], v[180:183], v[58:61]
	v_mfma_f32_16x16x32_bf16 v[54:57], v[164:167], v[188:191], v[54:57]
	v_mfma_f32_16x16x32_bf16 v[50:53], v[172:175], v[188:191], v[50:53]
	v_mfma_f32_16x16x32_bf16 v[46:49], v[164:167], v[196:199], v[46:49]
	v_mfma_f32_16x16x32_bf16 v[42:45], v[172:175], v[196:199], v[42:45]
	v_mfma_f32_16x16x32_bf16 v[38:41], v[164:167], v[222:225], v[38:41]
	v_mfma_f32_16x16x32_bf16 v[34:37], v[172:175], v[222:225], v[34:37]
	v_mfma_f32_16x16x32_bf16 v[62:65], v[168:171], v[184:187], v[62:65]
	v_mfma_f32_16x16x32_bf16 v[58:61], v[176:179], v[184:187], v[58:61]
	v_mfma_f32_16x16x32_bf16 v[54:57], v[168:171], v[192:195], v[54:57]
	v_mfma_f32_16x16x32_bf16 v[50:53], v[176:179], v[192:195], v[50:53]
	v_mfma_f32_16x16x32_bf16 v[46:49], v[168:171], v[200:203], v[46:49]
	v_mfma_f32_16x16x32_bf16 v[42:45], v[176:179], v[200:203], v[42:45]
	v_mfma_f32_16x16x32_bf16 v[38:41], v[168:171], v[232:235], v[38:41]
	v_mfma_f32_16x16x32_bf16 v[34:37], v[176:179], v[232:235], v[34:37]
	s_setprio 0
	s_barrier
	s_add_i32 m0, s1, 0x1bf80
	s_nop 0
	global_load_lds_dwordx4 v[154:155], off offset:128
	s_add_i32 m0, s1, 0x1df80
	s_nop 0
	global_load_lds_dwordx4 v[156:157], off offset:128
	s_waitcnt vmcnt(6)
	s_barrier
	s_setprio 1
	v_mfma_f32_16x16x32_bf16 v[30:33], v[236:239], v[180:183], v[30:33]
	v_mfma_f32_16x16x32_bf16 v[26:29], v[244:247], v[180:183], v[26:29]
	v_mfma_f32_16x16x32_bf16 v[22:25], v[236:239], v[188:191], v[22:25]
	v_mfma_f32_16x16x32_bf16 v[18:21], v[244:247], v[188:191], v[18:21]
	v_mfma_f32_16x16x32_bf16 v[14:17], v[236:239], v[196:199], v[14:17]
	v_mfma_f32_16x16x32_bf16 v[10:13], v[244:247], v[196:199], v[10:13]
	v_mfma_f32_16x16x32_bf16 v[6:9], v[236:239], v[222:225], v[6:9]
	v_mfma_f32_16x16x32_bf16 v[2:5], v[244:247], v[222:225], v[2:5]
	v_mfma_f32_16x16x32_bf16 v[30:33], v[240:243], v[184:187], v[30:33]
	v_mfma_f32_16x16x32_bf16 v[26:29], v[248:251], v[184:187], v[26:29]
	v_mfma_f32_16x16x32_bf16 v[22:25], v[240:243], v[192:195], v[22:25]
	v_mfma_f32_16x16x32_bf16 v[18:21], v[248:251], v[192:195], v[18:21]
	v_mfma_f32_16x16x32_bf16 v[14:17], v[240:243], v[200:203], v[14:17]
	v_mfma_f32_16x16x32_bf16 v[10:13], v[248:251], v[200:203], v[10:13]
	v_mfma_f32_16x16x32_bf16 v[6:9], v[240:243], v[232:235], v[6:9]
	v_mfma_f32_16x16x32_bf16 v[2:5], v[248:251], v[232:235], v[2:5]
	s_setprio 0
	s_add_i32 s0, s0, 2
	s_add_u32 s12, s12, 0x100
	s_addc_u32 s13, s13, 0
	s_cmp_lt_u32 s0, 28
	s_barrier
	s_cbranch_scc1 .LBB0_180
	s_add_i32 s1, s1, 0x1e000
	s_mov_b64 s[12:13], 0xf80
	v_readfirstlane_b32 s0, v162
	v_lshl_add_u64 v[132:133], v[132:133], 0, s[12:13]
	s_mov_b32 m0, s0
	v_readfirstlane_b32 s0, v163
	ds_read_b128 v[134:137], v151
	ds_read_b128 v[138:141], v151 offset:1024
	ds_read_b128 v[152:155], v151 offset:2048
	ds_read_b128 v[156:159], v151 offset:3072
	ds_read_b128 v[164:167], v0
	ds_read_b128 v[168:171], v0 offset:1024
	ds_read_b128 v[172:175], v0 offset:2048
	ds_read_b128 v[176:179], v0 offset:3072
	ds_read_b128 v[180:183], v0 offset:4096
	ds_read_b128 v[184:187], v0 offset:5120
	ds_read_b128 v[188:191], v0 offset:6144
	ds_read_b128 v[192:195], v0 offset:7168
	global_load_lds_dwordx4 v[132:133], off
	v_lshl_add_u64 v[130:131], v[130:131], 0, s[12:13]
	s_mov_b32 m0, s0
	s_nop 0
	global_load_lds_dwordx4 v[130:131], off
	s_barrier
	s_waitcnt lgkmcnt(0)
	s_setprio 1
	s_waitcnt lgkmcnt(0)
	v_mfma_f32_16x16x32_bf16 v[126:129], v[134:137], v[164:167], v[126:129]
	v_mfma_f32_16x16x32_bf16 v[122:125], v[152:155], v[164:167], v[122:125]
	v_mfma_f32_16x16x32_bf16 v[114:117], v[152:155], v[172:175], v[114:117]
	v_mfma_f32_16x16x32_bf16 v[106:109], v[152:155], v[180:183], v[106:109]
	v_mfma_f32_16x16x32_bf16 v[98:101], v[152:155], v[188:191], v[98:101]
	v_mfma_f32_16x16x32_bf16 v[126:129], v[138:141], v[168:171], v[126:129]
	v_mfma_f32_16x16x32_bf16 v[122:125], v[156:159], v[168:171], v[122:125]
	v_mfma_f32_16x16x32_bf16 v[118:121], v[134:137], v[172:175], v[118:121]
	v_mfma_f32_16x16x32_bf16 v[114:117], v[156:159], v[176:179], v[114:117]
	v_mfma_f32_16x16x32_bf16 v[110:113], v[134:137], v[180:183], v[110:113]
	v_mfma_f32_16x16x32_bf16 v[106:109], v[156:159], v[184:187], v[106:109]
	v_mfma_f32_16x16x32_bf16 v[102:105], v[134:137], v[188:191], v[102:105]
	v_mfma_f32_16x16x32_bf16 v[98:101], v[156:159], v[192:195], v[98:101]
	v_mfma_f32_16x16x32_bf16 v[130:133], v[138:141], v[176:179], v[118:121]
	v_mfma_f32_16x16x32_bf16 v[160:163], v[138:141], v[184:187], v[110:113]
	v_mfma_f32_16x16x32_bf16 v[196:199], v[138:141], v[192:195], v[102:105]
	s_setprio 0
	s_barrier
	s_nop 0
	ds_read_b128 v[102:105], v151 offset:16384
	ds_read_b128 v[110:113], v151 offset:17408
	ds_read_b128 v[118:121], v151 offset:18432
	ds_read_b128 v[200:203], v151 offset:19456
	s_barrier
	s_waitcnt lgkmcnt(0)
	s_setprio 1
	s_waitcnt lgkmcnt(1)
	v_mfma_f32_16x16x32_bf16 v[90:93], v[118:121], v[164:167], v[90:93]
	v_mfma_f32_16x16x32_bf16 v[82:85], v[118:121], v[172:175], v[82:85]
	v_mfma_f32_16x16x32_bf16 v[74:77], v[118:121], v[180:183], v[74:77]
	v_mfma_f32_16x16x32_bf16 v[66:69], v[118:121], v[188:191], v[66:69]
	v_mfma_f32_16x16x32_bf16 v[94:97], v[102:105], v[164:167], v[94:97]
	s_waitcnt lgkmcnt(0)
	v_mfma_f32_16x16x32_bf16 v[90:93], v[200:203], v[168:171], v[90:93]
	v_mfma_f32_16x16x32_bf16 v[86:89], v[102:105], v[172:175], v[86:89]
	v_mfma_f32_16x16x32_bf16 v[82:85], v[200:203], v[176:179], v[82:85]
	v_mfma_f32_16x16x32_bf16 v[78:81], v[102:105], v[180:183], v[78:81]
	v_mfma_f32_16x16x32_bf16 v[74:77], v[200:203], v[184:187], v[74:77]
	v_mfma_f32_16x16x32_bf16 v[70:73], v[102:105], v[188:191], v[70:73]
	v_mfma_f32_16x16x32_bf16 v[66:69], v[200:203], v[192:195], v[66:69]
	v_mfma_f32_16x16x32_bf16 v[222:225], v[110:113], v[168:171], v[94:97]
	v_mfma_f32_16x16x32_bf16 v[164:167], v[110:113], v[176:179], v[86:89]
	v_mfma_f32_16x16x32_bf16 v[168:171], v[110:113], v[184:187], v[78:81]
	v_mfma_f32_16x16x32_bf16 v[172:175], v[110:113], v[192:195], v[70:73]
	s_setprio 0
	s_barrier
	s_nop 0
	ds_read_b128 v[70:73], v0 offset:16384
	ds_read_b128 v[78:81], v0 offset:17408
	ds_read_b128 v[86:89], v0 offset:18432
	ds_read_b128 v[94:97], v0 offset:19456
	ds_read_b128 v[176:179], v0 offset:20480
	ds_read_b128 v[180:183], v0 offset:21504
	ds_read_b128 v[184:187], v0 offset:22528
	ds_read_b128 v[188:191], v0 offset:23552
	s_waitcnt vmcnt(4)
	s_barrier
	s_waitcnt lgkmcnt(0)
	s_setprio 1
	s_waitcnt lgkmcnt(7)
	v_mfma_f32_16x16x32_bf16 v[62:65], v[134:137], v[70:73], v[62:65]
	v_mfma_f32_16x16x32_bf16 v[58:61], v[152:155], v[70:73], v[58:61]
	s_waitcnt lgkmcnt(5)
	v_mfma_f32_16x16x32_bf16 v[50:53], v[152:155], v[86:89], v[50:53]
	s_waitcnt lgkmcnt(3)
	v_mfma_f32_16x16x32_bf16 v[42:45], v[152:155], v[176:179], v[42:45]
	s_waitcnt lgkmcnt(1)
	v_mfma_f32_16x16x32_bf16 v[34:37], v[152:155], v[184:187], v[34:37]
	v_mfma_f32_16x16x32_bf16 v[62:65], v[138:141], v[78:81], v[62:65]
	v_mfma_f32_16x16x32_bf16 v[58:61], v[156:159], v[78:81], v[58:61]
	v_mfma_f32_16x16x32_bf16 v[54:57], v[134:137], v[86:89], v[54:57]
	v_mfma_f32_16x16x32_bf16 v[50:53], v[156:159], v[94:97], v[50:53]
	v_mfma_f32_16x16x32_bf16 v[46:49], v[134:137], v[176:179], v[46:49]
	v_mfma_f32_16x16x32_bf16 v[42:45], v[156:159], v[180:183], v[42:45]
	v_mfma_f32_16x16x32_bf16 v[38:41], v[134:137], v[184:187], v[38:41]
	s_waitcnt lgkmcnt(0)
	v_mfma_f32_16x16x32_bf16 v[34:37], v[156:159], v[188:191], v[34:37]
	v_mfma_f32_16x16x32_bf16 v[192:195], v[138:141], v[94:97], v[54:57]
	v_mfma_f32_16x16x32_bf16 v[232:235], v[138:141], v[180:183], v[46:49]
	v_mfma_f32_16x16x32_bf16 v[134:137], v[138:141], v[188:191], v[38:41]
	s_setprio 0
	s_setprio 1
	v_mfma_f32_16x16x32_bf16 v[26:29], v[118:121], v[70:73], v[26:29]
	v_mfma_f32_16x16x32_bf16 v[18:21], v[118:121], v[86:89], v[18:21]
	v_mfma_f32_16x16x32_bf16 v[10:13], v[118:121], v[176:179], v[10:13]
	v_mfma_f32_16x16x32_bf16 v[2:5], v[118:121], v[184:187], v[2:5]
	v_mfma_f32_16x16x32_bf16 v[30:33], v[102:105], v[70:73], v[30:33]
	v_mfma_f32_16x16x32_bf16 v[26:29], v[200:203], v[78:81], v[26:29]
	v_mfma_f32_16x16x32_bf16 v[22:25], v[102:105], v[86:89], v[22:25]
	v_mfma_f32_16x16x32_bf16 v[18:21], v[200:203], v[94:97], v[18:21]
	v_mfma_f32_16x16x32_bf16 v[14:17], v[102:105], v[176:179], v[14:17]
	v_mfma_f32_16x16x32_bf16 v[10:13], v[200:203], v[180:183], v[10:13]
	v_mfma_f32_16x16x32_bf16 v[6:9], v[102:105], v[184:187], v[6:9]
	v_mfma_f32_16x16x32_bf16 v[2:5], v[200:203], v[188:191], v[2:5]
	v_mfma_f32_16x16x32_bf16 v[138:141], v[110:113], v[78:81], v[30:33]
	v_mfma_f32_16x16x32_bf16 v[152:155], v[110:113], v[94:97], v[22:25]
	v_mfma_f32_16x16x32_bf16 v[156:159], v[110:113], v[180:183], v[14:17]
	v_mfma_f32_16x16x32_bf16 v[176:179], v[110:113], v[188:191], v[6:9]
	s_setprio 0
	s_barrier
	s_nop 0
	ds_read_b128 v[6:9], v151 offset:32768
	ds_read_b128 v[14:17], v151 offset:33792
	ds_read_b128 v[180:183], v151 offset:34816
	ds_read_b128 v[184:187], v151 offset:35840
	ds_read_b128 v[22:25], v0 offset:32768
	ds_read_b128 v[30:33], v0 offset:33792
	ds_read_b128 v[38:41], v0 offset:34816
	ds_read_b128 v[46:49], v0 offset:35840
	ds_read_b128 v[54:57], v0 offset:36864
	ds_read_b128 v[188:191], v0 offset:37888
	ds_read_b128 v[200:203], v0 offset:38912
	ds_read_b128 v[236:239], v0 offset:39936
	s_waitcnt vmcnt(2)
	s_barrier
	s_waitcnt lgkmcnt(0)
	s_setprio 1
	s_waitcnt lgkmcnt(7)
	v_mfma_f32_16x16x32_bf16 v[70:73], v[6:9], v[22:25], v[126:129]
	s_waitcnt lgkmcnt(6)
	v_mfma_f32_16x16x32_bf16 v[126:129], v[14:17], v[30:33], v[70:73]
	v_mfma_f32_16x16x32_bf16 v[70:73], v[180:183], v[22:25], v[122:125]
	v_mfma_f32_16x16x32_bf16 v[118:121], v[184:187], v[30:33], v[70:73]
	s_waitcnt lgkmcnt(5)
	v_mfma_f32_16x16x32_bf16 v[70:73], v[6:9], v[38:41], v[130:133]
	s_waitcnt lgkmcnt(4)
	v_mfma_f32_16x16x32_bf16 v[110:113], v[14:17], v[46:49], v[70:73]
	v_mfma_f32_16x16x32_bf16 v[70:73], v[180:183], v[38:41], v[114:117]
	v_mfma_f32_16x16x32_bf16 v[102:105], v[184:187], v[46:49], v[70:73]
	s_waitcnt lgkmcnt(3)
	v_mfma_f32_16x16x32_bf16 v[70:73], v[6:9], v[54:57], v[160:163]
	s_waitcnt lgkmcnt(2)
	v_mfma_f32_16x16x32_bf16 v[94:97], v[14:17], v[188:191], v[70:73]
	v_mfma_f32_16x16x32_bf16 v[70:73], v[180:183], v[54:57], v[106:109]
	v_mfma_f32_16x16x32_bf16 v[86:89], v[184:187], v[188:191], v[70:73]
	s_waitcnt lgkmcnt(1)
	v_mfma_f32_16x16x32_bf16 v[70:73], v[6:9], v[200:203], v[196:199]
	s_waitcnt lgkmcnt(0)
	v_mfma_f32_16x16x32_bf16 v[78:81], v[14:17], v[236:239], v[70:73]
	v_mfma_f32_16x16x32_bf16 v[70:73], v[180:183], v[200:203], v[98:101]
	v_mfma_f32_16x16x32_bf16 v[70:73], v[184:187], v[236:239], v[70:73]
	s_setprio 0
	s_barrier
	ds_read_b128 v[130:133], v151 offset:49152
	ds_read_b128 v[160:163], v151 offset:50176
	ds_read_b128 v[196:199], v151 offset:51200
	ds_read_b128 v[148:151], v151 offset:52224
	s_waitcnt vmcnt(0)
	s_barrier
	s_waitcnt lgkmcnt(0)
	s_setprio 1
	s_waitcnt lgkmcnt(3)
	v_mfma_f32_16x16x32_bf16 v[98:101], v[130:133], v[22:25], v[222:225]
	s_waitcnt lgkmcnt(1)
	v_mfma_f32_16x16x32_bf16 v[22:25], v[196:199], v[22:25], v[90:93]
	s_waitcnt lgkmcnt(0)
	v_mfma_f32_16x16x32_bf16 v[114:117], v[148:151], v[30:33], v[22:25]
	v_mfma_f32_16x16x32_bf16 v[22:25], v[130:133], v[38:41], v[164:167]
	v_mfma_f32_16x16x32_bf16 v[106:109], v[160:163], v[46:49], v[22:25]
	v_mfma_f32_16x16x32_bf16 v[22:25], v[196:199], v[38:41], v[82:85]
	v_mfma_f32_16x16x32_bf16 v[122:125], v[160:163], v[30:33], v[98:101]
	v_mfma_f32_16x16x32_bf16 v[98:101], v[148:151], v[46:49], v[22:25]
	v_mfma_f32_16x16x32_bf16 v[22:25], v[130:133], v[54:57], v[168:171]
	v_mfma_f32_16x16x32_bf16 v[90:93], v[160:163], v[188:191], v[22:25]
	v_mfma_f32_16x16x32_bf16 v[22:25], v[196:199], v[54:57], v[74:77]
	v_mfma_f32_16x16x32_bf16 v[82:85], v[148:151], v[188:191], v[22:25]
	v_mfma_f32_16x16x32_bf16 v[22:25], v[130:133], v[200:203], v[172:175]
	v_mfma_f32_16x16x32_bf16 v[74:77], v[160:163], v[236:239], v[22:25]
	v_mfma_f32_16x16x32_bf16 v[22:25], v[196:199], v[200:203], v[66:69]
	v_mfma_f32_16x16x32_bf16 v[66:69], v[148:151], v[236:239], v[22:25]
	s_setprio 0
	s_barrier
	ds_read_b128 v[164:167], v0 offset:49152
	ds_read_b128 v[168:171], v0 offset:50176
	ds_read_b128 v[172:175], v0 offset:51200
	ds_read_b128 v[188:191], v0 offset:52224
	ds_read_b128 v[200:203], v0 offset:53248
	ds_read_b128 v[222:225], v0 offset:54272
	ds_read_b128 v[236:239], v0 offset:55296
	ds_read_b128 v[240:243], v0 offset:56320
	s_barrier
	s_waitcnt lgkmcnt(0)
	s_setprio 1
	s_waitcnt lgkmcnt(7)
	v_mfma_f32_16x16x32_bf16 v[22:25], v[6:9], v[164:167], v[62:65]
	s_waitcnt lgkmcnt(6)
	v_mfma_f32_16x16x32_bf16 v[62:65], v[14:17], v[168:171], v[22:25]
	v_mfma_f32_16x16x32_bf16 v[22:25], v[180:183], v[164:167], v[58:61]
	v_mfma_f32_16x16x32_bf16 v[54:57], v[184:187], v[168:171], v[22:25]
	s_waitcnt lgkmcnt(5)
	v_mfma_f32_16x16x32_bf16 v[22:25], v[6:9], v[172:175], v[192:195]
	s_waitcnt lgkmcnt(4)
	v_mfma_f32_16x16x32_bf16 v[46:49], v[14:17], v[188:191], v[22:25]
	v_mfma_f32_16x16x32_bf16 v[22:25], v[180:183], v[172:175], v[50:53]
	v_mfma_f32_16x16x32_bf16 v[38:41], v[184:187], v[188:191], v[22:25]
	s_waitcnt lgkmcnt(3)
	v_mfma_f32_16x16x32_bf16 v[22:25], v[6:9], v[200:203], v[232:235]
	s_waitcnt lgkmcnt(1)
	v_mfma_f32_16x16x32_bf16 v[6:9], v[6:9], v[236:239], v[134:137]
	v_mfma_f32_16x16x32_bf16 v[30:33], v[14:17], v[222:225], v[22:25]
	v_mfma_f32_16x16x32_bf16 v[22:25], v[180:183], v[200:203], v[42:45]
	s_waitcnt lgkmcnt(0)
	v_mfma_f32_16x16x32_bf16 v[14:17], v[14:17], v[240:243], v[6:9]
	v_mfma_f32_16x16x32_bf16 v[6:9], v[180:183], v[236:239], v[34:37]
	v_mfma_f32_16x16x32_bf16 v[22:25], v[184:187], v[222:225], v[22:25]
	v_mfma_f32_16x16x32_bf16 v[6:9], v[184:187], v[240:243], v[6:9]
	s_setprio 0
	s_setprio 1
	v_mfma_f32_16x16x32_bf16 v[34:37], v[130:133], v[164:167], v[138:141]
	v_mfma_f32_16x16x32_bf16 v[26:29], v[196:199], v[164:167], v[26:29]
	v_mfma_f32_16x16x32_bf16 v[18:21], v[196:199], v[172:175], v[18:21]
	v_mfma_f32_16x16x32_bf16 v[58:61], v[160:163], v[168:171], v[34:37]
	v_mfma_f32_16x16x32_bf16 v[50:53], v[148:151], v[168:171], v[26:29]
	v_mfma_f32_16x16x32_bf16 v[26:29], v[130:133], v[172:175], v[152:155]
	v_mfma_f32_16x16x32_bf16 v[34:37], v[148:151], v[188:191], v[18:21]
	v_mfma_f32_16x16x32_bf16 v[18:21], v[130:133], v[200:203], v[156:159]
	v_mfma_f32_16x16x32_bf16 v[10:13], v[196:199], v[200:203], v[10:13]
	v_mfma_f32_16x16x32_bf16 v[42:45], v[160:163], v[188:191], v[26:29]
	v_mfma_f32_16x16x32_bf16 v[26:29], v[160:163], v[222:225], v[18:21]
	v_mfma_f32_16x16x32_bf16 v[18:21], v[148:151], v[222:225], v[10:13]
	v_mfma_f32_16x16x32_bf16 v[10:13], v[130:133], v[236:239], v[176:179]
	v_mfma_f32_16x16x32_bf16 v[2:5], v[196:199], v[236:239], v[2:5]
	v_mfma_f32_16x16x32_bf16 v[10:13], v[160:163], v[240:243], v[10:13]
	v_mfma_f32_16x16x32_bf16 v[2:5], v[148:151], v[240:243], v[2:5]
	s_setprio 0
	s_movk_i32 s0, 0x100
	v_cmp_gt_u32_e32 vcc, s0, v142
	s_barrier
	s_and_saveexec_b64 s[0:1], vcc
	s_cbranch_execz .LBB0_183
	s_barrier

.LBB0_678:
	ds_read_b128 v[164:167], v151
	ds_read_b128 v[168:171], v151 offset:1024
	ds_read_b128 v[172:175], v151 offset:2048
	ds_read_b128 v[176:179], v151 offset:3072
	v_add_u32_e32 v162, 0xc000, v147
	v_add_u32_e32 v163, 0xe000, v147
	v_lshl_add_u64 v[204:205], v[138:139], 0, s[8:9]
	v_lshl_add_u64 v[218:219], v[204:205], 0, s[60:61]
	s_add_i32 m0, s1, 0xc000
	ds_read_b128 v[180:183], v0
	ds_read_b128 v[184:187], v0 offset:1024
	ds_read_b128 v[188:191], v0 offset:2048
	ds_read_b128 v[192:195], v0 offset:3072
	ds_read_b128 v[196:199], v0 offset:4096
	ds_read_b128 v[200:203], v0 offset:5120
	ds_read_b128 v[232:235], v0 offset:6144
	ds_read_b128 v[236:239], v0 offset:7168
	global_load_lds_dwordx4 v[218:219], off
	v_lshl_add_u64 v[216:217], v[140:141], 0, s[8:9]
	v_lshl_add_u64 v[152:153], v[216:217], 0, s[60:61]
	s_add_i32 m0, s1, 0xe000
	s_nop 0
	global_load_lds_dwordx4 v[152:153], off
	s_waitcnt lgkmcnt(8)
	s_barrier
	s_waitcnt lgkmcnt(0)
	s_setprio 1
	s_waitcnt lgkmcnt(0)
	v_mfma_f32_16x16x32_bf16 v[126:129], v[164:167], v[180:183], v[126:129]
	v_mfma_f32_16x16x32_bf16 v[122:125], v[172:175], v[180:183], v[122:125]
	v_mfma_f32_16x16x32_bf16 v[118:121], v[164:167], v[188:191], v[118:121]
	v_mfma_f32_16x16x32_bf16 v[114:117], v[172:175], v[188:191], v[114:117]
	v_mfma_f32_16x16x32_bf16 v[110:113], v[164:167], v[196:199], v[110:113]
	v_mfma_f32_16x16x32_bf16 v[106:109], v[172:175], v[196:199], v[106:109]
	v_mfma_f32_16x16x32_bf16 v[102:105], v[164:167], v[232:235], v[102:105]
	v_mfma_f32_16x16x32_bf16 v[98:101], v[172:175], v[232:235], v[98:101]
	v_mfma_f32_16x16x32_bf16 v[126:129], v[168:171], v[184:187], v[126:129]
	v_mfma_f32_16x16x32_bf16 v[122:125], v[176:179], v[184:187], v[122:125]
	v_mfma_f32_16x16x32_bf16 v[118:121], v[168:171], v[192:195], v[118:121]
	v_mfma_f32_16x16x32_bf16 v[114:117], v[176:179], v[192:195], v[114:117]
	v_mfma_f32_16x16x32_bf16 v[110:113], v[168:171], v[200:203], v[110:113]
	v_mfma_f32_16x16x32_bf16 v[106:109], v[176:179], v[200:203], v[106:109]
	v_mfma_f32_16x16x32_bf16 v[102:105], v[168:171], v[236:239], v[102:105]
	v_mfma_f32_16x16x32_bf16 v[98:101], v[176:179], v[236:239], v[98:101]
	s_setprio 0
	s_barrier
	v_lshl_add_u64 v[210:211], v[134:135], 0, s[8:9]
	s_add_i32 m0, s1, 0xff00
	ds_read_b128 v[240:243], v151 offset:16384
	ds_read_b128 v[244:247], v151 offset:17408
	ds_read_b128 v[248:251], v151 offset:18432
	ds_read_b128 v[222:225], v151 offset:19456
	global_load_lds_dwordx4 v[210:211], off offset:256
	v_lshl_add_u64 v[228:229], v[136:137], 0, s[8:9]
	s_add_i32 m0, s1, 0x11f00
	s_nop 0
	global_load_lds_dwordx4 v[228:229], off offset:256
	s_barrier
	s_waitcnt lgkmcnt(0)
	s_setprio 1
	s_waitcnt lgkmcnt(0)
	v_mfma_f32_16x16x32_bf16 v[94:97], v[240:243], v[180:183], v[94:97]
	v_mfma_f32_16x16x32_bf16 v[90:93], v[248:251], v[180:183], v[90:93]
	v_mfma_f32_16x16x32_bf16 v[86:89], v[240:243], v[188:191], v[86:89]
	v_mfma_f32_16x16x32_bf16 v[82:85], v[248:251], v[188:191], v[82:85]
	v_mfma_f32_16x16x32_bf16 v[78:81], v[240:243], v[196:199], v[78:81]
	v_mfma_f32_16x16x32_bf16 v[74:77], v[248:251], v[196:199], v[74:77]
	v_mfma_f32_16x16x32_bf16 v[70:73], v[240:243], v[232:235], v[70:73]
	v_mfma_f32_16x16x32_bf16 v[66:69], v[248:251], v[232:235], v[66:69]
	v_mfma_f32_16x16x32_bf16 v[94:97], v[244:247], v[184:187], v[94:97]
	v_mfma_f32_16x16x32_bf16 v[90:93], v[222:225], v[184:187], v[90:93]
	v_mfma_f32_16x16x32_bf16 v[86:89], v[244:247], v[192:195], v[86:89]
	v_mfma_f32_16x16x32_bf16 v[82:85], v[222:225], v[192:195], v[82:85]
	v_mfma_f32_16x16x32_bf16 v[78:81], v[244:247], v[200:203], v[78:81]
	v_mfma_f32_16x16x32_bf16 v[74:77], v[222:225], v[200:203], v[74:77]
	v_mfma_f32_16x16x32_bf16 v[70:73], v[244:247], v[236:239], v[70:73]
	v_mfma_f32_16x16x32_bf16 v[66:69], v[222:225], v[236:239], v[66:69]
	s_setprio 0
	v_lshl_add_u64 v[158:159], v[204:205], 0, s[74:75]
	s_mov_b32 m0, s1
	s_barrier
	ds_read_b128 v[180:183], v0 offset:16384
	ds_read_b128 v[184:187], v0 offset:17408
	ds_read_b128 v[188:191], v0 offset:18432
	ds_read_b128 v[192:195], v0 offset:19456
	ds_read_b128 v[196:199], v0 offset:20480
	ds_read_b128 v[200:203], v0 offset:21504
	ds_read_b128 v[232:235], v0 offset:22528
	ds_read_b128 v[236:239], v0 offset:23552
	global_load_lds_dwordx4 v[158:159], off
	s_add_i32 m0, s1, 0x1f00
	s_nop 0
	global_load_lds_dwordx4 v[216:217], off offset:256
	s_barrier
	s_waitcnt lgkmcnt(0)
	s_setprio 1
	s_waitcnt lgkmcnt(0)
	v_mfma_f32_16x16x32_bf16 v[62:65], v[164:167], v[180:183], v[62:65]
	v_mfma_f32_16x16x32_bf16 v[58:61], v[172:175], v[180:183], v[58:61]
	v_mfma_f32_16x16x32_bf16 v[54:57], v[164:167], v[188:191], v[54:57]
	v_mfma_f32_16x16x32_bf16 v[50:53], v[172:175], v[188:191], v[50:53]
	v_mfma_f32_16x16x32_bf16 v[46:49], v[164:167], v[196:199], v[46:49]
	v_mfma_f32_16x16x32_bf16 v[42:45], v[172:175], v[196:199], v[42:45]
	v_mfma_f32_16x16x32_bf16 v[38:41], v[164:167], v[232:235], v[38:41]
	v_mfma_f32_16x16x32_bf16 v[34:37], v[172:175], v[232:235], v[34:37]
	v_mfma_f32_16x16x32_bf16 v[62:65], v[168:171], v[184:187], v[62:65]
	v_mfma_f32_16x16x32_bf16 v[58:61], v[176:179], v[184:187], v[58:61]
	v_mfma_f32_16x16x32_bf16 v[54:57], v[168:171], v[192:195], v[54:57]
	v_mfma_f32_16x16x32_bf16 v[50:53], v[176:179], v[192:195], v[50:53]
	v_mfma_f32_16x16x32_bf16 v[46:49], v[168:171], v[200:203], v[46:49]
	v_mfma_f32_16x16x32_bf16 v[42:45], v[176:179], v[200:203], v[42:45]
	v_mfma_f32_16x16x32_bf16 v[38:41], v[168:171], v[236:239], v[38:41]
	v_mfma_f32_16x16x32_bf16 v[34:37], v[176:179], v[236:239], v[34:37]
	s_setprio 0
	s_barrier
	v_lshl_add_u64 v[154:155], v[210:211], 0, s[18:19]
	s_add_i32 m0, s1, 0x14000
	s_nop 0
	global_load_lds_dwordx4 v[154:155], off
	v_lshl_add_u64 v[156:157], v[228:229], 0, s[18:19]
	s_add_i32 m0, s1, 0x16000
	s_nop 0
	global_load_lds_dwordx4 v[156:157], off
	s_waitcnt vmcnt(6)
	s_barrier
	s_setprio 1
	v_mfma_f32_16x16x32_bf16 v[30:33], v[240:243], v[180:183], v[30:33]
	v_mfma_f32_16x16x32_bf16 v[26:29], v[248:251], v[180:183], v[26:29]
	v_mfma_f32_16x16x32_bf16 v[22:25], v[240:243], v[188:191], v[22:25]
	v_mfma_f32_16x16x32_bf16 v[18:21], v[248:251], v[188:191], v[18:21]
	v_mfma_f32_16x16x32_bf16 v[14:17], v[240:243], v[196:199], v[14:17]
	v_mfma_f32_16x16x32_bf16 v[10:13], v[248:251], v[196:199], v[10:13]
	v_mfma_f32_16x16x32_bf16 v[6:9], v[240:243], v[232:235], v[6:9]
	v_mfma_f32_16x16x32_bf16 v[2:5], v[248:251], v[232:235], v[2:5]
	v_mfma_f32_16x16x32_bf16 v[30:33], v[244:247], v[184:187], v[30:33]
	v_mfma_f32_16x16x32_bf16 v[26:29], v[222:225], v[184:187], v[26:29]
	v_mfma_f32_16x16x32_bf16 v[22:25], v[244:247], v[192:195], v[22:25]
	v_mfma_f32_16x16x32_bf16 v[18:21], v[222:225], v[192:195], v[18:21]
	v_mfma_f32_16x16x32_bf16 v[14:17], v[244:247], v[200:203], v[14:17]
	v_mfma_f32_16x16x32_bf16 v[10:13], v[222:225], v[200:203], v[10:13]
	v_mfma_f32_16x16x32_bf16 v[6:9], v[244:247], v[236:239], v[6:9]
	v_mfma_f32_16x16x32_bf16 v[2:5], v[222:225], v[236:239], v[2:5]
	s_setprio 0
	s_barrier
	ds_read_b128 v[164:167], v151 offset:32768
	ds_read_b128 v[168:171], v151 offset:33792
	ds_read_b128 v[172:175], v151 offset:34816
	ds_read_b128 v[176:179], v151 offset:35840
	s_add_i32 m0, s1, 0x3f80
	ds_read_b128 v[180:183], v0 offset:32768
	ds_read_b128 v[184:187], v0 offset:33792
	ds_read_b128 v[188:191], v0 offset:34816
	ds_read_b128 v[192:195], v0 offset:35840
	ds_read_b128 v[196:199], v0 offset:36864
	ds_read_b128 v[200:203], v0 offset:37888
	ds_read_b128 v[222:225], v0 offset:38912
	ds_read_b128 v[232:235], v0 offset:39936
	global_load_lds_dwordx4 v[218:219], off offset:128
	s_add_i32 m0, s1, 0x5f80
	s_nop 0
	global_load_lds_dwordx4 v[152:153], off offset:128
	s_waitcnt lgkmcnt(8)
	s_barrier
	s_waitcnt lgkmcnt(0)
	s_setprio 1
	s_waitcnt lgkmcnt(0)
	v_mfma_f32_16x16x32_bf16 v[126:129], v[164:167], v[180:183], v[126:129]
	v_mfma_f32_16x16x32_bf16 v[122:125], v[172:175], v[180:183], v[122:125]
	v_mfma_f32_16x16x32_bf16 v[118:121], v[164:167], v[188:191], v[118:121]
	v_mfma_f32_16x16x32_bf16 v[114:117], v[172:175], v[188:191], v[114:117]
	v_mfma_f32_16x16x32_bf16 v[110:113], v[164:167], v[196:199], v[110:113]
	v_mfma_f32_16x16x32_bf16 v[106:109], v[172:175], v[196:199], v[106:109]
	v_mfma_f32_16x16x32_bf16 v[102:105], v[164:167], v[222:225], v[102:105]
	v_mfma_f32_16x16x32_bf16 v[98:101], v[172:175], v[222:225], v[98:101]
	v_mfma_f32_16x16x32_bf16 v[126:129], v[168:171], v[184:187], v[126:129]
	v_mfma_f32_16x16x32_bf16 v[122:125], v[176:179], v[184:187], v[122:125]
	v_mfma_f32_16x16x32_bf16 v[118:121], v[168:171], v[192:195], v[118:121]
	v_mfma_f32_16x16x32_bf16 v[114:117], v[176:179], v[192:195], v[114:117]
	v_mfma_f32_16x16x32_bf16 v[110:113], v[168:171], v[200:203], v[110:113]
	v_mfma_f32_16x16x32_bf16 v[106:109], v[176:179], v[200:203], v[106:109]
	v_mfma_f32_16x16x32_bf16 v[102:105], v[168:171], v[232:235], v[102:105]
	v_mfma_f32_16x16x32_bf16 v[98:101], v[176:179], v[232:235], v[98:101]
	s_setprio 0
	s_barrier
	s_add_i32 m0, s1, 0x17e80
	ds_read_b128 v[236:239], v151 offset:49152
	ds_read_b128 v[240:243], v151 offset:50176
	ds_read_b128 v[244:247], v151 offset:51200
	ds_read_b128 v[248:251], v151 offset:52224
	global_load_lds_dwordx4 v[210:211], off offset:384
	s_add_i32 m0, s1, 0x19e80
	s_nop 0
	global_load_lds_dwordx4 v[228:229], off offset:384
	s_barrier
	s_waitcnt lgkmcnt(0)
	s_setprio 1
	s_waitcnt lgkmcnt(0)
	v_mfma_f32_16x16x32_bf16 v[94:97], v[236:239], v[180:183], v[94:97]
	v_mfma_f32_16x16x32_bf16 v[90:93], v[244:247], v[180:183], v[90:93]
	v_mfma_f32_16x16x32_bf16 v[86:89], v[236:239], v[188:191], v[86:89]
	v_mfma_f32_16x16x32_bf16 v[82:85], v[244:247], v[188:191], v[82:85]
	v_mfma_f32_16x16x32_bf16 v[78:81], v[236:239], v[196:199], v[78:81]
	v_mfma_f32_16x16x32_bf16 v[74:77], v[244:247], v[196:199], v[74:77]
	v_mfma_f32_16x16x32_bf16 v[70:73], v[236:239], v[222:225], v[70:73]
	v_mfma_f32_16x16x32_bf16 v[66:69], v[244:247], v[222:225], v[66:69]
	v_mfma_f32_16x16x32_bf16 v[94:97], v[240:243], v[184:187], v[94:97]
	v_mfma_f32_16x16x32_bf16 v[90:93], v[248:251], v[184:187], v[90:93]
	v_mfma_f32_16x16x32_bf16 v[86:89], v[240:243], v[192:195], v[86:89]
	v_mfma_f32_16x16x32_bf16 v[82:85], v[248:251], v[192:195], v[82:85]
	v_mfma_f32_16x16x32_bf16 v[78:81], v[240:243], v[200:203], v[78:81]
	v_mfma_f32_16x16x32_bf16 v[74:77], v[248:251], v[200:203], v[74:77]
	v_mfma_f32_16x16x32_bf16 v[70:73], v[240:243], v[232:235], v[70:73]
	v_mfma_f32_16x16x32_bf16 v[66:69], v[248:251], v[232:235], v[66:69]
	s_setprio 0
	s_add_i32 m0, s1, 0x7e80
	s_barrier
	ds_read_b128 v[180:183], v0 offset:49152
	ds_read_b128 v[184:187], v0 offset:50176
	ds_read_b128 v[188:191], v0 offset:51200
	ds_read_b128 v[192:195], v0 offset:52224
	ds_read_b128 v[196:199], v0 offset:53248
	ds_read_b128 v[200:203], v0 offset:54272
	ds_read_b128 v[222:225], v0 offset:55296
	ds_read_b128 v[232:235], v0 offset:56320
	global_load_lds_dwordx4 v[204:205], off offset:384
	s_add_i32 m0, s1, 0x9e80
	s_nop 0
	global_load_lds_dwordx4 v[216:217], off offset:384
	s_barrier
	s_waitcnt lgkmcnt(0)
	s_setprio 1
	s_waitcnt lgkmcnt(0)
	v_mfma_f32_16x16x32_bf16 v[62:65], v[164:167], v[180:183], v[62:65]
	v_mfma_f32_16x16x32_bf16 v[58:61], v[172:175], v[180:183], v[58:61]
	v_mfma_f32_16x16x32_bf16 v[54:57], v[164:167], v[188:191], v[54:57]
	v_mfma_f32_16x16x32_bf16 v[50:53], v[172:175], v[188:191], v[50:53]
	v_mfma_f32_16x16x32_bf16 v[46:49], v[164:167], v[196:199], v[46:49]
	v_mfma_f32_16x16x32_bf16 v[42:45], v[172:175], v[196:199], v[42:45]
	v_mfma_f32_16x16x32_bf16 v[38:41], v[164:167], v[222:225], v[38:41]
	v_mfma_f32_16x16x32_bf16 v[34:37], v[172:175], v[222:225], v[34:37]
	v_mfma_f32_16x16x32_bf16 v[62:65], v[168:171], v[184:187], v[62:65]
	v_mfma_f32_16x16x32_bf16 v[58:61], v[176:179], v[184:187], v[58:61]
	v_mfma_f32_16x16x32_bf16 v[54:57], v[168:171], v[192:195], v[54:57]
	v_mfma_f32_16x16x32_bf16 v[50:53], v[176:179], v[192:195], v[50:53]
	v_mfma_f32_16x16x32_bf16 v[46:49], v[168:171], v[200:203], v[46:49]
	v_mfma_f32_16x16x32_bf16 v[42:45], v[176:179], v[200:203], v[42:45]
	v_mfma_f32_16x16x32_bf16 v[38:41], v[168:171], v[232:235], v[38:41]
	v_mfma_f32_16x16x32_bf16 v[34:37], v[176:179], v[232:235], v[34:37]
	s_setprio 0
	s_barrier
	s_add_i32 m0, s1, 0x1bf80
	s_nop 0
	global_load_lds_dwordx4 v[154:155], off offset:128
	s_add_i32 m0, s1, 0x1df80
	s_nop 0
	global_load_lds_dwordx4 v[156:157], off offset:128
	s_waitcnt vmcnt(6)
	s_barrier
	s_setprio 1
	v_mfma_f32_16x16x32_bf16 v[30:33], v[236:239], v[180:183], v[30:33]
	v_mfma_f32_16x16x32_bf16 v[26:29], v[244:247], v[180:183], v[26:29]
	v_mfma_f32_16x16x32_bf16 v[22:25], v[236:239], v[188:191], v[22:25]
	v_mfma_f32_16x16x32_bf16 v[18:21], v[244:247], v[188:191], v[18:21]
	v_mfma_f32_16x16x32_bf16 v[14:17], v[236:239], v[196:199], v[14:17]
	v_mfma_f32_16x16x32_bf16 v[10:13], v[244:247], v[196:199], v[10:13]
	v_mfma_f32_16x16x32_bf16 v[6:9], v[236:239], v[222:225], v[6:9]
	v_mfma_f32_16x16x32_bf16 v[2:5], v[244:247], v[222:225], v[2:5]
	v_mfma_f32_16x16x32_bf16 v[30:33], v[240:243], v[184:187], v[30:33]
	v_mfma_f32_16x16x32_bf16 v[26:29], v[248:251], v[184:187], v[26:29]
	v_mfma_f32_16x16x32_bf16 v[22:25], v[240:243], v[192:195], v[22:25]
	v_mfma_f32_16x16x32_bf16 v[18:21], v[248:251], v[192:195], v[18:21]
	v_mfma_f32_16x16x32_bf16 v[14:17], v[240:243], v[200:203], v[14:17]
	v_mfma_f32_16x16x32_bf16 v[10:13], v[248:251], v[200:203], v[10:13]
	v_mfma_f32_16x16x32_bf16 v[6:9], v[240:243], v[232:235], v[6:9]
	v_mfma_f32_16x16x32_bf16 v[2:5], v[248:251], v[232:235], v[2:5]
	s_setprio 0
	s_add_i32 s0, s0, 2
	s_add_u32 s8, s8, 0x100
	s_addc_u32 s9, s9, 0
	s_cmp_lt_u32 s0, 28
	s_barrier
	s_cbranch_scc1 .LBB0_678
	s_add_i32 s1, s1, 0x1e000
	s_mov_b64 s[8:9], 0xf80
	v_readfirstlane_b32 s0, v162
	v_lshl_add_u64 v[132:133], v[132:133], 0, s[8:9]
	s_mov_b32 m0, s0
	v_readfirstlane_b32 s0, v163
	ds_read_b128 v[134:137], v151
	ds_read_b128 v[138:141], v151 offset:1024
	ds_read_b128 v[152:155], v151 offset:2048
	ds_read_b128 v[156:159], v151 offset:3072
	ds_read_b128 v[164:167], v0
	ds_read_b128 v[168:171], v0 offset:1024
	ds_read_b128 v[172:175], v0 offset:2048
	ds_read_b128 v[176:179], v0 offset:3072
	ds_read_b128 v[180:183], v0 offset:4096
	ds_read_b128 v[184:187], v0 offset:5120
	ds_read_b128 v[188:191], v0 offset:6144
	ds_read_b128 v[192:195], v0 offset:7168
	global_load_lds_dwordx4 v[132:133], off
	v_lshl_add_u64 v[130:131], v[130:131], 0, s[8:9]
	s_mov_b32 m0, s0
	s_nop 0
	global_load_lds_dwordx4 v[130:131], off
	s_barrier
	s_waitcnt lgkmcnt(0)
	s_setprio 1
	s_waitcnt lgkmcnt(0)
	v_mfma_f32_16x16x32_bf16 v[126:129], v[134:137], v[164:167], v[126:129]
	v_mfma_f32_16x16x32_bf16 v[122:125], v[152:155], v[164:167], v[122:125]
	v_mfma_f32_16x16x32_bf16 v[114:117], v[152:155], v[172:175], v[114:117]
	v_mfma_f32_16x16x32_bf16 v[106:109], v[152:155], v[180:183], v[106:109]
	v_mfma_f32_16x16x32_bf16 v[98:101], v[152:155], v[188:191], v[98:101]
	v_mfma_f32_16x16x32_bf16 v[126:129], v[138:141], v[168:171], v[126:129]
	v_mfma_f32_16x16x32_bf16 v[122:125], v[156:159], v[168:171], v[122:125]
	v_mfma_f32_16x16x32_bf16 v[118:121], v[134:137], v[172:175], v[118:121]
	v_mfma_f32_16x16x32_bf16 v[114:117], v[156:159], v[176:179], v[114:117]
	v_mfma_f32_16x16x32_bf16 v[110:113], v[134:137], v[180:183], v[110:113]
	v_mfma_f32_16x16x32_bf16 v[106:109], v[156:159], v[184:187], v[106:109]
	v_mfma_f32_16x16x32_bf16 v[102:105], v[134:137], v[188:191], v[102:105]
	v_mfma_f32_16x16x32_bf16 v[98:101], v[156:159], v[192:195], v[98:101]
	v_mfma_f32_16x16x32_bf16 v[130:133], v[138:141], v[176:179], v[118:121]
	v_mfma_f32_16x16x32_bf16 v[160:163], v[138:141], v[184:187], v[110:113]
	v_mfma_f32_16x16x32_bf16 v[196:199], v[138:141], v[192:195], v[102:105]
	s_setprio 0
	s_barrier
	s_nop 0
	ds_read_b128 v[102:105], v151 offset:16384
	ds_read_b128 v[110:113], v151 offset:17408
	ds_read_b128 v[118:121], v151 offset:18432
	ds_read_b128 v[200:203], v151 offset:19456
	s_barrier
	s_waitcnt lgkmcnt(0)
	s_setprio 1
	s_waitcnt lgkmcnt(1)
	v_mfma_f32_16x16x32_bf16 v[90:93], v[118:121], v[164:167], v[90:93]
	v_mfma_f32_16x16x32_bf16 v[86:89], v[102:105], v[172:175], v[86:89]
	v_mfma_f32_16x16x32_bf16 v[82:85], v[118:121], v[172:175], v[82:85]
	v_mfma_f32_16x16x32_bf16 v[78:81], v[102:105], v[180:183], v[78:81]
	v_mfma_f32_16x16x32_bf16 v[70:73], v[102:105], v[188:191], v[70:73]
	v_mfma_f32_16x16x32_bf16 v[94:97], v[102:105], v[164:167], v[94:97]
	s_waitcnt lgkmcnt(0)
	v_mfma_f32_16x16x32_bf16 v[90:93], v[200:203], v[168:171], v[90:93]
	v_mfma_f32_16x16x32_bf16 v[86:89], v[110:113], v[176:179], v[86:89]
	v_mfma_f32_16x16x32_bf16 v[82:85], v[200:203], v[176:179], v[82:85]
	v_mfma_f32_16x16x32_bf16 v[78:81], v[110:113], v[184:187], v[78:81]
	v_mfma_f32_16x16x32_bf16 v[74:77], v[118:121], v[180:183], v[74:77]
	v_mfma_f32_16x16x32_bf16 v[70:73], v[110:113], v[192:195], v[70:73]
	v_mfma_f32_16x16x32_bf16 v[66:69], v[118:121], v[188:191], v[66:69]
	v_mfma_f32_16x16x32_bf16 v[222:225], v[110:113], v[168:171], v[94:97]
	v_mfma_f32_16x16x32_bf16 v[164:167], v[200:203], v[184:187], v[74:77]
	v_mfma_f32_16x16x32_bf16 v[168:171], v[200:203], v[192:195], v[66:69]
	s_setprio 0
	s_barrier
	s_nop 2
	ds_read_b128 v[66:69], v0 offset:16384
	ds_read_b128 v[74:77], v0 offset:17408
	ds_read_b128 v[94:97], v0 offset:18432
	ds_read_b128 v[172:175], v0 offset:19456
	ds_read_b128 v[176:179], v0 offset:20480
	ds_read_b128 v[180:183], v0 offset:21504
	ds_read_b128 v[184:187], v0 offset:22528
	ds_read_b128 v[188:191], v0 offset:23552
	s_waitcnt vmcnt(4)
	s_barrier
	s_waitcnt lgkmcnt(0)
	s_setprio 1
	s_waitcnt lgkmcnt(5)
	v_mfma_f32_16x16x32_bf16 v[54:57], v[134:137], v[94:97], v[54:57]
	v_mfma_f32_16x16x32_bf16 v[50:53], v[152:155], v[94:97], v[50:53]
	v_mfma_f32_16x16x32_bf16 v[62:65], v[134:137], v[66:69], v[62:65]
	v_mfma_f32_16x16x32_bf16 v[58:61], v[152:155], v[66:69], v[58:61]
	s_waitcnt lgkmcnt(4)
	v_mfma_f32_16x16x32_bf16 v[54:57], v[138:141], v[172:175], v[54:57]
	v_mfma_f32_16x16x32_bf16 v[50:53], v[156:159], v[172:175], v[50:53]
	s_waitcnt lgkmcnt(3)
	v_mfma_f32_16x16x32_bf16 v[46:49], v[134:137], v[176:179], v[46:49]
	v_mfma_f32_16x16x32_bf16 v[42:45], v[152:155], v[176:179], v[42:45]
	s_waitcnt lgkmcnt(1)
	v_mfma_f32_16x16x32_bf16 v[38:41], v[134:137], v[184:187], v[38:41]
	v_mfma_f32_16x16x32_bf16 v[34:37], v[152:155], v[184:187], v[34:37]
	v_mfma_f32_16x16x32_bf16 v[192:195], v[138:141], v[74:77], v[62:65]
	v_mfma_f32_16x16x32_bf16 v[232:235], v[156:159], v[74:77], v[58:61]
	v_mfma_f32_16x16x32_bf16 v[236:239], v[138:141], v[180:183], v[46:49]
	v_mfma_f32_16x16x32_bf16 v[240:243], v[156:159], v[180:183], v[42:45]
	s_waitcnt lgkmcnt(0)
	v_mfma_f32_16x16x32_bf16 v[134:137], v[138:141], v[188:191], v[38:41]
	v_mfma_f32_16x16x32_bf16 v[138:141], v[156:159], v[188:191], v[34:37]
	s_setprio 0
	s_setprio 1
	v_mfma_f32_16x16x32_bf16 v[30:33], v[102:105], v[66:69], v[30:33]
	v_mfma_f32_16x16x32_bf16 v[26:29], v[118:121], v[66:69], v[26:29]
	v_mfma_f32_16x16x32_bf16 v[14:17], v[102:105], v[176:179], v[14:17]
	v_mfma_f32_16x16x32_bf16 v[10:13], v[118:121], v[176:179], v[10:13]
	v_mfma_f32_16x16x32_bf16 v[30:33], v[110:113], v[74:77], v[30:33]
	v_mfma_f32_16x16x32_bf16 v[26:29], v[200:203], v[74:77], v[26:29]
	v_mfma_f32_16x16x32_bf16 v[22:25], v[102:105], v[94:97], v[22:25]
	v_mfma_f32_16x16x32_bf16 v[18:21], v[118:121], v[94:97], v[18:21]
	v_mfma_f32_16x16x32_bf16 v[14:17], v[110:113], v[180:183], v[14:17]
	v_mfma_f32_16x16x32_bf16 v[10:13], v[200:203], v[180:183], v[10:13]
	v_mfma_f32_16x16x32_bf16 v[6:9], v[102:105], v[184:187], v[6:9]
	v_mfma_f32_16x16x32_bf16 v[2:5], v[118:121], v[184:187], v[2:5]
	v_mfma_f32_16x16x32_bf16 v[152:155], v[110:113], v[172:175], v[22:25]
	v_mfma_f32_16x16x32_bf16 v[156:159], v[200:203], v[172:175], v[18:21]
	v_mfma_f32_16x16x32_bf16 v[172:175], v[110:113], v[188:191], v[6:9]
	v_mfma_f32_16x16x32_bf16 v[176:179], v[200:203], v[188:191], v[2:5]
	s_setprio 0
	s_barrier
	s_nop 1
	ds_read_b128 v[2:5], v151 offset:32768
	ds_read_b128 v[6:9], v151 offset:33792
	ds_read_b128 v[180:183], v151 offset:34816
	ds_read_b128 v[184:187], v151 offset:35840
	ds_read_b128 v[18:21], v0 offset:32768
	ds_read_b128 v[22:25], v0 offset:33792
	ds_read_b128 v[38:41], v0 offset:34816
	ds_read_b128 v[46:49], v0 offset:35840
	ds_read_b128 v[58:61], v0 offset:36864
	ds_read_b128 v[66:69], v0 offset:37888
	ds_read_b128 v[188:191], v0 offset:38912
	ds_read_b128 v[200:203], v0 offset:39936
	s_waitcnt vmcnt(2)
	s_barrier
	s_waitcnt lgkmcnt(0)
	s_setprio 1
	s_waitcnt lgkmcnt(7)
	v_mfma_f32_16x16x32_bf16 v[34:37], v[2:5], v[18:21], v[126:129]
	s_waitcnt lgkmcnt(6)
	v_mfma_f32_16x16x32_bf16 v[118:121], v[6:9], v[22:25], v[34:37]
	v_mfma_f32_16x16x32_bf16 v[34:37], v[180:183], v[18:21], v[122:125]
	v_mfma_f32_16x16x32_bf16 v[110:113], v[184:187], v[22:25], v[34:37]
	s_waitcnt lgkmcnt(5)
	v_mfma_f32_16x16x32_bf16 v[34:37], v[2:5], v[38:41], v[130:133]
	s_waitcnt lgkmcnt(4)
	v_mfma_f32_16x16x32_bf16 v[102:105], v[6:9], v[46:49], v[34:37]
	v_mfma_f32_16x16x32_bf16 v[34:37], v[180:183], v[38:41], v[114:117]
	v_mfma_f32_16x16x32_bf16 v[94:97], v[184:187], v[46:49], v[34:37]
	s_waitcnt lgkmcnt(3)
	v_mfma_f32_16x16x32_bf16 v[34:37], v[2:5], v[58:61], v[160:163]
	s_waitcnt lgkmcnt(2)
	v_mfma_f32_16x16x32_bf16 v[74:77], v[6:9], v[66:69], v[34:37]
	v_mfma_f32_16x16x32_bf16 v[34:37], v[180:183], v[58:61], v[106:109]
	v_mfma_f32_16x16x32_bf16 v[62:65], v[184:187], v[66:69], v[34:37]
	s_waitcnt lgkmcnt(1)
	v_mfma_f32_16x16x32_bf16 v[34:37], v[2:5], v[188:191], v[196:199]
	s_waitcnt lgkmcnt(0)
	v_mfma_f32_16x16x32_bf16 v[42:45], v[6:9], v[200:203], v[34:37]
	v_mfma_f32_16x16x32_bf16 v[34:37], v[180:183], v[188:191], v[98:101]
	v_mfma_f32_16x16x32_bf16 v[34:37], v[184:187], v[200:203], v[34:37]
	s_setprio 0
	s_barrier
	ds_read_b128 v[130:133], v151 offset:49152
	ds_read_b128 v[160:163], v151 offset:50176
	ds_read_b128 v[196:199], v151 offset:51200
	ds_read_b128 v[148:151], v151 offset:52224
	s_waitcnt vmcnt(0)
	s_barrier
	s_waitcnt lgkmcnt(0)
	s_setprio 1
	s_waitcnt lgkmcnt(3)
	v_mfma_f32_16x16x32_bf16 v[98:101], v[130:133], v[18:21], v[222:225]
	s_waitcnt lgkmcnt(1)
	v_mfma_f32_16x16x32_bf16 v[18:21], v[196:199], v[18:21], v[90:93]
	s_waitcnt lgkmcnt(0)
	v_mfma_f32_16x16x32_bf16 v[122:125], v[148:151], v[22:25], v[18:21]
	v_mfma_f32_16x16x32_bf16 v[18:21], v[130:133], v[38:41], v[86:89]
	v_mfma_f32_16x16x32_bf16 v[114:117], v[160:163], v[46:49], v[18:21]
	v_mfma_f32_16x16x32_bf16 v[18:21], v[196:199], v[38:41], v[82:85]
	v_mfma_f32_16x16x32_bf16 v[106:109], v[148:151], v[46:49], v[18:21]
	v_mfma_f32_16x16x32_bf16 v[18:21], v[130:133], v[58:61], v[78:81]
	v_mfma_f32_16x16x32_bf16 v[126:129], v[160:163], v[22:25], v[98:101]
	v_mfma_f32_16x16x32_bf16 v[98:101], v[160:163], v[66:69], v[18:21]
	v_mfma_f32_16x16x32_bf16 v[18:21], v[196:199], v[58:61], v[164:167]
	v_mfma_f32_16x16x32_bf16 v[90:93], v[148:151], v[66:69], v[18:21]
	v_mfma_f32_16x16x32_bf16 v[18:21], v[130:133], v[188:191], v[70:73]
	v_mfma_f32_16x16x32_bf16 v[66:69], v[160:163], v[200:203], v[18:21]
	v_mfma_f32_16x16x32_bf16 v[18:21], v[196:199], v[188:191], v[168:171]
	v_mfma_f32_16x16x32_bf16 v[58:61], v[148:151], v[200:203], v[18:21]
	s_setprio 0
	s_barrier
	ds_read_b128 v[82:85], v0 offset:49152
	ds_read_b128 v[164:167], v0 offset:50176
	ds_read_b128 v[168:171], v0 offset:51200
	ds_read_b128 v[188:191], v0 offset:52224
	ds_read_b128 v[200:203], v0 offset:53248
	ds_read_b128 v[222:225], v0 offset:54272
	ds_read_b128 v[244:247], v0 offset:55296
	ds_read_b128 v[248:251], v0 offset:56320
	s_barrier
	s_waitcnt lgkmcnt(0)
	s_setprio 1
	s_waitcnt lgkmcnt(7)
	v_mfma_f32_16x16x32_bf16 v[18:21], v[2:5], v[82:85], v[192:195]
	s_waitcnt lgkmcnt(6)
	v_mfma_f32_16x16x32_bf16 v[78:81], v[6:9], v[164:167], v[18:21]
	v_mfma_f32_16x16x32_bf16 v[18:21], v[180:183], v[82:85], v[232:235]
	v_mfma_f32_16x16x32_bf16 v[70:73], v[184:187], v[164:167], v[18:21]
	s_waitcnt lgkmcnt(5)
	v_mfma_f32_16x16x32_bf16 v[18:21], v[2:5], v[168:171], v[54:57]
	s_waitcnt lgkmcnt(4)
	v_mfma_f32_16x16x32_bf16 v[46:49], v[6:9], v[188:191], v[18:21]
	v_mfma_f32_16x16x32_bf16 v[18:21], v[180:183], v[168:171], v[50:53]
	v_mfma_f32_16x16x32_bf16 v[38:41], v[184:187], v[188:191], v[18:21]
	s_waitcnt lgkmcnt(3)
	v_mfma_f32_16x16x32_bf16 v[18:21], v[2:5], v[200:203], v[236:239]
	s_waitcnt lgkmcnt(1)
	v_mfma_f32_16x16x32_bf16 v[2:5], v[2:5], v[244:247], v[134:137]
	v_mfma_f32_16x16x32_bf16 v[22:25], v[6:9], v[222:225], v[18:21]
	v_mfma_f32_16x16x32_bf16 v[18:21], v[180:183], v[200:203], v[240:243]
	s_waitcnt lgkmcnt(0)
	v_mfma_f32_16x16x32_bf16 v[6:9], v[6:9], v[248:251], v[2:5]
	v_mfma_f32_16x16x32_bf16 v[2:5], v[180:183], v[244:247], v[138:141]
	v_mfma_f32_16x16x32_bf16 v[18:21], v[184:187], v[222:225], v[18:21]
	v_mfma_f32_16x16x32_bf16 v[2:5], v[184:187], v[248:251], v[2:5]
	s_setprio 0
	s_setprio 1
	v_mfma_f32_16x16x32_bf16 v[26:29], v[196:199], v[82:85], v[26:29]
	v_mfma_f32_16x16x32_bf16 v[30:33], v[130:133], v[82:85], v[30:33]
	v_mfma_f32_16x16x32_bf16 v[82:85], v[148:151], v[164:167], v[26:29]
	v_mfma_f32_16x16x32_bf16 v[26:29], v[130:133], v[168:171], v[152:155]
	v_mfma_f32_16x16x32_bf16 v[54:57], v[160:163], v[188:191], v[26:29]
	v_mfma_f32_16x16x32_bf16 v[26:29], v[196:199], v[168:171], v[156:159]
	v_mfma_f32_16x16x32_bf16 v[10:13], v[196:199], v[200:203], v[10:13]
	v_mfma_f32_16x16x32_bf16 v[50:53], v[148:151], v[188:191], v[26:29]
	v_mfma_f32_16x16x32_bf16 v[14:17], v[130:133], v[200:203], v[14:17]
	v_mfma_f32_16x16x32_bf16 v[26:29], v[148:151], v[222:225], v[10:13]
	v_mfma_f32_16x16x32_bf16 v[10:13], v[130:133], v[244:247], v[172:175]
	v_mfma_f32_16x16x32_bf16 v[86:89], v[160:163], v[164:167], v[30:33]
	v_mfma_f32_16x16x32_bf16 v[30:33], v[160:163], v[222:225], v[14:17]
	v_mfma_f32_16x16x32_bf16 v[14:17], v[160:163], v[248:251], v[10:13]
	v_mfma_f32_16x16x32_bf16 v[10:13], v[196:199], v[244:247], v[176:179]
	v_mfma_f32_16x16x32_bf16 v[10:13], v[148:151], v[248:251], v[10:13]
	s_setprio 0
	s_movk_i32 s0, 0x100
	v_cmp_gt_u32_e32 vcc, s0, v142
	s_barrier
	s_and_saveexec_b64 s[0:1], vcc
	s_cbranch_execz .LBB0_674
	s_barrier
	s_branch .LBB0_674

.LBB0_689:
	ds_read_b128 v[104:107], v95
	ds_read_b128 v[108:111], v95 offset:1024
	ds_read_b128 v[112:115], v95 offset:2048
	ds_read_b128 v[116:119], v95 offset:3072
	v_add_u32_e32 v101, 0xc000, v85
	v_lshl_add_u64 v[152:153], v[72:73], 0, s[10:11]
	v_lshl_add_u64 v[102:103], v[152:153], 0, s[34:35]
	s_add_i32 m0, s1, 0xc000
	ds_read_b128 v[120:123], v93
	ds_read_b128 v[124:127], v93 offset:1024
	ds_read_b128 v[128:131], v93 offset:2048
	ds_read_b128 v[132:135], v93 offset:3072
	ds_read_b128 v[136:139], v93 offset:4096
	ds_read_b128 v[140:143], v93 offset:5120
	ds_read_b128 v[144:147], v93 offset:6144
	ds_read_b128 v[148:151], v93 offset:7168
	global_load_lds_dwordx4 v[102:103], off
	v_add_u32_e32 v102, 0xe000, v85
	v_lshl_add_u64 v[154:155], v[74:75], 0, s[10:11]
	v_lshl_add_u64 v[156:157], v[154:155], 0, s[34:35]
	s_add_i32 m0, s1, 0xe000
	s_nop 0
	global_load_lds_dwordx4 v[156:157], off
	s_waitcnt lgkmcnt(8)
	s_barrier
	s_waitcnt lgkmcnt(0)
	s_setprio 1
	s_waitcnt lgkmcnt(0)
	v_mfma_f32_16x16x32_bf16 v[62:65], v[104:107], v[120:123], v[62:65]
	v_mfma_f32_16x16x32_bf16 v[58:61], v[112:115], v[120:123], v[58:61]
	v_mfma_f32_16x16x32_bf16 v[54:57], v[104:107], v[128:131], v[54:57]
	v_mfma_f32_16x16x32_bf16 v[50:53], v[112:115], v[128:131], v[50:53]
	v_mfma_f32_16x16x32_bf16 v[46:49], v[104:107], v[136:139], v[46:49]
	v_mfma_f32_16x16x32_bf16 v[42:45], v[112:115], v[136:139], v[42:45]
	v_mfma_f32_16x16x32_bf16 v[38:41], v[104:107], v[144:147], v[38:41]
	v_mfma_f32_16x16x32_bf16 v[34:37], v[112:115], v[144:147], v[34:37]
	v_mfma_f32_16x16x32_bf16 v[62:65], v[108:111], v[124:127], v[62:65]
	v_mfma_f32_16x16x32_bf16 v[58:61], v[116:119], v[124:127], v[58:61]
	v_mfma_f32_16x16x32_bf16 v[54:57], v[108:111], v[132:135], v[54:57]
	v_mfma_f32_16x16x32_bf16 v[50:53], v[116:119], v[132:135], v[50:53]
	v_mfma_f32_16x16x32_bf16 v[46:49], v[108:111], v[140:143], v[46:49]
	v_mfma_f32_16x16x32_bf16 v[42:45], v[116:119], v[140:143], v[42:45]
	v_mfma_f32_16x16x32_bf16 v[38:41], v[108:111], v[148:151], v[38:41]
	v_mfma_f32_16x16x32_bf16 v[34:37], v[116:119], v[148:151], v[34:37]
	s_setprio 0
	s_barrier
	v_lshl_add_u64 v[156:157], v[68:69], 0, s[10:11]
	v_lshl_add_u64 v[120:121], v[156:157], 0, s[74:75]
	s_add_i32 m0, s1, 0x10000
	v_lshl_add_u64 v[158:159], v[70:71], 0, s[10:11]
	global_load_lds_dwordx4 v[120:121], off
	v_lshl_add_u64 v[120:121], v[158:159], 0, s[74:75]
	s_add_i32 m0, s1, 0x12000
	s_nop 0
	global_load_lds_dwordx4 v[120:121], off
	v_lshl_add_u64 v[160:161], v[152:153], 0, s[74:75]
	s_mov_b32 m0, s1
	s_barrier
	s_waitcnt lgkmcnt(0)
	s_barrier
	ds_read_b128 v[120:123], v93 offset:16384
	ds_read_b128 v[124:127], v93 offset:17408
	ds_read_b128 v[128:131], v93 offset:18432
	ds_read_b128 v[132:135], v93 offset:19456
	ds_read_b128 v[136:139], v93 offset:20480
	ds_read_b128 v[140:143], v93 offset:21504
	ds_read_b128 v[144:147], v93 offset:22528
	ds_read_b128 v[148:151], v93 offset:23552
	global_load_lds_dwordx4 v[160:161], off
	v_lshl_add_u64 v[160:161], v[154:155], 0, s[74:75]
	s_add_i32 m0, s1, 0x2000
	s_nop 0
	global_load_lds_dwordx4 v[160:161], off
	s_barrier
	s_waitcnt lgkmcnt(0)
	s_setprio 1
	s_waitcnt lgkmcnt(0)
	v_mfma_f32_16x16x32_bf16 v[2:5], v[104:107], v[120:123], v[2:5]
	v_mfma_f32_16x16x32_bf16 v[6:9], v[112:115], v[120:123], v[6:9]
	v_mfma_f32_16x16x32_bf16 v[10:13], v[104:107], v[128:131], v[10:13]
	v_mfma_f32_16x16x32_bf16 v[14:17], v[112:115], v[128:131], v[14:17]
	v_mfma_f32_16x16x32_bf16 v[18:21], v[104:107], v[136:139], v[18:21]
	v_mfma_f32_16x16x32_bf16 v[22:25], v[112:115], v[136:139], v[22:25]
	v_mfma_f32_16x16x32_bf16 v[26:29], v[104:107], v[144:147], v[26:29]
	v_mfma_f32_16x16x32_bf16 v[30:33], v[112:115], v[144:147], v[30:33]
	v_mfma_f32_16x16x32_bf16 v[2:5], v[108:111], v[124:127], v[2:5]
	v_mfma_f32_16x16x32_bf16 v[6:9], v[116:119], v[124:127], v[6:9]
	v_mfma_f32_16x16x32_bf16 v[10:13], v[108:111], v[132:135], v[10:13]
	v_mfma_f32_16x16x32_bf16 v[14:17], v[116:119], v[132:135], v[14:17]
	v_mfma_f32_16x16x32_bf16 v[18:21], v[108:111], v[140:143], v[18:21]
	v_mfma_f32_16x16x32_bf16 v[22:25], v[116:119], v[140:143], v[22:25]
	v_mfma_f32_16x16x32_bf16 v[26:29], v[108:111], v[148:151], v[26:29]
	v_mfma_f32_16x16x32_bf16 v[30:33], v[116:119], v[148:151], v[30:33]
	s_setprio 0
	s_barrier
	v_lshl_add_u64 v[160:161], v[76:77], 0, s[10:11]
	v_lshl_add_u64 v[104:105], v[160:161], 0, s[74:75]
	s_add_i32 m0, s1, 0x14000
	v_lshl_add_u64 v[162:163], v[78:79], 0, s[10:11]
	global_load_lds_dwordx4 v[104:105], off
	v_lshl_add_u64 v[104:105], v[162:163], 0, s[74:75]
	s_add_i32 m0, s1, 0x16000
	s_nop 0
	global_load_lds_dwordx4 v[104:105], off
	s_waitcnt vmcnt(6)
	s_barrier
	s_barrier
	ds_read_b128 v[104:107], v95 offset:32768
	ds_read_b128 v[108:111], v95 offset:33792
	ds_read_b128 v[112:115], v95 offset:34816
	ds_read_b128 v[116:119], v95 offset:35840
	v_lshl_add_u64 v[164:165], v[152:153], 0, s[78:79]
	s_add_i32 m0, s1, 0x4000
	ds_read_b128 v[120:123], v93 offset:32768
	ds_read_b128 v[124:127], v93 offset:33792
	ds_read_b128 v[128:131], v93 offset:34816
	ds_read_b128 v[132:135], v93 offset:35840
	ds_read_b128 v[136:139], v93 offset:36864
	ds_read_b128 v[140:143], v93 offset:37888
	ds_read_b128 v[144:147], v93 offset:38912
	ds_read_b128 v[148:151], v93 offset:39936
	global_load_lds_dwordx4 v[164:165], off
	v_lshl_add_u64 v[164:165], v[154:155], 0, s[78:79]
	s_add_i32 m0, s1, 0x6000
	s_nop 0
	global_load_lds_dwordx4 v[164:165], off
	s_waitcnt lgkmcnt(8)
	s_barrier
	s_waitcnt lgkmcnt(0)
	s_setprio 1
	s_waitcnt lgkmcnt(0)
	v_mfma_f32_16x16x32_bf16 v[62:65], v[104:107], v[120:123], v[62:65]
	v_mfma_f32_16x16x32_bf16 v[58:61], v[112:115], v[120:123], v[58:61]
	v_mfma_f32_16x16x32_bf16 v[54:57], v[104:107], v[128:131], v[54:57]
	v_mfma_f32_16x16x32_bf16 v[50:53], v[112:115], v[128:131], v[50:53]
	v_mfma_f32_16x16x32_bf16 v[46:49], v[104:107], v[136:139], v[46:49]
	v_mfma_f32_16x16x32_bf16 v[42:45], v[112:115], v[136:139], v[42:45]
	v_mfma_f32_16x16x32_bf16 v[38:41], v[104:107], v[144:147], v[38:41]
	v_mfma_f32_16x16x32_bf16 v[34:37], v[112:115], v[144:147], v[34:37]
	v_mfma_f32_16x16x32_bf16 v[62:65], v[108:111], v[124:127], v[62:65]
	v_mfma_f32_16x16x32_bf16 v[58:61], v[116:119], v[124:127], v[58:61]
	v_mfma_f32_16x16x32_bf16 v[54:57], v[108:111], v[132:135], v[54:57]
	v_mfma_f32_16x16x32_bf16 v[50:53], v[116:119], v[132:135], v[50:53]
	v_mfma_f32_16x16x32_bf16 v[46:49], v[108:111], v[140:143], v[46:49]
	v_mfma_f32_16x16x32_bf16 v[42:45], v[116:119], v[140:143], v[42:45]
	v_mfma_f32_16x16x32_bf16 v[38:41], v[108:111], v[148:151], v[38:41]
	v_mfma_f32_16x16x32_bf16 v[34:37], v[116:119], v[148:151], v[34:37]
	s_setprio 0
	s_barrier
	v_lshl_add_u64 v[120:121], v[156:157], 0, s[28:29]
	s_add_i32 m0, s1, 0x18000
	s_nop 0
	global_load_lds_dwordx4 v[120:121], off
	v_lshl_add_u64 v[120:121], v[158:159], 0, s[28:29]
	s_add_i32 m0, s1, 0x1a000
	s_nop 0
	global_load_lds_dwordx4 v[120:121], off
	v_lshl_add_u64 v[152:153], v[152:153], 0, s[28:29]
	s_add_i32 m0, s1, 0x8000
	s_barrier
	s_waitcnt lgkmcnt(0)
	s_barrier
	ds_read_b128 v[120:123], v93 offset:49152
	ds_read_b128 v[124:127], v93 offset:50176
	ds_read_b128 v[128:131], v93 offset:51200
	ds_read_b128 v[132:135], v93 offset:52224
	ds_read_b128 v[136:139], v93 offset:53248
	ds_read_b128 v[140:143], v93 offset:54272
	ds_read_b128 v[144:147], v93 offset:55296
	ds_read_b128 v[148:151], v93 offset:56320
	global_load_lds_dwordx4 v[152:153], off
	v_lshl_add_u64 v[152:153], v[154:155], 0, s[28:29]
	s_add_i32 m0, s1, 0xa000
	s_nop 0
	global_load_lds_dwordx4 v[152:153], off
	s_barrier
	s_waitcnt lgkmcnt(0)
	s_setprio 1
	s_waitcnt lgkmcnt(0)
	v_mfma_f32_16x16x32_bf16 v[2:5], v[104:107], v[120:123], v[2:5]
	v_mfma_f32_16x16x32_bf16 v[6:9], v[112:115], v[120:123], v[6:9]
	v_mfma_f32_16x16x32_bf16 v[10:13], v[104:107], v[128:131], v[10:13]
	v_mfma_f32_16x16x32_bf16 v[14:17], v[112:115], v[128:131], v[14:17]
	v_mfma_f32_16x16x32_bf16 v[18:21], v[104:107], v[136:139], v[18:21]
	v_mfma_f32_16x16x32_bf16 v[22:25], v[112:115], v[136:139], v[22:25]
	v_mfma_f32_16x16x32_bf16 v[26:29], v[104:107], v[144:147], v[26:29]
	v_mfma_f32_16x16x32_bf16 v[30:33], v[112:115], v[144:147], v[30:33]
	v_mfma_f32_16x16x32_bf16 v[2:5], v[108:111], v[124:127], v[2:5]
	v_mfma_f32_16x16x32_bf16 v[6:9], v[116:119], v[124:127], v[6:9]
	v_mfma_f32_16x16x32_bf16 v[10:13], v[108:111], v[132:135], v[10:13]
	v_mfma_f32_16x16x32_bf16 v[14:17], v[116:119], v[132:135], v[14:17]
	v_mfma_f32_16x16x32_bf16 v[18:21], v[108:111], v[140:143], v[18:21]
	v_mfma_f32_16x16x32_bf16 v[22:25], v[116:119], v[140:143], v[22:25]
	v_mfma_f32_16x16x32_bf16 v[26:29], v[108:111], v[148:151], v[26:29]
	v_mfma_f32_16x16x32_bf16 v[30:33], v[116:119], v[148:151], v[30:33]
	s_setprio 0
	s_barrier
	v_lshl_add_u64 v[104:105], v[160:161], 0, s[28:29]
	s_add_i32 m0, s1, 0x1c000
	s_nop 0
	global_load_lds_dwordx4 v[104:105], off
	v_lshl_add_u64 v[104:105], v[162:163], 0, s[28:29]
	s_add_i32 m0, s1, 0x1e000
	s_add_i32 s0, s0, 2
	global_load_lds_dwordx4 v[104:105], off
	s_waitcnt vmcnt(6)
	s_add_u32 s10, s10, 0x100
	s_addc_u32 s11, s11, 0
	s_cmpk_lt_u32 s0, 0x54
	s_barrier
	s_barrier
	s_cbranch_scc1 .LBB0_689
	s_add_i32 s1, s1, 0x1e000
	s_add_u32 s0, s8, 0x2b80
	s_addc_u32 s1, s9, 0
	v_readfirstlane_b32 s8, v101
	v_lshl_add_u64 v[90:91], s[0:1], 0, v[0:1]
	s_mov_b32 m0, s8
	v_lshl_add_u64 v[66:67], s[0:1], 0, v[66:67]
	v_readfirstlane_b32 s0, v102
	ds_read_b128 v[68:71], v95
	ds_read_b128 v[72:75], v95 offset:1024
	ds_read_b128 v[76:79], v95 offset:2048
	ds_read_b128 v[86:89], v95 offset:3072
	ds_read_b128 v[96:99], v93
	ds_read_b128 v[104:107], v93 offset:1024
	ds_read_b128 v[108:111], v93 offset:2048
	ds_read_b128 v[112:115], v93 offset:3072
	ds_read_b128 v[116:119], v93 offset:4096
	ds_read_b128 v[120:123], v93 offset:5120
	ds_read_b128 v[124:127], v93 offset:6144
	ds_read_b128 v[128:131], v93 offset:7168
	global_load_lds_dwordx4 v[90:91], off
	s_mov_b32 m0, s0
	s_nop 0
	global_load_lds_dwordx4 v[66:67], off
	s_barrier
	s_waitcnt lgkmcnt(0)
	s_setprio 1
	s_waitcnt lgkmcnt(0)
	v_mfma_f32_16x16x32_bf16 v[62:65], v[68:71], v[96:99], v[62:65]
	v_mfma_f32_16x16x32_bf16 v[58:61], v[76:79], v[96:99], v[58:61]
	v_mfma_f32_16x16x32_bf16 v[54:57], v[68:71], v[108:111], v[54:57]
	v_mfma_f32_16x16x32_bf16 v[50:53], v[76:79], v[108:111], v[50:53]
	v_mfma_f32_16x16x32_bf16 v[46:49], v[68:71], v[116:119], v[46:49]
	v_mfma_f32_16x16x32_bf16 v[42:45], v[76:79], v[116:119], v[42:45]
	v_mfma_f32_16x16x32_bf16 v[38:41], v[68:71], v[124:127], v[38:41]
	v_mfma_f32_16x16x32_bf16 v[34:37], v[76:79], v[124:127], v[34:37]
	v_mfma_f32_16x16x32_bf16 v[62:65], v[72:75], v[104:107], v[62:65]
	v_mfma_f32_16x16x32_bf16 v[58:61], v[86:89], v[104:107], v[58:61]
	v_mfma_f32_16x16x32_bf16 v[54:57], v[72:75], v[112:115], v[54:57]
	v_mfma_f32_16x16x32_bf16 v[50:53], v[86:89], v[112:115], v[50:53]
	v_mfma_f32_16x16x32_bf16 v[46:49], v[72:75], v[120:123], v[46:49]
	v_mfma_f32_16x16x32_bf16 v[42:45], v[86:89], v[120:123], v[42:45]
	v_mfma_f32_16x16x32_bf16 v[38:41], v[72:75], v[128:131], v[38:41]
	v_mfma_f32_16x16x32_bf16 v[34:37], v[86:89], v[128:131], v[34:37]
	s_setprio 0
	s_barrier
	s_barrier
	s_waitcnt lgkmcnt(0)
	s_barrier
	ds_read_b128 v[96:99], v93 offset:16384
	ds_read_b128 v[100:103], v93 offset:17408
	ds_read_b128 v[104:107], v93 offset:18432
	ds_read_b128 v[108:111], v93 offset:19456
	ds_read_b128 v[112:115], v93 offset:20480
	ds_read_b128 v[116:119], v93 offset:21504
	ds_read_b128 v[120:123], v93 offset:22528
	ds_read_b128 v[124:127], v93 offset:23552
	s_waitcnt vmcnt(4)
	s_barrier
	s_waitcnt lgkmcnt(0)
	s_setprio 1
	s_waitcnt lgkmcnt(3)
	v_mfma_f32_16x16x32_bf16 v[18:21], v[68:71], v[112:115], v[18:21]
	v_mfma_f32_16x16x32_bf16 v[2:5], v[68:71], v[96:99], v[2:5]
	v_mfma_f32_16x16x32_bf16 v[6:9], v[76:79], v[96:99], v[6:9]
	s_waitcnt lgkmcnt(2)
	v_mfma_f32_16x16x32_bf16 v[96:99], v[72:75], v[116:119], v[18:21]
	v_mfma_f32_16x16x32_bf16 v[18:21], v[76:79], v[112:115], v[22:25]
	v_mfma_f32_16x16x32_bf16 v[2:5], v[72:75], v[100:103], v[2:5]
	v_mfma_f32_16x16x32_bf16 v[6:9], v[86:89], v[100:103], v[6:9]
	v_mfma_f32_16x16x32_bf16 v[10:13], v[68:71], v[104:107], v[10:13]
	v_mfma_f32_16x16x32_bf16 v[14:17], v[76:79], v[104:107], v[14:17]
	v_mfma_f32_16x16x32_bf16 v[100:103], v[86:89], v[116:119], v[18:21]
	s_waitcnt lgkmcnt(1)
	v_mfma_f32_16x16x32_bf16 v[18:21], v[68:71], v[120:123], v[26:29]
	v_mfma_f32_16x16x32_bf16 v[10:13], v[72:75], v[108:111], v[10:13]
	v_mfma_f32_16x16x32_bf16 v[14:17], v[86:89], v[108:111], v[14:17]
	s_waitcnt lgkmcnt(0)
	v_mfma_f32_16x16x32_bf16 v[66:69], v[72:75], v[124:127], v[18:21]
	v_mfma_f32_16x16x32_bf16 v[18:21], v[76:79], v[120:123], v[30:33]
	v_mfma_f32_16x16x32_bf16 v[70:73], v[86:89], v[124:127], v[18:21]
	s_setprio 0
	s_barrier
	ds_read_b128 v[74:77], v95 offset:32768
	ds_read_b128 v[86:89], v95 offset:33792
	ds_read_b128 v[104:107], v95 offset:34816
	ds_read_b128 v[108:111], v95 offset:35840
	s_nop 0
	ds_read_b128 v[18:21], v93 offset:32768
	ds_read_b128 v[22:25], v93 offset:33792
	ds_read_b128 v[26:29], v93 offset:34816
	ds_read_b128 v[30:33], v93 offset:35840
	ds_read_b128 v[112:115], v93 offset:36864
	ds_read_b128 v[116:119], v93 offset:37888
	ds_read_b128 v[120:123], v93 offset:38912
	ds_read_b128 v[124:127], v93 offset:39936
	s_waitcnt vmcnt(2)
	s_barrier
	s_waitcnt lgkmcnt(0)
	s_setprio 1
	s_waitcnt lgkmcnt(7)
	v_mfma_f32_16x16x32_bf16 v[62:65], v[74:77], v[18:21], v[62:65]
	v_mfma_f32_16x16x32_bf16 v[18:21], v[104:107], v[18:21], v[58:61]
	s_waitcnt lgkmcnt(6)
	v_mfma_f32_16x16x32_bf16 v[58:61], v[108:111], v[22:25], v[18:21]
	s_waitcnt lgkmcnt(5)
	v_mfma_f32_16x16x32_bf16 v[18:21], v[74:77], v[26:29], v[54:57]
	s_waitcnt lgkmcnt(4)
	v_mfma_f32_16x16x32_bf16 v[54:57], v[86:89], v[30:33], v[18:21]
	v_mfma_f32_16x16x32_bf16 v[18:21], v[104:107], v[26:29], v[50:53]
	v_mfma_f32_16x16x32_bf16 v[50:53], v[108:111], v[30:33], v[18:21]
	s_waitcnt lgkmcnt(3)
	v_mfma_f32_16x16x32_bf16 v[18:21], v[74:77], v[112:115], v[46:49]
	s_waitcnt lgkmcnt(2)
	v_mfma_f32_16x16x32_bf16 v[46:49], v[86:89], v[116:119], v[18:21]
	v_mfma_f32_16x16x32_bf16 v[18:21], v[104:107], v[112:115], v[42:45]
	v_mfma_f32_16x16x32_bf16 v[42:45], v[108:111], v[116:119], v[18:21]
	s_waitcnt lgkmcnt(1)
	v_mfma_f32_16x16x32_bf16 v[18:21], v[74:77], v[120:123], v[38:41]
	s_waitcnt lgkmcnt(0)
	v_mfma_f32_16x16x32_bf16 v[38:41], v[86:89], v[124:127], v[18:21]
	v_mfma_f32_16x16x32_bf16 v[18:21], v[104:107], v[120:123], v[34:37]
	v_mfma_f32_16x16x32_bf16 v[62:65], v[86:89], v[22:25], v[62:65]
	v_mfma_f32_16x16x32_bf16 v[34:37], v[108:111], v[124:127], v[18:21]
	s_setprio 0
	s_barrier
	s_waitcnt vmcnt(0)
	s_barrier
	s_waitcnt lgkmcnt(0)
	s_barrier
	s_nop 1
	ds_read_b128 v[18:21], v93 offset:49152
	ds_read_b128 v[22:25], v93 offset:50176
	ds_read_b128 v[112:115], v93 offset:51200
	ds_read_b128 v[116:119], v93 offset:52224
	ds_read_b128 v[120:123], v93 offset:53248
	ds_read_b128 v[124:127], v93 offset:54272
	ds_read_b128 v[128:131], v93 offset:55296
	ds_read_b128 v[90:93], v93 offset:56320
	s_barrier
	s_waitcnt lgkmcnt(0)
	s_setprio 1
	s_waitcnt lgkmcnt(7)
	v_mfma_f32_16x16x32_bf16 v[2:5], v[74:77], v[18:21], v[2:5]
	s_waitcnt lgkmcnt(6)
	v_mfma_f32_16x16x32_bf16 v[30:33], v[86:89], v[22:25], v[2:5]
	v_mfma_f32_16x16x32_bf16 v[2:5], v[104:107], v[18:21], v[6:9]
	v_mfma_f32_16x16x32_bf16 v[26:29], v[108:111], v[22:25], v[2:5]
	s_waitcnt lgkmcnt(5)
	v_mfma_f32_16x16x32_bf16 v[2:5], v[74:77], v[112:115], v[10:13]
	s_waitcnt lgkmcnt(4)
	v_mfma_f32_16x16x32_bf16 v[22:25], v[86:89], v[116:119], v[2:5]
	v_mfma_f32_16x16x32_bf16 v[2:5], v[104:107], v[112:115], v[14:17]
	v_mfma_f32_16x16x32_bf16 v[18:21], v[108:111], v[116:119], v[2:5]
	s_waitcnt lgkmcnt(3)
	v_mfma_f32_16x16x32_bf16 v[2:5], v[74:77], v[120:123], v[96:99]
	s_waitcnt lgkmcnt(2)
	v_mfma_f32_16x16x32_bf16 v[14:17], v[86:89], v[124:127], v[2:5]
	v_mfma_f32_16x16x32_bf16 v[2:5], v[104:107], v[120:123], v[100:103]
	v_mfma_f32_16x16x32_bf16 v[10:13], v[108:111], v[124:127], v[2:5]
	s_waitcnt lgkmcnt(1)
	v_mfma_f32_16x16x32_bf16 v[2:5], v[74:77], v[128:131], v[66:69]
	s_waitcnt lgkmcnt(0)
	v_mfma_f32_16x16x32_bf16 v[6:9], v[86:89], v[90:93], v[2:5]
	v_mfma_f32_16x16x32_bf16 v[2:5], v[104:107], v[128:131], v[70:73]
	v_mfma_f32_16x16x32_bf16 v[2:5], v[108:111], v[90:93], v[2:5]
	s_setprio 0
	s_movk_i32 s0, 0x100
	v_cmp_gt_u32_e32 vcc, s0, v80
	s_barrier
	s_and_saveexec_b64 s[0:1], vcc
	s_cbranch_execz .LBB0_692
	s_barrier

.LBB0_761:
	ds_read_b128 v[164:167], v148
	ds_read_b128 v[168:171], v148 offset:1024
	ds_read_b128 v[172:175], v148 offset:2048
	ds_read_b128 v[176:179], v148 offset:3072
	v_add_u32_e32 v161, 0xc000, v145
	v_lshl_add_u64 v[204:205], v[136:137], 0, s[10:11]
	v_lshl_add_u64 v[228:229], v[204:205], 0, s[34:35]
	s_add_i32 m0, s1, 0xc000
	ds_read_b128 v[180:183], v147
	ds_read_b128 v[184:187], v147 offset:1024
	ds_read_b128 v[188:191], v147 offset:2048
	ds_read_b128 v[192:195], v147 offset:3072
	ds_read_b128 v[196:199], v147 offset:4096
	ds_read_b128 v[200:203], v147 offset:5120
	ds_read_b128 v[222:225], v147 offset:6144
	ds_read_b128 v[232:235], v147 offset:7168
	global_load_lds_dwordx4 v[228:229], off
	v_add_u32_e32 v162, 0xe000, v145
	v_lshl_add_u64 v[210:211], v[138:139], 0, s[10:11]
	v_lshl_add_u64 v[152:153], v[210:211], 0, s[34:35]
	s_add_i32 m0, s1, 0xe000
	s_nop 0
	global_load_lds_dwordx4 v[152:153], off
	s_waitcnt lgkmcnt(8)
	s_barrier
	s_waitcnt lgkmcnt(0)
	s_setprio 1
	s_waitcnt lgkmcnt(0)
	v_mfma_f32_16x16x32_bf16 v[126:129], v[164:167], v[180:183], v[126:129]
	v_mfma_f32_16x16x32_bf16 v[122:125], v[172:175], v[180:183], v[122:125]
	v_mfma_f32_16x16x32_bf16 v[118:121], v[164:167], v[188:191], v[118:121]
	v_mfma_f32_16x16x32_bf16 v[114:117], v[172:175], v[188:191], v[114:117]
	v_mfma_f32_16x16x32_bf16 v[110:113], v[164:167], v[196:199], v[110:113]
	v_mfma_f32_16x16x32_bf16 v[106:109], v[172:175], v[196:199], v[106:109]
	v_mfma_f32_16x16x32_bf16 v[102:105], v[164:167], v[222:225], v[102:105]
	v_mfma_f32_16x16x32_bf16 v[98:101], v[172:175], v[222:225], v[98:101]
	v_mfma_f32_16x16x32_bf16 v[126:129], v[168:171], v[184:187], v[126:129]
	v_mfma_f32_16x16x32_bf16 v[122:125], v[176:179], v[184:187], v[122:125]
	v_mfma_f32_16x16x32_bf16 v[118:121], v[168:171], v[192:195], v[118:121]
	v_mfma_f32_16x16x32_bf16 v[114:117], v[176:179], v[192:195], v[114:117]
	v_mfma_f32_16x16x32_bf16 v[110:113], v[168:171], v[200:203], v[110:113]
	v_mfma_f32_16x16x32_bf16 v[106:109], v[176:179], v[200:203], v[106:109]
	v_mfma_f32_16x16x32_bf16 v[102:105], v[168:171], v[232:235], v[102:105]
	v_mfma_f32_16x16x32_bf16 v[98:101], v[176:179], v[232:235], v[98:101]
	s_setprio 0
	s_barrier
	v_lshl_add_u64 v[216:217], v[132:133], 0, s[10:11]
	s_add_i32 m0, s1, 0xff00
	ds_read_b128 v[236:239], v148 offset:16384
	ds_read_b128 v[240:243], v148 offset:17408
	ds_read_b128 v[244:247], v148 offset:18432
	ds_read_b128 v[248:251], v148 offset:19456
	global_load_lds_dwordx4 v[216:217], off offset:256
	v_lshl_add_u64 v[218:219], v[134:135], 0, s[10:11]
	s_add_i32 m0, s1, 0x11f00
	s_nop 0
	global_load_lds_dwordx4 v[218:219], off offset:256
	s_barrier
	s_waitcnt lgkmcnt(0)
	s_setprio 1
	s_waitcnt lgkmcnt(0)
	v_mfma_f32_16x16x32_bf16 v[94:97], v[236:239], v[180:183], v[94:97]
	v_mfma_f32_16x16x32_bf16 v[90:93], v[244:247], v[180:183], v[90:93]
	v_mfma_f32_16x16x32_bf16 v[86:89], v[236:239], v[188:191], v[86:89]
	v_mfma_f32_16x16x32_bf16 v[82:85], v[244:247], v[188:191], v[82:85]
	v_mfma_f32_16x16x32_bf16 v[78:81], v[236:239], v[196:199], v[78:81]
	v_mfma_f32_16x16x32_bf16 v[74:77], v[244:247], v[196:199], v[74:77]
	v_mfma_f32_16x16x32_bf16 v[70:73], v[236:239], v[222:225], v[70:73]
	v_mfma_f32_16x16x32_bf16 v[66:69], v[244:247], v[222:225], v[66:69]
	v_mfma_f32_16x16x32_bf16 v[94:97], v[240:243], v[184:187], v[94:97]
	v_mfma_f32_16x16x32_bf16 v[90:93], v[248:251], v[184:187], v[90:93]
	v_mfma_f32_16x16x32_bf16 v[86:89], v[240:243], v[192:195], v[86:89]
	v_mfma_f32_16x16x32_bf16 v[82:85], v[248:251], v[192:195], v[82:85]
	v_mfma_f32_16x16x32_bf16 v[78:81], v[240:243], v[200:203], v[78:81]
	v_mfma_f32_16x16x32_bf16 v[74:77], v[248:251], v[200:203], v[74:77]
	v_mfma_f32_16x16x32_bf16 v[70:73], v[240:243], v[232:235], v[70:73]
	v_mfma_f32_16x16x32_bf16 v[66:69], v[248:251], v[232:235], v[66:69]
	s_setprio 0
	v_lshl_add_u64 v[158:159], v[204:205], 0, s[74:75]
	s_mov_b32 m0, s1
	s_barrier
	ds_read_b128 v[180:183], v147 offset:16384
	ds_read_b128 v[184:187], v147 offset:17408
	ds_read_b128 v[188:191], v147 offset:18432
	ds_read_b128 v[192:195], v147 offset:19456
	ds_read_b128 v[196:199], v147 offset:20480
	ds_read_b128 v[200:203], v147 offset:21504
	ds_read_b128 v[222:225], v147 offset:22528
	ds_read_b128 v[232:235], v147 offset:23552
	global_load_lds_dwordx4 v[158:159], off
	s_add_i32 m0, s1, 0x1f00
	s_nop 0
	global_load_lds_dwordx4 v[210:211], off offset:256
	s_barrier
	s_waitcnt lgkmcnt(0)
	s_setprio 1
	s_waitcnt lgkmcnt(0)
	v_mfma_f32_16x16x32_bf16 v[62:65], v[164:167], v[180:183], v[62:65]
	v_mfma_f32_16x16x32_bf16 v[58:61], v[172:175], v[180:183], v[58:61]
	v_mfma_f32_16x16x32_bf16 v[54:57], v[164:167], v[188:191], v[54:57]
	v_mfma_f32_16x16x32_bf16 v[50:53], v[172:175], v[188:191], v[50:53]
	v_mfma_f32_16x16x32_bf16 v[46:49], v[164:167], v[196:199], v[46:49]
	v_mfma_f32_16x16x32_bf16 v[42:45], v[172:175], v[196:199], v[42:45]
	v_mfma_f32_16x16x32_bf16 v[38:41], v[164:167], v[222:225], v[38:41]
	v_mfma_f32_16x16x32_bf16 v[34:37], v[172:175], v[222:225], v[34:37]
	v_mfma_f32_16x16x32_bf16 v[62:65], v[168:171], v[184:187], v[62:65]
	v_mfma_f32_16x16x32_bf16 v[58:61], v[176:179], v[184:187], v[58:61]
	v_mfma_f32_16x16x32_bf16 v[54:57], v[168:171], v[192:195], v[54:57]
	v_mfma_f32_16x16x32_bf16 v[50:53], v[176:179], v[192:195], v[50:53]
	v_mfma_f32_16x16x32_bf16 v[46:49], v[168:171], v[200:203], v[46:49]
	v_mfma_f32_16x16x32_bf16 v[42:45], v[176:179], v[200:203], v[42:45]
	v_mfma_f32_16x16x32_bf16 v[38:41], v[168:171], v[232:235], v[38:41]
	v_mfma_f32_16x16x32_bf16 v[34:37], v[176:179], v[232:235], v[34:37]
	s_setprio 0
	s_barrier
	v_lshl_add_u64 v[154:155], v[216:217], 0, s[78:79]
	s_add_i32 m0, s1, 0x14000
	s_nop 0
	global_load_lds_dwordx4 v[154:155], off
	v_lshl_add_u64 v[156:157], v[218:219], 0, s[78:79]
	s_add_i32 m0, s1, 0x16000
	s_nop 0
	global_load_lds_dwordx4 v[156:157], off
	s_waitcnt vmcnt(6)
	s_barrier
	s_setprio 1
	v_mfma_f32_16x16x32_bf16 v[30:33], v[236:239], v[180:183], v[30:33]
	v_mfma_f32_16x16x32_bf16 v[26:29], v[244:247], v[180:183], v[26:29]
	v_mfma_f32_16x16x32_bf16 v[22:25], v[236:239], v[188:191], v[22:25]
	v_mfma_f32_16x16x32_bf16 v[18:21], v[244:247], v[188:191], v[18:21]
	v_mfma_f32_16x16x32_bf16 v[14:17], v[236:239], v[196:199], v[14:17]
	v_mfma_f32_16x16x32_bf16 v[10:13], v[244:247], v[196:199], v[10:13]
	v_mfma_f32_16x16x32_bf16 v[6:9], v[236:239], v[222:225], v[6:9]
	v_mfma_f32_16x16x32_bf16 v[2:5], v[244:247], v[222:225], v[2:5]
	v_mfma_f32_16x16x32_bf16 v[30:33], v[240:243], v[184:187], v[30:33]
	v_mfma_f32_16x16x32_bf16 v[26:29], v[248:251], v[184:187], v[26:29]
	v_mfma_f32_16x16x32_bf16 v[22:25], v[240:243], v[192:195], v[22:25]
	v_mfma_f32_16x16x32_bf16 v[18:21], v[248:251], v[192:195], v[18:21]
	v_mfma_f32_16x16x32_bf16 v[14:17], v[240:243], v[200:203], v[14:17]
	v_mfma_f32_16x16x32_bf16 v[10:13], v[248:251], v[200:203], v[10:13]
	v_mfma_f32_16x16x32_bf16 v[6:9], v[240:243], v[232:235], v[6:9]
	v_mfma_f32_16x16x32_bf16 v[2:5], v[248:251], v[232:235], v[2:5]
	s_setprio 0
	s_barrier
	ds_read_b128 v[164:167], v148 offset:32768
	ds_read_b128 v[168:171], v148 offset:33792
	ds_read_b128 v[172:175], v148 offset:34816
	ds_read_b128 v[176:179], v148 offset:35840
	s_add_i32 m0, s1, 0x3f80
	ds_read_b128 v[180:183], v147 offset:32768
	ds_read_b128 v[184:187], v147 offset:33792
	ds_read_b128 v[188:191], v147 offset:34816
	ds_read_b128 v[192:195], v147 offset:35840
	ds_read_b128 v[196:199], v147 offset:36864
	ds_read_b128 v[200:203], v147 offset:37888
	ds_read_b128 v[222:225], v147 offset:38912
	ds_read_b128 v[232:235], v147 offset:39936
	global_load_lds_dwordx4 v[228:229], off offset:128
	s_add_i32 m0, s1, 0x5f80
	s_nop 0
	global_load_lds_dwordx4 v[152:153], off offset:128
	s_waitcnt lgkmcnt(8)
	s_barrier
	s_waitcnt lgkmcnt(0)
	s_setprio 1
	s_waitcnt lgkmcnt(0)
	v_mfma_f32_16x16x32_bf16 v[126:129], v[164:167], v[180:183], v[126:129]
	v_mfma_f32_16x16x32_bf16 v[122:125], v[172:175], v[180:183], v[122:125]
	v_mfma_f32_16x16x32_bf16 v[118:121], v[164:167], v[188:191], v[118:121]
	v_mfma_f32_16x16x32_bf16 v[114:117], v[172:175], v[188:191], v[114:117]
	v_mfma_f32_16x16x32_bf16 v[110:113], v[164:167], v[196:199], v[110:113]
	v_mfma_f32_16x16x32_bf16 v[106:109], v[172:175], v[196:199], v[106:109]
	v_mfma_f32_16x16x32_bf16 v[102:105], v[164:167], v[222:225], v[102:105]
	v_mfma_f32_16x16x32_bf16 v[98:101], v[172:175], v[222:225], v[98:101]
	v_mfma_f32_16x16x32_bf16 v[126:129], v[168:171], v[184:187], v[126:129]
	v_mfma_f32_16x16x32_bf16 v[122:125], v[176:179], v[184:187], v[122:125]
	v_mfma_f32_16x16x32_bf16 v[118:121], v[168:171], v[192:195], v[118:121]
	v_mfma_f32_16x16x32_bf16 v[114:117], v[176:179], v[192:195], v[114:117]
	v_mfma_f32_16x16x32_bf16 v[110:113], v[168:171], v[200:203], v[110:113]
	v_mfma_f32_16x16x32_bf16 v[106:109], v[176:179], v[200:203], v[106:109]
	v_mfma_f32_16x16x32_bf16 v[102:105], v[168:171], v[232:235], v[102:105]
	v_mfma_f32_16x16x32_bf16 v[98:101], v[176:179], v[232:235], v[98:101]
	s_setprio 0
	s_barrier
	s_add_i32 m0, s1, 0x17e80
	ds_read_b128 v[236:239], v148 offset:49152
	ds_read_b128 v[240:243], v148 offset:50176
	ds_read_b128 v[244:247], v148 offset:51200
	ds_read_b128 v[248:251], v148 offset:52224
	global_load_lds_dwordx4 v[216:217], off offset:384
	s_add_i32 m0, s1, 0x19e80
	s_nop 0
	global_load_lds_dwordx4 v[218:219], off offset:384
	s_barrier
	s_waitcnt lgkmcnt(0)
	s_setprio 1
	s_waitcnt lgkmcnt(0)
	v_mfma_f32_16x16x32_bf16 v[94:97], v[236:239], v[180:183], v[94:97]
	v_mfma_f32_16x16x32_bf16 v[90:93], v[244:247], v[180:183], v[90:93]
	v_mfma_f32_16x16x32_bf16 v[86:89], v[236:239], v[188:191], v[86:89]
	v_mfma_f32_16x16x32_bf16 v[82:85], v[244:247], v[188:191], v[82:85]
	v_mfma_f32_16x16x32_bf16 v[78:81], v[236:239], v[196:199], v[78:81]
	v_mfma_f32_16x16x32_bf16 v[74:77], v[244:247], v[196:199], v[74:77]
	v_mfma_f32_16x16x32_bf16 v[70:73], v[236:239], v[222:225], v[70:73]
	v_mfma_f32_16x16x32_bf16 v[66:69], v[244:247], v[222:225], v[66:69]
	v_mfma_f32_16x16x32_bf16 v[94:97], v[240:243], v[184:187], v[94:97]
	v_mfma_f32_16x16x32_bf16 v[90:93], v[248:251], v[184:187], v[90:93]
	v_mfma_f32_16x16x32_bf16 v[86:89], v[240:243], v[192:195], v[86:89]
	v_mfma_f32_16x16x32_bf16 v[82:85], v[248:251], v[192:195], v[82:85]
	v_mfma_f32_16x16x32_bf16 v[78:81], v[240:243], v[200:203], v[78:81]
	v_mfma_f32_16x16x32_bf16 v[74:77], v[248:251], v[200:203], v[74:77]
	v_mfma_f32_16x16x32_bf16 v[70:73], v[240:243], v[232:235], v[70:73]
	v_mfma_f32_16x16x32_bf16 v[66:69], v[248:251], v[232:235], v[66:69]
	s_setprio 0
	s_add_i32 m0, s1, 0x7e80
	s_barrier
	ds_read_b128 v[180:183], v147 offset:49152
	ds_read_b128 v[184:187], v147 offset:50176
	ds_read_b128 v[188:191], v147 offset:51200
	ds_read_b128 v[192:195], v147 offset:52224
	ds_read_b128 v[196:199], v147 offset:53248
	ds_read_b128 v[200:203], v147 offset:54272
	ds_read_b128 v[222:225], v147 offset:55296
	ds_read_b128 v[232:235], v147 offset:56320
	global_load_lds_dwordx4 v[204:205], off offset:384
	s_add_i32 m0, s1, 0x9e80
	s_nop 0
	global_load_lds_dwordx4 v[210:211], off offset:384
	s_barrier
	s_waitcnt lgkmcnt(0)
	s_setprio 1
	s_waitcnt lgkmcnt(0)
	v_mfma_f32_16x16x32_bf16 v[62:65], v[164:167], v[180:183], v[62:65]
	v_mfma_f32_16x16x32_bf16 v[58:61], v[172:175], v[180:183], v[58:61]
	v_mfma_f32_16x16x32_bf16 v[54:57], v[164:167], v[188:191], v[54:57]
	v_mfma_f32_16x16x32_bf16 v[50:53], v[172:175], v[188:191], v[50:53]
	v_mfma_f32_16x16x32_bf16 v[46:49], v[164:167], v[196:199], v[46:49]
	v_mfma_f32_16x16x32_bf16 v[42:45], v[172:175], v[196:199], v[42:45]
	v_mfma_f32_16x16x32_bf16 v[38:41], v[164:167], v[222:225], v[38:41]
	v_mfma_f32_16x16x32_bf16 v[34:37], v[172:175], v[222:225], v[34:37]
	v_mfma_f32_16x16x32_bf16 v[62:65], v[168:171], v[184:187], v[62:65]
	v_mfma_f32_16x16x32_bf16 v[58:61], v[176:179], v[184:187], v[58:61]
	v_mfma_f32_16x16x32_bf16 v[54:57], v[168:171], v[192:195], v[54:57]
	v_mfma_f32_16x16x32_bf16 v[50:53], v[176:179], v[192:195], v[50:53]
	v_mfma_f32_16x16x32_bf16 v[46:49], v[168:171], v[200:203], v[46:49]
	v_mfma_f32_16x16x32_bf16 v[42:45], v[176:179], v[200:203], v[42:45]
	v_mfma_f32_16x16x32_bf16 v[38:41], v[168:171], v[232:235], v[38:41]
	v_mfma_f32_16x16x32_bf16 v[34:37], v[176:179], v[232:235], v[34:37]
	s_setprio 0
	s_barrier
	s_add_i32 m0, s1, 0x1bf80
	s_nop 0
	global_load_lds_dwordx4 v[154:155], off offset:128
	s_add_i32 m0, s1, 0x1df80
	s_nop 0
	global_load_lds_dwordx4 v[156:157], off offset:128
	s_waitcnt vmcnt(6)
	s_barrier
	s_setprio 1
	v_mfma_f32_16x16x32_bf16 v[30:33], v[236:239], v[180:183], v[30:33]
	v_mfma_f32_16x16x32_bf16 v[26:29], v[244:247], v[180:183], v[26:29]
	v_mfma_f32_16x16x32_bf16 v[22:25], v[236:239], v[188:191], v[22:25]
	v_mfma_f32_16x16x32_bf16 v[18:21], v[244:247], v[188:191], v[18:21]
	v_mfma_f32_16x16x32_bf16 v[14:17], v[236:239], v[196:199], v[14:17]
	v_mfma_f32_16x16x32_bf16 v[10:13], v[244:247], v[196:199], v[10:13]
	v_mfma_f32_16x16x32_bf16 v[6:9], v[236:239], v[222:225], v[6:9]
	v_mfma_f32_16x16x32_bf16 v[2:5], v[244:247], v[222:225], v[2:5]
	v_mfma_f32_16x16x32_bf16 v[30:33], v[240:243], v[184:187], v[30:33]
	v_mfma_f32_16x16x32_bf16 v[26:29], v[248:251], v[184:187], v[26:29]
	v_mfma_f32_16x16x32_bf16 v[22:25], v[240:243], v[192:195], v[22:25]
	v_mfma_f32_16x16x32_bf16 v[18:21], v[248:251], v[192:195], v[18:21]
	v_mfma_f32_16x16x32_bf16 v[14:17], v[240:243], v[200:203], v[14:17]
	v_mfma_f32_16x16x32_bf16 v[10:13], v[248:251], v[200:203], v[10:13]
	v_mfma_f32_16x16x32_bf16 v[6:9], v[240:243], v[232:235], v[6:9]
	v_mfma_f32_16x16x32_bf16 v[2:5], v[248:251], v[232:235], v[2:5]
	s_setprio 0
	s_add_i32 s0, s0, 2
	s_add_u32 s10, s10, 0x100
	s_addc_u32 s11, s11, 0
	s_cmpk_lt_u32 s0, 0x54
	s_barrier
	s_cbranch_scc1 .LBB0_761
	s_add_i32 s1, s1, 0x1e000
	s_add_u32 s0, s8, 0x162b80
	s_addc_u32 s1, s9, 0
	v_readfirstlane_b32 s8, v161
	v_lshl_add_u64 v[158:159], s[0:1], 0, v[0:1]
	s_mov_b32 m0, s8
	v_lshl_add_u64 v[130:131], s[0:1], 0, v[130:131]
	v_readfirstlane_b32 s0, v162
	ds_read_b128 v[132:135], v148
	ds_read_b128 v[136:139], v148 offset:1024
	ds_read_b128 v[150:153], v148 offset:2048
	ds_read_b128 v[154:157], v148 offset:3072
	ds_read_b128 v[164:167], v147
	ds_read_b128 v[168:171], v147 offset:1024
	ds_read_b128 v[172:175], v147 offset:2048
	ds_read_b128 v[176:179], v147 offset:3072
	ds_read_b128 v[180:183], v147 offset:4096
	ds_read_b128 v[184:187], v147 offset:5120
	ds_read_b128 v[188:191], v147 offset:6144
	ds_read_b128 v[192:195], v147 offset:7168
	global_load_lds_dwordx4 v[158:159], off
	s_mov_b32 m0, s0
	s_nop 0
	global_load_lds_dwordx4 v[130:131], off
	s_barrier
	s_waitcnt lgkmcnt(0)
	s_setprio 1
	s_waitcnt lgkmcnt(0)
	v_mfma_f32_16x16x32_bf16 v[122:125], v[150:153], v[164:167], v[122:125]
	v_mfma_f32_16x16x32_bf16 v[118:121], v[132:135], v[172:175], v[118:121]
	v_mfma_f32_16x16x32_bf16 v[114:117], v[150:153], v[172:175], v[114:117]
	v_mfma_f32_16x16x32_bf16 v[102:105], v[132:135], v[188:191], v[102:105]
	v_mfma_f32_16x16x32_bf16 v[98:101], v[150:153], v[188:191], v[98:101]
	v_mfma_f32_16x16x32_bf16 v[126:129], v[132:135], v[164:167], v[126:129]
	v_mfma_f32_16x16x32_bf16 v[122:125], v[154:157], v[168:171], v[122:125]
	v_mfma_f32_16x16x32_bf16 v[118:121], v[136:139], v[176:179], v[118:121]
	v_mfma_f32_16x16x32_bf16 v[114:117], v[154:157], v[176:179], v[114:117]
	v_mfma_f32_16x16x32_bf16 v[110:113], v[132:135], v[180:183], v[110:113]
	v_mfma_f32_16x16x32_bf16 v[106:109], v[150:153], v[180:183], v[106:109]
	v_mfma_f32_16x16x32_bf16 v[102:105], v[136:139], v[192:195], v[102:105]
	v_mfma_f32_16x16x32_bf16 v[98:101], v[154:157], v[192:195], v[98:101]
	v_mfma_f32_16x16x32_bf16 v[126:129], v[136:139], v[168:171], v[126:129]
	v_mfma_f32_16x16x32_bf16 v[158:161], v[136:139], v[184:187], v[110:113]
	v_mfma_f32_16x16x32_bf16 v[196:199], v[154:157], v[184:187], v[106:109]
	s_setprio 0
	s_barrier
	ds_read_b128 v[106:109], v148 offset:16384
	ds_read_b128 v[110:113], v148 offset:17408
	ds_read_b128 v[200:203], v148 offset:18432
	ds_read_b128 v[222:225], v148 offset:19456
	s_barrier
	s_waitcnt lgkmcnt(0)
	s_setprio 1
	s_waitcnt lgkmcnt(3)
	v_mfma_f32_16x16x32_bf16 v[86:89], v[106:109], v[172:175], v[86:89]
	s_waitcnt lgkmcnt(1)
	v_mfma_f32_16x16x32_bf16 v[82:85], v[200:203], v[172:175], v[82:85]
	v_mfma_f32_16x16x32_bf16 v[70:73], v[106:109], v[188:191], v[70:73]
	v_mfma_f32_16x16x32_bf16 v[66:69], v[200:203], v[188:191], v[66:69]
	v_mfma_f32_16x16x32_bf16 v[94:97], v[106:109], v[164:167], v[94:97]
	v_mfma_f32_16x16x32_bf16 v[90:93], v[200:203], v[164:167], v[90:93]
	v_mfma_f32_16x16x32_bf16 v[86:89], v[110:113], v[176:179], v[86:89]
	s_waitcnt lgkmcnt(0)
	v_mfma_f32_16x16x32_bf16 v[82:85], v[222:225], v[176:179], v[82:85]
	v_mfma_f32_16x16x32_bf16 v[78:81], v[106:109], v[180:183], v[78:81]
	v_mfma_f32_16x16x32_bf16 v[74:77], v[200:203], v[180:183], v[74:77]
	v_mfma_f32_16x16x32_bf16 v[70:73], v[110:113], v[192:195], v[70:73]
	v_mfma_f32_16x16x32_bf16 v[66:69], v[222:225], v[192:195], v[66:69]
	v_mfma_f32_16x16x32_bf16 v[232:235], v[110:113], v[168:171], v[94:97]
	v_mfma_f32_16x16x32_bf16 v[162:165], v[222:225], v[168:171], v[90:93]
	v_mfma_f32_16x16x32_bf16 v[166:169], v[110:113], v[184:187], v[78:81]
	v_mfma_f32_16x16x32_bf16 v[170:173], v[222:225], v[184:187], v[74:77]
	s_setprio 0
	s_barrier
	s_nop 0
	ds_read_b128 v[74:77], v147 offset:16384
	ds_read_b128 v[78:81], v147 offset:17408
	ds_read_b128 v[90:93], v147 offset:18432
	ds_read_b128 v[94:97], v147 offset:19456
	ds_read_b128 v[174:177], v147 offset:20480
	ds_read_b128 v[178:181], v147 offset:21504
	ds_read_b128 v[182:185], v147 offset:22528
	ds_read_b128 v[186:189], v147 offset:23552
	s_waitcnt vmcnt(4)
	s_barrier
	s_waitcnt lgkmcnt(0)
	s_setprio 1
	s_waitcnt lgkmcnt(7)
	v_mfma_f32_16x16x32_bf16 v[62:65], v[132:135], v[74:77], v[62:65]
	v_mfma_f32_16x16x32_bf16 v[58:61], v[150:153], v[74:77], v[58:61]
	s_waitcnt lgkmcnt(5)
	v_mfma_f32_16x16x32_bf16 v[54:57], v[132:135], v[90:93], v[54:57]
	v_mfma_f32_16x16x32_bf16 v[50:53], v[150:153], v[90:93], v[50:53]
	s_waitcnt lgkmcnt(1)
	v_mfma_f32_16x16x32_bf16 v[38:41], v[132:135], v[182:185], v[38:41]
	v_mfma_f32_16x16x32_bf16 v[34:37], v[150:153], v[182:185], v[34:37]
	v_mfma_f32_16x16x32_bf16 v[62:65], v[136:139], v[78:81], v[62:65]
	v_mfma_f32_16x16x32_bf16 v[58:61], v[154:157], v[78:81], v[58:61]
	v_mfma_f32_16x16x32_bf16 v[54:57], v[136:139], v[94:97], v[54:57]
	v_mfma_f32_16x16x32_bf16 v[50:53], v[154:157], v[94:97], v[50:53]
	v_mfma_f32_16x16x32_bf16 v[46:49], v[132:135], v[174:177], v[46:49]
	v_mfma_f32_16x16x32_bf16 v[42:45], v[150:153], v[174:177], v[42:45]
	s_waitcnt lgkmcnt(0)
	v_mfma_f32_16x16x32_bf16 v[38:41], v[136:139], v[186:189], v[38:41]
	v_mfma_f32_16x16x32_bf16 v[34:37], v[154:157], v[186:189], v[34:37]
	v_mfma_f32_16x16x32_bf16 v[190:193], v[136:139], v[178:181], v[46:49]
	v_mfma_f32_16x16x32_bf16 v[236:239], v[154:157], v[178:181], v[42:45]
	s_setprio 0
	s_setprio 1
	v_mfma_f32_16x16x32_bf16 v[22:25], v[106:109], v[90:93], v[22:25]
	v_mfma_f32_16x16x32_bf16 v[18:21], v[200:203], v[90:93], v[18:21]
	v_mfma_f32_16x16x32_bf16 v[6:9], v[106:109], v[182:185], v[6:9]
	v_mfma_f32_16x16x32_bf16 v[2:5], v[200:203], v[182:185], v[2:5]
	v_mfma_f32_16x16x32_bf16 v[30:33], v[106:109], v[74:77], v[30:33]
	v_mfma_f32_16x16x32_bf16 v[26:29], v[200:203], v[74:77], v[26:29]
	v_mfma_f32_16x16x32_bf16 v[22:25], v[110:113], v[94:97], v[22:25]
	v_mfma_f32_16x16x32_bf16 v[18:21], v[222:225], v[94:97], v[18:21]
	v_mfma_f32_16x16x32_bf16 v[14:17], v[106:109], v[174:177], v[14:17]
	v_mfma_f32_16x16x32_bf16 v[10:13], v[200:203], v[174:177], v[10:13]
	v_mfma_f32_16x16x32_bf16 v[6:9], v[110:113], v[186:189], v[6:9]
	v_mfma_f32_16x16x32_bf16 v[2:5], v[222:225], v[186:189], v[2:5]
	v_mfma_f32_16x16x32_bf16 v[134:137], v[110:113], v[78:81], v[30:33]
	v_mfma_f32_16x16x32_bf16 v[150:153], v[222:225], v[78:81], v[26:29]
	v_mfma_f32_16x16x32_bf16 v[154:157], v[110:113], v[178:181], v[14:17]
	v_mfma_f32_16x16x32_bf16 v[174:177], v[222:225], v[178:181], v[10:13]
	s_setprio 0
	s_barrier
	s_nop 0
	ds_read_b128 v[10:13], v148 offset:32768
	ds_read_b128 v[14:17], v148 offset:33792
	ds_read_b128 v[178:181], v148 offset:34816
	ds_read_b128 v[182:185], v148 offset:35840
	ds_read_b128 v[26:29], v147 offset:32768
	ds_read_b128 v[30:33], v147 offset:33792
	ds_read_b128 v[42:45], v147 offset:34816
	ds_read_b128 v[46:49], v147 offset:35840
	ds_read_b128 v[186:189], v147 offset:36864
	ds_read_b128 v[200:203], v147 offset:37888
	ds_read_b128 v[222:225], v147 offset:38912
	ds_read_b128 v[240:243], v147 offset:39936
	s_waitcnt vmcnt(2)
	s_barrier
	s_waitcnt lgkmcnt(0)
	s_setprio 1
	s_waitcnt lgkmcnt(7)
	v_mfma_f32_16x16x32_bf16 v[74:77], v[10:13], v[26:29], v[126:129]
	s_waitcnt lgkmcnt(6)
	v_mfma_f32_16x16x32_bf16 v[130:133], v[14:17], v[30:33], v[74:77]
	v_mfma_f32_16x16x32_bf16 v[74:77], v[178:181], v[26:29], v[122:125]
	v_mfma_f32_16x16x32_bf16 v[122:125], v[182:185], v[30:33], v[74:77]
	s_waitcnt lgkmcnt(5)
	v_mfma_f32_16x16x32_bf16 v[74:77], v[10:13], v[42:45], v[118:121]
	s_waitcnt lgkmcnt(4)
	v_mfma_f32_16x16x32_bf16 v[110:113], v[14:17], v[46:49], v[74:77]
	v_mfma_f32_16x16x32_bf16 v[74:77], v[178:181], v[42:45], v[114:117]
	v_mfma_f32_16x16x32_bf16 v[106:109], v[182:185], v[46:49], v[74:77]
	s_waitcnt lgkmcnt(3)
	v_mfma_f32_16x16x32_bf16 v[74:77], v[10:13], v[186:189], v[158:161]
	s_waitcnt lgkmcnt(2)
	v_mfma_f32_16x16x32_bf16 v[94:97], v[14:17], v[200:203], v[74:77]
	v_mfma_f32_16x16x32_bf16 v[74:77], v[178:181], v[186:189], v[196:199]
	v_mfma_f32_16x16x32_bf16 v[90:93], v[182:185], v[200:203], v[74:77]
	s_waitcnt lgkmcnt(1)
	v_mfma_f32_16x16x32_bf16 v[74:77], v[10:13], v[222:225], v[102:105]
	s_waitcnt lgkmcnt(0)
	v_mfma_f32_16x16x32_bf16 v[78:81], v[14:17], v[240:243], v[74:77]
	v_mfma_f32_16x16x32_bf16 v[74:77], v[178:181], v[222:225], v[98:101]
	v_mfma_f32_16x16x32_bf16 v[74:77], v[182:185], v[240:243], v[74:77]
	s_setprio 0
	s_barrier
	ds_read_b128 v[126:129], v148 offset:49152
	ds_read_b128 v[158:161], v148 offset:50176
	ds_read_b128 v[194:197], v148 offset:51200
	ds_read_b128 v[244:247], v148 offset:52224
	s_waitcnt vmcnt(0)
	s_barrier
	s_waitcnt lgkmcnt(0)
	s_setprio 1
	s_waitcnt lgkmcnt(3)
	v_mfma_f32_16x16x32_bf16 v[98:101], v[126:129], v[26:29], v[232:235]
	s_waitcnt lgkmcnt(1)
	v_mfma_f32_16x16x32_bf16 v[26:29], v[194:197], v[26:29], v[162:165]
	s_waitcnt lgkmcnt(0)
	v_mfma_f32_16x16x32_bf16 v[114:117], v[244:247], v[30:33], v[26:29]
	v_mfma_f32_16x16x32_bf16 v[26:29], v[126:129], v[42:45], v[86:89]
	v_mfma_f32_16x16x32_bf16 v[102:105], v[158:161], v[46:49], v[26:29]
	v_mfma_f32_16x16x32_bf16 v[26:29], v[194:197], v[42:45], v[82:85]
	v_mfma_f32_16x16x32_bf16 v[118:121], v[158:161], v[30:33], v[98:101]
	v_mfma_f32_16x16x32_bf16 v[98:101], v[244:247], v[46:49], v[26:29]
	v_mfma_f32_16x16x32_bf16 v[26:29], v[126:129], v[186:189], v[166:169]
	v_mfma_f32_16x16x32_bf16 v[86:89], v[158:161], v[200:203], v[26:29]
	v_mfma_f32_16x16x32_bf16 v[26:29], v[194:197], v[186:189], v[170:173]
	v_mfma_f32_16x16x32_bf16 v[82:85], v[244:247], v[200:203], v[26:29]
	v_mfma_f32_16x16x32_bf16 v[26:29], v[126:129], v[222:225], v[70:73]
	v_mfma_f32_16x16x32_bf16 v[70:73], v[158:161], v[240:243], v[26:29]
	v_mfma_f32_16x16x32_bf16 v[26:29], v[194:197], v[222:225], v[66:69]
	v_mfma_f32_16x16x32_bf16 v[66:69], v[244:247], v[240:243], v[26:29]
	s_setprio 0
	s_barrier
	ds_read_b128 v[162:165], v147 offset:49152
	ds_read_b128 v[166:169], v147 offset:50176
	ds_read_b128 v[170:173], v147 offset:51200
	ds_read_b128 v[186:189], v147 offset:52224
	ds_read_b128 v[198:201], v147 offset:53248
	ds_read_b128 v[202:205], v147 offset:54272
	ds_read_b128 v[222:225], v147 offset:55296
	ds_read_b128 v[146:149], v147 offset:56320
	s_barrier
	s_waitcnt lgkmcnt(0)
	s_setprio 1
	s_waitcnt lgkmcnt(7)
	v_mfma_f32_16x16x32_bf16 v[26:29], v[10:13], v[162:165], v[62:65]
	s_waitcnt lgkmcnt(6)
	v_mfma_f32_16x16x32_bf16 v[62:65], v[14:17], v[166:169], v[26:29]
	v_mfma_f32_16x16x32_bf16 v[26:29], v[178:181], v[162:165], v[58:61]
	v_mfma_f32_16x16x32_bf16 v[58:61], v[182:185], v[166:169], v[26:29]
	s_waitcnt lgkmcnt(5)
	v_mfma_f32_16x16x32_bf16 v[26:29], v[10:13], v[170:173], v[54:57]
	s_waitcnt lgkmcnt(4)
	v_mfma_f32_16x16x32_bf16 v[46:49], v[14:17], v[186:189], v[26:29]
	v_mfma_f32_16x16x32_bf16 v[26:29], v[178:181], v[170:173], v[50:53]
	v_mfma_f32_16x16x32_bf16 v[42:45], v[182:185], v[186:189], v[26:29]
	s_waitcnt lgkmcnt(3)
	v_mfma_f32_16x16x32_bf16 v[26:29], v[10:13], v[198:201], v[190:193]
	s_waitcnt lgkmcnt(1)
	v_mfma_f32_16x16x32_bf16 v[10:13], v[10:13], v[222:225], v[38:41]
	v_mfma_f32_16x16x32_bf16 v[30:33], v[14:17], v[202:205], v[26:29]
	v_mfma_f32_16x16x32_bf16 v[26:29], v[178:181], v[198:201], v[236:239]
	s_waitcnt lgkmcnt(0)
	v_mfma_f32_16x16x32_bf16 v[14:17], v[14:17], v[146:149], v[10:13]
	v_mfma_f32_16x16x32_bf16 v[10:13], v[178:181], v[222:225], v[34:37]
	v_mfma_f32_16x16x32_bf16 v[26:29], v[182:185], v[202:205], v[26:29]
	v_mfma_f32_16x16x32_bf16 v[10:13], v[182:185], v[146:149], v[10:13]
	s_setprio 0
	s_setprio 1
	v_mfma_f32_16x16x32_bf16 v[34:37], v[126:129], v[162:165], v[134:137]
	v_mfma_f32_16x16x32_bf16 v[54:57], v[158:161], v[166:169], v[34:37]
	v_mfma_f32_16x16x32_bf16 v[34:37], v[194:197], v[162:165], v[150:153]
	v_mfma_f32_16x16x32_bf16 v[18:21], v[194:197], v[170:173], v[18:21]
	v_mfma_f32_16x16x32_bf16 v[50:53], v[244:247], v[166:169], v[34:37]
	v_mfma_f32_16x16x32_bf16 v[22:25], v[126:129], v[170:173], v[22:25]
	v_mfma_f32_16x16x32_bf16 v[34:37], v[244:247], v[186:189], v[18:21]
	v_mfma_f32_16x16x32_bf16 v[18:21], v[126:129], v[198:201], v[154:157]
	v_mfma_f32_16x16x32_bf16 v[38:41], v[158:161], v[186:189], v[22:25]
	v_mfma_f32_16x16x32_bf16 v[22:25], v[158:161], v[202:205], v[18:21]
	v_mfma_f32_16x16x32_bf16 v[18:21], v[194:197], v[198:201], v[174:177]
	v_mfma_f32_16x16x32_bf16 v[6:9], v[126:129], v[222:225], v[6:9]
	v_mfma_f32_16x16x32_bf16 v[2:5], v[194:197], v[222:225], v[2:5]
	v_mfma_f32_16x16x32_bf16 v[18:21], v[244:247], v[202:205], v[18:21]
	v_mfma_f32_16x16x32_bf16 v[6:9], v[158:161], v[146:149], v[6:9]
	v_mfma_f32_16x16x32_bf16 v[2:5], v[244:247], v[146:149], v[2:5]
	s_setprio 0
	s_movk_i32 s0, 0x100
	v_cmp_gt_u32_e32 vcc, s0, v140
	s_barrier
	s_and_saveexec_b64 s[0:1], vcc
	s_cbranch_execz .LBB0_764
	s_barrier
